# gl1 front end: 192 fewer VALU per item (max(-z,0) in one op, decay chain as v_fma, exp2(+x) taken as exp2 of the negated -x) on top of the DPP broadcast projection
# speedup vs baseline: 1.0083x; 1.0010x over previous
; __device__ __forceinline__ void gl1_item(PREF p, int l, int item, bool valid, LAS unsigned char* pl, int sw, int lane) {
;     ...
;         for (int ss = 0; ss < 16; ++ss) { const int i = d ? 63 - ss : ss; const bf16_t* pr = P + (size_t)(row0 + i * rstride) * PW + h * 64 + lane;
;             qc[ss] = __builtin_bit_cast(float, (unsigned)pr[1024]); kc[ss] = __builtin_bit_cast(float, (unsigned)pr[1280]); }
;         __builtin_amdgcn_sched_barrier(0);
; #pragma unroll
;         for (int ss = 0; ss < 16; ++ss) { qc[ss] = bf2f(__builtin_bit_cast(unsigned, qc[ss])); kc[ss] = bf2f(__builtin_bit_cast(unsigned, kc[ss])); }
;         unsigned wupp[8];
; #pragma unroll
;         for (int r2 = 0; r2 < 8; ++r2) wupp[r2] = pk2(p.gla_wup[(size_t)((l * 2 + d) * 16 + 2 * r2) * 256 + h * 64 + lane], p.gla_wup[(size_t)((l * 2 + d) * 16 + 2 * r2 + 1) * 256 + h * 64 + lane]);
;         const float bup = p.gla_bup[(l * 2 + d) * 256 + h * 64 + lane];
; #pragma unroll 1
;         for (int g2 = 0; g2 < 2; ++g2) {
;             unsigned vr[16];
; #pragma unroll
;             for (int ii = 0; ii < 16; ++ii) { const int i = 32 * sw + g2 * 16 + ii; vr[ii] = *(const unsigned*)(P + (size_t)(row0 + i * rstride) * PW + 1536 + h * 128 + 2 * lane); }
; #pragma unroll
;             for (int ii = 0; ii < 16; ++ii) { const int i = 32 * sw + g2 * 16 + ii; sVt[(2 * lane) * 72 + i] = (bf16_t)(vr[ii] & 0xffffu); sVt[(2 * lane + 1) * 72 + i] = (bf16_t)(vr[ii] >> 16); }
;         }
;         float bc = 0.f;
; #pragma unroll 1
;         for (int g4 = 0; g4 < 4; ++g4) {
;             float qn[16], kn[16];
;             if (g4 < 3) {
; #pragma unroll
;                 for (int ss = 0; ss < 16; ++ss) { const int s = (g4 + 1) * 16 + ss; const int i = d ? 63 - s : s; const bf16_t* pr = P + (size_t)(row0 + i * rstride) * PW + h * 64 + lane;
;                     qn[ss] = __builtin_bit_cast(float, (unsigned)pr[1024]); kn[ss] = __builtin_bit_cast(float, (unsigned)pr[1280]); }
;                 __builtin_amdgcn_sched_barrier(0);
;             }
;             float gv[16];
; #pragma unroll
;             for (int ss = 0; ss < 16; ++ss) { const int s = g4 * 16 + ss; const int i = d ? 63 - s : s;
;                 float z = bup;
; #pragma unroll
;                 for (int r2 = 0; r2 < 8; ++r2) { const unsigned w = (unsigned)__builtin_amdgcn_readlane((int)lrp[r2], i);
.Lgl1v_fwd:
	s_mul_i32 s45, s46, 0x2400
	s_add_i32 s45, s45, s47
	s_add_i32 s45, s45, 0x4800
	s_lshl_b32 s50, s30, 1
	s_add_i32 s45, s45, s50
	s_movk_i32 s50, 0x90
	v_mul_u32_u24_e32 v60, 0x90, v64
	v_add_u32_e32 v60, s45, v60
	s_lshl_b32 s50, s2, 1
	v_mov_b32_e32 v61, s50
	s_waitcnt vmcnt(32)
	v_cvt_pk_bf16_f32 v8, v90, v91
	v_cvt_pk_bf16_f32 v9, v92, v93
	v_cvt_pk_bf16_f32 v10, v94, v95
	v_cvt_pk_bf16_f32 v11, v96, v97
	v_cvt_pk_bf16_f32 v12, v98, v99
	v_cvt_pk_bf16_f32 v13, v100, v101
	v_cvt_pk_bf16_f32 v14, v102, v103
	v_cvt_pk_bf16_f32 v15, v104, v105
	s_waitcnt vmcnt(0)
	v_mul_u32_u24_e32 v86, 0x120, v64
	s_lshl_b32 s45, s46, 6
	s_add_i32 s45, s45, s47
	v_add_u32_e32 v86, s45, v86
	ds_write_b16 v86, v34 offset:0
	ds_write_b16_d16_hi v86, v34 offset:144
	ds_write_b16 v86, v35 offset:2
	ds_write_b16_d16_hi v86, v35 offset:146
	ds_write_b16 v86, v36 offset:4
	ds_write_b16_d16_hi v86, v36 offset:148
	ds_write_b16 v86, v37 offset:6
	ds_write_b16_d16_hi v86, v37 offset:150
	ds_write_b16 v86, v38 offset:8
	ds_write_b16_d16_hi v86, v38 offset:152
	ds_write_b16 v86, v39 offset:10
	ds_write_b16_d16_hi v86, v39 offset:154
	ds_write_b16 v86, v40 offset:12
	ds_write_b16_d16_hi v86, v40 offset:156
	ds_write_b16 v86, v41 offset:14
	ds_write_b16_d16_hi v86, v41 offset:158
	ds_write_b16 v86, v42 offset:16
	ds_write_b16_d16_hi v86, v42 offset:160
	ds_write_b16 v86, v43 offset:18
	ds_write_b16_d16_hi v86, v43 offset:162
	ds_write_b16 v86, v44 offset:20
	ds_write_b16_d16_hi v86, v44 offset:164
	ds_write_b16 v86, v45 offset:22
	ds_write_b16_d16_hi v86, v45 offset:166
	ds_write_b16 v86, v46 offset:24
	ds_write_b16_d16_hi v86, v46 offset:168
	ds_write_b16 v86, v47 offset:26
	ds_write_b16_d16_hi v86, v47 offset:170
	ds_write_b16 v86, v212 offset:28
	ds_write_b16_d16_hi v86, v212 offset:172
	ds_write_b16 v86, v213 offset:30
	ds_write_b16_d16_hi v86, v213 offset:174
	ds_write_b16 v86, v214 offset:32
	ds_write_b16_d16_hi v86, v214 offset:176
	ds_write_b16 v86, v215 offset:34
	ds_write_b16_d16_hi v86, v215 offset:178
	ds_write_b16 v86, v216 offset:36
	ds_write_b16_d16_hi v86, v216 offset:180
	ds_write_b16 v86, v217 offset:38
	ds_write_b16_d16_hi v86, v217 offset:182
	ds_write_b16 v86, v218 offset:40
	ds_write_b16_d16_hi v86, v218 offset:184
	ds_write_b16 v86, v219 offset:42
	ds_write_b16_d16_hi v86, v219 offset:186
	ds_write_b16 v86, v222 offset:44
	ds_write_b16_d16_hi v86, v222 offset:188
	ds_write_b16 v86, v223 offset:46
	ds_write_b16_d16_hi v86, v223 offset:190
	ds_write_b16 v86, v228 offset:48
	ds_write_b16_d16_hi v86, v228 offset:192
	ds_write_b16 v86, v229 offset:50
	ds_write_b16_d16_hi v86, v229 offset:194
	ds_write_b16 v86, v230 offset:52
	ds_write_b16_d16_hi v86, v230 offset:196
	ds_write_b16 v86, v231 offset:54
	ds_write_b16_d16_hi v86, v231 offset:198
	ds_write_b16 v86, v232 offset:56
	ds_write_b16_d16_hi v86, v232 offset:200
	ds_write_b16 v86, v233 offset:58
	ds_write_b16_d16_hi v86, v233 offset:202
	ds_write_b16 v86, v234 offset:60
	ds_write_b16_d16_hi v86, v234 offset:204
	ds_write_b16 v86, v235 offset:62
	ds_write_b16_d16_hi v86, v235 offset:206
	global_load_ushort v148, v134, s[6:7]
	global_load_ushort v164, v134, s[6:7] offset:512
	s_add_u32 s6, s6, s54
	s_addc_u32 s7, s7, s55
	global_load_ushort v149, v134, s[6:7]
	global_load_ushort v165, v134, s[6:7] offset:512
	s_add_u32 s6, s6, s54
	s_addc_u32 s7, s7, s55
	global_load_ushort v150, v134, s[6:7]
	global_load_ushort v166, v134, s[6:7] offset:512
	s_add_u32 s6, s6, s54
	s_addc_u32 s7, s7, s55
	global_load_ushort v151, v134, s[6:7]
	global_load_ushort v167, v134, s[6:7] offset:512
	s_add_u32 s6, s6, s54
	s_addc_u32 s7, s7, s55
	global_load_ushort v152, v134, s[6:7]
	global_load_ushort v168, v134, s[6:7] offset:512
	s_add_u32 s6, s6, s54
	s_addc_u32 s7, s7, s55
	global_load_ushort v153, v134, s[6:7]
	global_load_ushort v169, v134, s[6:7] offset:512
	s_add_u32 s6, s6, s54
	s_addc_u32 s7, s7, s55
	global_load_ushort v154, v134, s[6:7]
	global_load_ushort v170, v134, s[6:7] offset:512
	s_add_u32 s6, s6, s54
	s_addc_u32 s7, s7, s55
	global_load_ushort v155, v134, s[6:7]
	global_load_ushort v171, v134, s[6:7] offset:512
	s_add_u32 s6, s6, s54
	s_addc_u32 s7, s7, s55
	global_load_ushort v156, v134, s[6:7]
	global_load_ushort v172, v134, s[6:7] offset:512
	s_add_u32 s6, s6, s54
	s_addc_u32 s7, s7, s55
	global_load_ushort v157, v134, s[6:7]
	global_load_ushort v173, v134, s[6:7] offset:512
	s_add_u32 s6, s6, s54
	s_addc_u32 s7, s7, s55
	global_load_ushort v158, v134, s[6:7]
	global_load_ushort v174, v134, s[6:7] offset:512
	s_add_u32 s6, s6, s54
	s_addc_u32 s7, s7, s55
	global_load_ushort v159, v134, s[6:7]
	global_load_ushort v175, v134, s[6:7] offset:512
	s_add_u32 s6, s6, s54
	s_addc_u32 s7, s7, s55
	global_load_ushort v160, v134, s[6:7]
	global_load_ushort v176, v134, s[6:7] offset:512
	s_add_u32 s6, s6, s54
	s_addc_u32 s7, s7, s55
	global_load_ushort v161, v134, s[6:7]
	global_load_ushort v177, v134, s[6:7] offset:512
	s_add_u32 s6, s6, s54
	s_addc_u32 s7, s7, s55
	global_load_ushort v162, v134, s[6:7]
	global_load_ushort v178, v134, s[6:7] offset:512
	s_add_u32 s6, s6, s54
	s_addc_u32 s7, s7, s55
	global_load_ushort v163, v134, s[6:7]
	global_load_ushort v179, v134, s[6:7] offset:512
	s_add_u32 s6, s6, s54
	s_addc_u32 s7, s7, s55
	v_mov_b32_e32 v17, 0
	s_mov_b32 s1, 0xbfb8aa3b
	s_mov_b32 s49, 0xbd800000
	v_mov_b32_e32 v236, v16
	v_dot2c_f32_bf16_dpp v236, v0, v8 row_newbcast:0 row_mask:0xf bank_mask:0xf
	v_dot2c_f32_bf16_dpp v236, v1, v9 row_newbcast:0 row_mask:0xf bank_mask:0xf
	v_dot2c_f32_bf16_dpp v236, v2, v10 row_newbcast:0 row_mask:0xf bank_mask:0xf
; __device__ __forceinline__ void gl1_item(PREF p, int l, int item, bool valid, LAS unsigned char* pl, int sw, int lane) {
;     ...
;             for (int ss = 0; ss < 16; ++ss) { const int s = g4 * 16 + ss; const int i = d ? 63 - s : s;
;                 float z = bup;
; #pragma unroll
;                 for (int r2 = 0; r2 < 8; ++r2) { const unsigned w = (unsigned)__builtin_amdgcn_readlane((int)lrp[r2], i);
;                     z = __builtin_amdgcn_fdot2_f32_bf16(__builtin_bit_cast(bf16x2_t, w), __builtin_bit_cast(bf16x2_t, wupp[r2]), z, false); }
	v_dot2c_f32_bf16_dpp v236, v3, v11 row_newbcast:0 row_mask:0xf bank_mask:0xf
	v_dot2c_f32_bf16_dpp v236, v4, v12 row_newbcast:0 row_mask:0xf bank_mask:0xf
	v_dot2c_f32_bf16_dpp v236, v5, v13 row_newbcast:0 row_mask:0xf bank_mask:0xf
	v_dot2c_f32_bf16_dpp v236, v6, v14 row_newbcast:0 row_mask:0xf bank_mask:0xf
	v_dot2c_f32_bf16_dpp v236, v7, v15 row_newbcast:0 row_mask:0xf bank_mask:0xf
	v_mov_b32_e32 v237, v16
	v_dot2c_f32_bf16_dpp v237, v0, v8 row_newbcast:1 row_mask:0xf bank_mask:0xf
	v_dot2c_f32_bf16_dpp v237, v1, v9 row_newbcast:1 row_mask:0xf bank_mask:0xf
	v_dot2c_f32_bf16_dpp v237, v2, v10 row_newbcast:1 row_mask:0xf bank_mask:0xf
	v_dot2c_f32_bf16_dpp v237, v3, v11 row_newbcast:1 row_mask:0xf bank_mask:0xf
	v_dot2c_f32_bf16_dpp v237, v4, v12 row_newbcast:1 row_mask:0xf bank_mask:0xf
	v_dot2c_f32_bf16_dpp v237, v5, v13 row_newbcast:1 row_mask:0xf bank_mask:0xf
	v_dot2c_f32_bf16_dpp v237, v6, v14 row_newbcast:1 row_mask:0xf bank_mask:0xf
	v_dot2c_f32_bf16_dpp v237, v7, v15 row_newbcast:1 row_mask:0xf bank_mask:0xf
	v_mov_b32_e32 v238, v16
	v_dot2c_f32_bf16_dpp v238, v0, v8 row_newbcast:2 row_mask:0xf bank_mask:0xf
	v_dot2c_f32_bf16_dpp v238, v1, v9 row_newbcast:2 row_mask:0xf bank_mask:0xf
	v_dot2c_f32_bf16_dpp v238, v2, v10 row_newbcast:2 row_mask:0xf bank_mask:0xf
	v_dot2c_f32_bf16_dpp v238, v3, v11 row_newbcast:2 row_mask:0xf bank_mask:0xf
	v_dot2c_f32_bf16_dpp v238, v4, v12 row_newbcast:2 row_mask:0xf bank_mask:0xf
	v_dot2c_f32_bf16_dpp v238, v5, v13 row_newbcast:2 row_mask:0xf bank_mask:0xf
	v_dot2c_f32_bf16_dpp v238, v6, v14 row_newbcast:2 row_mask:0xf bank_mask:0xf
	v_dot2c_f32_bf16_dpp v238, v7, v15 row_newbcast:2 row_mask:0xf bank_mask:0xf
	v_mov_b32_e32 v239, v16
	v_dot2c_f32_bf16_dpp v239, v0, v8 row_newbcast:3 row_mask:0xf bank_mask:0xf
	v_dot2c_f32_bf16_dpp v239, v1, v9 row_newbcast:3 row_mask:0xf bank_mask:0xf
	v_dot2c_f32_bf16_dpp v239, v2, v10 row_newbcast:3 row_mask:0xf bank_mask:0xf
	v_dot2c_f32_bf16_dpp v239, v3, v11 row_newbcast:3 row_mask:0xf bank_mask:0xf
	v_dot2c_f32_bf16_dpp v239, v4, v12 row_newbcast:3 row_mask:0xf bank_mask:0xf
	v_dot2c_f32_bf16_dpp v239, v5, v13 row_newbcast:3 row_mask:0xf bank_mask:0xf
	v_dot2c_f32_bf16_dpp v239, v6, v14 row_newbcast:3 row_mask:0xf bank_mask:0xf
	v_dot2c_f32_bf16_dpp v239, v7, v15 row_newbcast:3 row_mask:0xf bank_mask:0xf
	v_mov_b32_e32 v240, v16
	v_dot2c_f32_bf16_dpp v240, v0, v8 row_newbcast:4 row_mask:0xf bank_mask:0xf
	v_dot2c_f32_bf16_dpp v240, v1, v9 row_newbcast:4 row_mask:0xf bank_mask:0xf
	v_dot2c_f32_bf16_dpp v240, v2, v10 row_newbcast:4 row_mask:0xf bank_mask:0xf
	v_dot2c_f32_bf16_dpp v240, v3, v11 row_newbcast:4 row_mask:0xf bank_mask:0xf
	v_dot2c_f32_bf16_dpp v240, v4, v12 row_newbcast:4 row_mask:0xf bank_mask:0xf
	v_dot2c_f32_bf16_dpp v240, v5, v13 row_newbcast:4 row_mask:0xf bank_mask:0xf
	v_dot2c_f32_bf16_dpp v240, v6, v14 row_newbcast:4 row_mask:0xf bank_mask:0xf
	v_dot2c_f32_bf16_dpp v240, v7, v15 row_newbcast:4 row_mask:0xf bank_mask:0xf
	v_mov_b32_e32 v241, v16
	v_dot2c_f32_bf16_dpp v241, v0, v8 row_newbcast:5 row_mask:0xf bank_mask:0xf
	v_dot2c_f32_bf16_dpp v241, v1, v9 row_newbcast:5 row_mask:0xf bank_mask:0xf
	v_dot2c_f32_bf16_dpp v241, v2, v10 row_newbcast:5 row_mask:0xf bank_mask:0xf
	v_dot2c_f32_bf16_dpp v241, v3, v11 row_newbcast:5 row_mask:0xf bank_mask:0xf
	v_dot2c_f32_bf16_dpp v241, v4, v12 row_newbcast:5 row_mask:0xf bank_mask:0xf
	v_dot2c_f32_bf16_dpp v241, v5, v13 row_newbcast:5 row_mask:0xf bank_mask:0xf
	v_dot2c_f32_bf16_dpp v241, v6, v14 row_newbcast:5 row_mask:0xf bank_mask:0xf
	v_dot2c_f32_bf16_dpp v241, v7, v15 row_newbcast:5 row_mask:0xf bank_mask:0xf
	v_mov_b32_e32 v242, v16
	v_dot2c_f32_bf16_dpp v242, v0, v8 row_newbcast:6 row_mask:0xf bank_mask:0xf
	v_dot2c_f32_bf16_dpp v242, v1, v9 row_newbcast:6 row_mask:0xf bank_mask:0xf
	v_dot2c_f32_bf16_dpp v242, v2, v10 row_newbcast:6 row_mask:0xf bank_mask:0xf
	v_dot2c_f32_bf16_dpp v242, v3, v11 row_newbcast:6 row_mask:0xf bank_mask:0xf
	v_dot2c_f32_bf16_dpp v242, v4, v12 row_newbcast:6 row_mask:0xf bank_mask:0xf
	v_dot2c_f32_bf16_dpp v242, v5, v13 row_newbcast:6 row_mask:0xf bank_mask:0xf
	v_dot2c_f32_bf16_dpp v242, v6, v14 row_newbcast:6 row_mask:0xf bank_mask:0xf
	v_dot2c_f32_bf16_dpp v242, v7, v15 row_newbcast:6 row_mask:0xf bank_mask:0xf
	v_mov_b32_e32 v243, v16
	v_dot2c_f32_bf16_dpp v243, v0, v8 row_newbcast:7 row_mask:0xf bank_mask:0xf
	v_dot2c_f32_bf16_dpp v243, v1, v9 row_newbcast:7 row_mask:0xf bank_mask:0xf
	v_dot2c_f32_bf16_dpp v243, v2, v10 row_newbcast:7 row_mask:0xf bank_mask:0xf
	v_dot2c_f32_bf16_dpp v243, v3, v11 row_newbcast:7 row_mask:0xf bank_mask:0xf
	v_dot2c_f32_bf16_dpp v243, v4, v12 row_newbcast:7 row_mask:0xf bank_mask:0xf
	v_dot2c_f32_bf16_dpp v243, v5, v13 row_newbcast:7 row_mask:0xf bank_mask:0xf
	v_dot2c_f32_bf16_dpp v243, v6, v14 row_newbcast:7 row_mask:0xf bank_mask:0xf
	v_dot2c_f32_bf16_dpp v243, v7, v15 row_newbcast:7 row_mask:0xf bank_mask:0xf
	v_mov_b32_e32 v244, v16
	v_dot2c_f32_bf16_dpp v244, v0, v8 row_newbcast:8 row_mask:0xf bank_mask:0xf
	v_dot2c_f32_bf16_dpp v244, v1, v9 row_newbcast:8 row_mask:0xf bank_mask:0xf
	v_dot2c_f32_bf16_dpp v244, v2, v10 row_newbcast:8 row_mask:0xf bank_mask:0xf
	v_dot2c_f32_bf16_dpp v244, v3, v11 row_newbcast:8 row_mask:0xf bank_mask:0xf
	v_dot2c_f32_bf16_dpp v244, v4, v12 row_newbcast:8 row_mask:0xf bank_mask:0xf
	v_dot2c_f32_bf16_dpp v244, v5, v13 row_newbcast:8 row_mask:0xf bank_mask:0xf
	v_dot2c_f32_bf16_dpp v244, v6, v14 row_newbcast:8 row_mask:0xf bank_mask:0xf
	v_dot2c_f32_bf16_dpp v244, v7, v15 row_newbcast:8 row_mask:0xf bank_mask:0xf
	v_mov_b32_e32 v245, v16
	v_dot2c_f32_bf16_dpp v245, v0, v8 row_newbcast:9 row_mask:0xf bank_mask:0xf
; __device__ __forceinline__ void gl1_item(PREF p, int l, int item, bool valid, LAS unsigned char* pl, int sw, int lane) {
;     ...
;             for (int ss = 0; ss < 16; ++ss) { const int s = g4 * 16 + ss; const int i = d ? 63 - s : s;
;                 float z = bup;
; #pragma unroll
;                 for (int r2 = 0; r2 < 8; ++r2) { const unsigned w = (unsigned)__builtin_amdgcn_readlane((int)lrp[r2], i);
;                     z = __builtin_amdgcn_fdot2_f32_bf16(__builtin_bit_cast(bf16x2_t, w), __builtin_bit_cast(bf16x2_t, wupp[r2]), z, false); }
;                 gv[ss] = -(fmaxf(-z, 0.f) + __logf(1.f + __expf(-fabsf(z)))) * (1.f / 16.f);
	v_dot2c_f32_bf16_dpp v245, v1, v9 row_newbcast:9 row_mask:0xf bank_mask:0xf
	v_dot2c_f32_bf16_dpp v245, v2, v10 row_newbcast:9 row_mask:0xf bank_mask:0xf
	v_dot2c_f32_bf16_dpp v245, v3, v11 row_newbcast:9 row_mask:0xf bank_mask:0xf
	v_dot2c_f32_bf16_dpp v245, v4, v12 row_newbcast:9 row_mask:0xf bank_mask:0xf
	v_dot2c_f32_bf16_dpp v245, v5, v13 row_newbcast:9 row_mask:0xf bank_mask:0xf
	v_dot2c_f32_bf16_dpp v245, v6, v14 row_newbcast:9 row_mask:0xf bank_mask:0xf
	v_dot2c_f32_bf16_dpp v245, v7, v15 row_newbcast:9 row_mask:0xf bank_mask:0xf
	v_mov_b32_e32 v246, v16
	v_dot2c_f32_bf16_dpp v246, v0, v8 row_newbcast:10 row_mask:0xf bank_mask:0xf
	v_dot2c_f32_bf16_dpp v246, v1, v9 row_newbcast:10 row_mask:0xf bank_mask:0xf
	v_dot2c_f32_bf16_dpp v246, v2, v10 row_newbcast:10 row_mask:0xf bank_mask:0xf
	v_dot2c_f32_bf16_dpp v246, v3, v11 row_newbcast:10 row_mask:0xf bank_mask:0xf
	v_dot2c_f32_bf16_dpp v246, v4, v12 row_newbcast:10 row_mask:0xf bank_mask:0xf
	v_dot2c_f32_bf16_dpp v246, v5, v13 row_newbcast:10 row_mask:0xf bank_mask:0xf
	v_dot2c_f32_bf16_dpp v246, v6, v14 row_newbcast:10 row_mask:0xf bank_mask:0xf
	v_dot2c_f32_bf16_dpp v246, v7, v15 row_newbcast:10 row_mask:0xf bank_mask:0xf
	v_mov_b32_e32 v247, v16
	v_dot2c_f32_bf16_dpp v247, v0, v8 row_newbcast:11 row_mask:0xf bank_mask:0xf
	v_dot2c_f32_bf16_dpp v247, v1, v9 row_newbcast:11 row_mask:0xf bank_mask:0xf
	v_dot2c_f32_bf16_dpp v247, v2, v10 row_newbcast:11 row_mask:0xf bank_mask:0xf
	v_dot2c_f32_bf16_dpp v247, v3, v11 row_newbcast:11 row_mask:0xf bank_mask:0xf
	v_dot2c_f32_bf16_dpp v247, v4, v12 row_newbcast:11 row_mask:0xf bank_mask:0xf
	v_dot2c_f32_bf16_dpp v247, v5, v13 row_newbcast:11 row_mask:0xf bank_mask:0xf
	v_dot2c_f32_bf16_dpp v247, v6, v14 row_newbcast:11 row_mask:0xf bank_mask:0xf
	v_dot2c_f32_bf16_dpp v247, v7, v15 row_newbcast:11 row_mask:0xf bank_mask:0xf
	v_mov_b32_e32 v248, v16
	v_dot2c_f32_bf16_dpp v248, v0, v8 row_newbcast:12 row_mask:0xf bank_mask:0xf
	v_dot2c_f32_bf16_dpp v248, v1, v9 row_newbcast:12 row_mask:0xf bank_mask:0xf
	v_dot2c_f32_bf16_dpp v248, v2, v10 row_newbcast:12 row_mask:0xf bank_mask:0xf
	v_dot2c_f32_bf16_dpp v248, v3, v11 row_newbcast:12 row_mask:0xf bank_mask:0xf
	v_dot2c_f32_bf16_dpp v248, v4, v12 row_newbcast:12 row_mask:0xf bank_mask:0xf
	v_dot2c_f32_bf16_dpp v248, v5, v13 row_newbcast:12 row_mask:0xf bank_mask:0xf
	v_dot2c_f32_bf16_dpp v248, v6, v14 row_newbcast:12 row_mask:0xf bank_mask:0xf
	v_dot2c_f32_bf16_dpp v248, v7, v15 row_newbcast:12 row_mask:0xf bank_mask:0xf
	v_mov_b32_e32 v249, v16
	v_dot2c_f32_bf16_dpp v249, v0, v8 row_newbcast:13 row_mask:0xf bank_mask:0xf
	v_dot2c_f32_bf16_dpp v249, v1, v9 row_newbcast:13 row_mask:0xf bank_mask:0xf
	v_dot2c_f32_bf16_dpp v249, v2, v10 row_newbcast:13 row_mask:0xf bank_mask:0xf
	v_dot2c_f32_bf16_dpp v249, v3, v11 row_newbcast:13 row_mask:0xf bank_mask:0xf
	v_dot2c_f32_bf16_dpp v249, v4, v12 row_newbcast:13 row_mask:0xf bank_mask:0xf
	v_dot2c_f32_bf16_dpp v249, v5, v13 row_newbcast:13 row_mask:0xf bank_mask:0xf
	v_dot2c_f32_bf16_dpp v249, v6, v14 row_newbcast:13 row_mask:0xf bank_mask:0xf
	v_dot2c_f32_bf16_dpp v249, v7, v15 row_newbcast:13 row_mask:0xf bank_mask:0xf
	v_mov_b32_e32 v250, v16
	v_dot2c_f32_bf16_dpp v250, v0, v8 row_newbcast:14 row_mask:0xf bank_mask:0xf
	v_dot2c_f32_bf16_dpp v250, v1, v9 row_newbcast:14 row_mask:0xf bank_mask:0xf
	v_dot2c_f32_bf16_dpp v250, v2, v10 row_newbcast:14 row_mask:0xf bank_mask:0xf
	v_dot2c_f32_bf16_dpp v250, v3, v11 row_newbcast:14 row_mask:0xf bank_mask:0xf
	v_dot2c_f32_bf16_dpp v250, v4, v12 row_newbcast:14 row_mask:0xf bank_mask:0xf
	v_dot2c_f32_bf16_dpp v250, v5, v13 row_newbcast:14 row_mask:0xf bank_mask:0xf
	v_dot2c_f32_bf16_dpp v250, v6, v14 row_newbcast:14 row_mask:0xf bank_mask:0xf
	v_dot2c_f32_bf16_dpp v250, v7, v15 row_newbcast:14 row_mask:0xf bank_mask:0xf
	v_mov_b32_e32 v251, v16
	v_dot2c_f32_bf16_dpp v251, v0, v8 row_newbcast:15 row_mask:0xf bank_mask:0xf
	v_dot2c_f32_bf16_dpp v251, v1, v9 row_newbcast:15 row_mask:0xf bank_mask:0xf
	v_dot2c_f32_bf16_dpp v251, v2, v10 row_newbcast:15 row_mask:0xf bank_mask:0xf
	v_dot2c_f32_bf16_dpp v251, v3, v11 row_newbcast:15 row_mask:0xf bank_mask:0xf
	v_dot2c_f32_bf16_dpp v251, v4, v12 row_newbcast:15 row_mask:0xf bank_mask:0xf
	v_dot2c_f32_bf16_dpp v251, v5, v13 row_newbcast:15 row_mask:0xf bank_mask:0xf
	v_dot2c_f32_bf16_dpp v251, v6, v14 row_newbcast:15 row_mask:0xf bank_mask:0xf
	v_dot2c_f32_bf16_dpp v251, v7, v15 row_newbcast:15 row_mask:0xf bank_mask:0xf
	s_nop 2
	v_mul_f32_e64 v18, |v236|, s1
	v_mul_f32_e64 v19, |v237|, s1
	v_mul_f32_e64 v20, |v238|, s1
	v_mul_f32_e64 v21, |v239|, s1
	v_mul_f32_e64 v22, |v240|, s1
	v_mul_f32_e64 v23, |v241|, s1
	v_mul_f32_e64 v24, |v242|, s1
	v_mul_f32_e64 v25, |v243|, s1
	v_mul_f32_e64 v26, |v244|, s1
	v_mul_f32_e64 v27, |v245|, s1
	v_mul_f32_e64 v28, |v246|, s1
	v_mul_f32_e64 v29, |v247|, s1
	v_mul_f32_e64 v30, |v248|, s1
	v_mul_f32_e64 v31, |v249|, s1
	v_mul_f32_e64 v32, |v250|, s1
	v_mul_f32_e64 v33, |v251|, s1
	v_exp_f32_e32 v18, v18
	v_exp_f32_e32 v19, v19
	v_exp_f32_e32 v20, v20
	v_exp_f32_e32 v21, v21
	v_exp_f32_e32 v22, v22
	v_exp_f32_e32 v23, v23
	v_exp_f32_e32 v24, v24
	v_exp_f32_e32 v25, v25
	v_exp_f32_e32 v26, v26
	v_exp_f32_e32 v27, v27
	v_exp_f32_e32 v28, v28
	v_exp_f32_e32 v29, v29
	v_exp_f32_e32 v30, v30
	v_exp_f32_e32 v31, v31
	v_exp_f32_e32 v32, v32
	v_exp_f32_e32 v33, v33
	v_max_f32_e64 v236, -v236, 0
	v_max_f32_e64 v237, -v237, 0
	v_max_f32_e64 v238, -v238, 0
	v_max_f32_e64 v239, -v239, 0
	v_max_f32_e64 v240, -v240, 0
	v_max_f32_e64 v241, -v241, 0
	v_max_f32_e64 v242, -v242, 0
	v_max_f32_e64 v243, -v243, 0
	v_max_f32_e64 v244, -v244, 0
; __device__ __forceinline__ void gl1_item(PREF p, int l, int item, bool valid, LAS unsigned char* pl, int sw, int lane) {
;     ...
;                 gv[ss] = -(fmaxf(-z, 0.f) + __logf(1.f + __expf(-fabsf(z)))) * (1.f / 16.f);
;     ...
;                 bc += gv[ss];
	v_max_f32_e64 v245, -v245, 0
	v_max_f32_e64 v246, -v246, 0
	v_max_f32_e64 v247, -v247, 0
	v_max_f32_e64 v248, -v248, 0
	v_max_f32_e64 v249, -v249, 0
	v_max_f32_e64 v250, -v250, 0
	v_max_f32_e64 v251, -v251, 0
	v_add_f32_e32 v18, 1.0, v18
	v_add_f32_e32 v19, 1.0, v19
	v_add_f32_e32 v20, 1.0, v20
	v_add_f32_e32 v21, 1.0, v21
	v_add_f32_e32 v22, 1.0, v22
	v_add_f32_e32 v23, 1.0, v23
	v_add_f32_e32 v24, 1.0, v24
	v_add_f32_e32 v25, 1.0, v25
	v_add_f32_e32 v26, 1.0, v26
	v_add_f32_e32 v27, 1.0, v27
	v_add_f32_e32 v28, 1.0, v28
	v_add_f32_e32 v29, 1.0, v29
	v_add_f32_e32 v30, 1.0, v30
	v_add_f32_e32 v31, 1.0, v31
	v_add_f32_e32 v32, 1.0, v32
	v_add_f32_e32 v33, 1.0, v33
	v_log_f32_e32 v18, v18
	v_log_f32_e32 v19, v19
	v_log_f32_e32 v20, v20
	v_log_f32_e32 v21, v21
	v_log_f32_e32 v22, v22
	v_log_f32_e32 v23, v23
	v_log_f32_e32 v24, v24
	v_log_f32_e32 v25, v25
	v_log_f32_e32 v26, v26
	v_log_f32_e32 v27, v27
	v_log_f32_e32 v28, v28
	v_log_f32_e32 v29, v29
	v_log_f32_e32 v30, v30
	v_log_f32_e32 v31, v31
	v_log_f32_e32 v32, v32
	v_log_f32_e32 v33, v33
	s_mov_b32 s45, 0x3f317217
	v_mul_f32_e32 v70, 0x3f317217, v18
	v_mul_f32_e32 v71, 0x3f317217, v19
	v_mul_f32_e32 v72, 0x3f317217, v20
	v_mul_f32_e32 v73, 0x3f317217, v21
	v_mul_f32_e32 v74, 0x3f317217, v22
	v_mul_f32_e32 v75, 0x3f317217, v23
	v_mul_f32_e32 v76, 0x3f317217, v24
	v_mul_f32_e32 v77, 0x3f317217, v25
	v_mul_f32_e32 v78, 0x3f317217, v26
	v_mul_f32_e32 v79, 0x3f317217, v27
	v_mul_f32_e32 v80, 0x3f317217, v28
	v_mul_f32_e32 v81, 0x3f317217, v29
	v_mul_f32_e32 v82, 0x3f317217, v30
	v_mul_f32_e32 v83, 0x3f317217, v31
	v_mul_f32_e32 v84, 0x3f317217, v32
	v_mul_f32_e32 v85, 0x3f317217, v33
	v_fma_f32 v70, v18, s45, -v70
	v_fma_f32 v71, v19, s45, -v71
	v_fma_f32 v72, v20, s45, -v72
	v_fma_f32 v73, v21, s45, -v73
	v_fma_f32 v74, v22, s45, -v74
	v_fma_f32 v75, v23, s45, -v75
	v_fma_f32 v76, v24, s45, -v76
	v_fma_f32 v77, v25, s45, -v77
	v_fma_f32 v78, v26, s45, -v78
	v_fma_f32 v79, v27, s45, -v79
	v_fma_f32 v80, v28, s45, -v80
	v_fma_f32 v81, v29, s45, -v81
	v_fma_f32 v82, v30, s45, -v82
	v_fma_f32 v83, v31, s45, -v83
	v_fma_f32 v84, v32, s45, -v84
	v_fma_f32 v85, v33, s45, -v85
	v_fmac_f32_e32 v70, 0x3377d1cf, v18
	v_fmac_f32_e32 v71, 0x3377d1cf, v19
	v_fmac_f32_e32 v72, 0x3377d1cf, v20
	v_fmac_f32_e32 v73, 0x3377d1cf, v21
	v_fmac_f32_e32 v74, 0x3377d1cf, v22
	v_fmac_f32_e32 v75, 0x3377d1cf, v23
	v_fmac_f32_e32 v76, 0x3377d1cf, v24
	v_fmac_f32_e32 v77, 0x3377d1cf, v25
	v_fmac_f32_e32 v78, 0x3377d1cf, v26
	v_fmac_f32_e32 v79, 0x3377d1cf, v27
	v_fmac_f32_e32 v80, 0x3377d1cf, v28
	v_fmac_f32_e32 v81, 0x3377d1cf, v29
	v_fmac_f32_e32 v82, 0x3377d1cf, v30
	v_fmac_f32_e32 v83, 0x3377d1cf, v31
	v_fmac_f32_e32 v84, 0x3377d1cf, v32
	v_fmac_f32_e32 v85, 0x3377d1cf, v33
	v_fmac_f32_e32 v70, 0x3f317217, v18
	v_fmac_f32_e32 v71, 0x3f317217, v19
	v_fmac_f32_e32 v72, 0x3f317217, v20
	v_fmac_f32_e32 v73, 0x3f317217, v21
	v_fmac_f32_e32 v74, 0x3f317217, v22
	v_fmac_f32_e32 v75, 0x3f317217, v23
	v_fmac_f32_e32 v76, 0x3f317217, v24
	v_fmac_f32_e32 v77, 0x3f317217, v25
	v_fmac_f32_e32 v78, 0x3f317217, v26
	v_fmac_f32_e32 v79, 0x3f317217, v27
	v_fmac_f32_e32 v80, 0x3f317217, v28
	v_fmac_f32_e32 v81, 0x3f317217, v29
	v_fmac_f32_e32 v82, 0x3f317217, v30
	v_fmac_f32_e32 v83, 0x3f317217, v31
	v_fmac_f32_e32 v84, 0x3f317217, v32
	v_fmac_f32_e32 v85, 0x3f317217, v33
	v_add_f32_e32 v236, v236, v70
	v_add_f32_e32 v237, v237, v71
	v_add_f32_e32 v238, v238, v72
	v_add_f32_e32 v239, v239, v73
	v_add_f32_e32 v240, v240, v74
	v_add_f32_e32 v241, v241, v75
	v_add_f32_e32 v242, v242, v76
	v_add_f32_e32 v243, v243, v77
	v_add_f32_e32 v244, v244, v78
	v_add_f32_e32 v245, v245, v79
	v_add_f32_e32 v246, v246, v80
	v_add_f32_e32 v247, v247, v81
	v_add_f32_e32 v248, v248, v82
	v_add_f32_e32 v249, v249, v83
	v_add_f32_e32 v250, v250, v84
	v_add_f32_e32 v251, v251, v85
	v_fma_f32 v70, v236, s49, v17
	v_fma_f32 v71, v237, s49, v70
	v_fma_f32 v72, v238, s49, v71
	v_fma_f32 v73, v239, s49, v72
	v_fma_f32 v74, v240, s49, v73
	v_fma_f32 v75, v241, s49, v74
	v_fma_f32 v76, v242, s49, v75
	v_fma_f32 v77, v243, s49, v76
	v_fma_f32 v78, v244, s49, v77
	v_fma_f32 v79, v245, s49, v78
	v_fma_f32 v80, v246, s49, v79
	v_fma_f32 v81, v247, s49, v80
	v_fma_f32 v82, v248, s49, v81
	v_fma_f32 v83, v249, s49, v82
	v_fma_f32 v84, v250, s49, v83
	v_fma_f32 v85, v251, s49, v84
	v_mov_b32_e32 v17, v85
	s_waitcnt vmcnt(0)
; __device__ __forceinline__ void gl1_item(PREF p, int l, int item, bool valid, LAS unsigned char* pl, int sw, int lane) {
;     ...
;             if (g4 < 3) {
; #pragma unroll
;                 for (int ss = 0; ss < 16; ++ss) { const int s = (g4 + 1) * 16 + ss; const int i = d ? 63 - s : s; const bf16_t* pr = P + (size_t)(row0 + i * rstride) * PW + h * 64 + lane;
;                     qn[ss] = __builtin_bit_cast(float, (unsigned)pr[1024]); kn[ss] = __builtin_bit_cast(float, (unsigned)pr[1280]); }
;                 __builtin_amdgcn_sched_barrier(0);
;             }
;     ...
;                 const float en = __expf(-bc), ep = __expf(bc);
;                 const float kt = kc[ss] * en, qt = qc[ss] * 0.125f * ep;
	global_load_ushort v180, v134, s[6:7]
	global_load_ushort v196, v134, s[6:7] offset:512
	s_add_u32 s6, s6, s54
	s_addc_u32 s7, s7, s55
	global_load_ushort v181, v134, s[6:7]
	global_load_ushort v197, v134, s[6:7] offset:512
	s_add_u32 s6, s6, s54
	s_addc_u32 s7, s7, s55
	global_load_ushort v182, v134, s[6:7]
	global_load_ushort v198, v134, s[6:7] offset:512
	s_add_u32 s6, s6, s54
	s_addc_u32 s7, s7, s55
	global_load_ushort v183, v134, s[6:7]
	global_load_ushort v199, v134, s[6:7] offset:512
	s_add_u32 s6, s6, s54
	s_addc_u32 s7, s7, s55
	global_load_ushort v184, v134, s[6:7]
	global_load_ushort v200, v134, s[6:7] offset:512
	s_add_u32 s6, s6, s54
	s_addc_u32 s7, s7, s55
	global_load_ushort v185, v134, s[6:7]
	global_load_ushort v201, v134, s[6:7] offset:512
	s_add_u32 s6, s6, s54
	s_addc_u32 s7, s7, s55
	global_load_ushort v186, v134, s[6:7]
	global_load_ushort v202, v134, s[6:7] offset:512
	s_add_u32 s6, s6, s54
	s_addc_u32 s7, s7, s55
	global_load_ushort v187, v134, s[6:7]
	global_load_ushort v203, v134, s[6:7] offset:512
	s_add_u32 s6, s6, s54
	s_addc_u32 s7, s7, s55
	global_load_ushort v188, v134, s[6:7]
	global_load_ushort v204, v134, s[6:7] offset:512
	s_add_u32 s6, s6, s54
	s_addc_u32 s7, s7, s55
	global_load_ushort v189, v134, s[6:7]
	global_load_ushort v205, v134, s[6:7] offset:512
	s_add_u32 s6, s6, s54
	s_addc_u32 s7, s7, s55
	global_load_ushort v190, v134, s[6:7]
	global_load_ushort v206, v134, s[6:7] offset:512
	s_add_u32 s6, s6, s54
	s_addc_u32 s7, s7, s55
	global_load_ushort v191, v134, s[6:7]
	global_load_ushort v207, v134, s[6:7] offset:512
	s_add_u32 s6, s6, s54
	s_addc_u32 s7, s7, s55
	global_load_ushort v192, v134, s[6:7]
	global_load_ushort v208, v134, s[6:7] offset:512
	s_add_u32 s6, s6, s54
	s_addc_u32 s7, s7, s55
	global_load_ushort v193, v134, s[6:7]
	global_load_ushort v209, v134, s[6:7] offset:512
	s_add_u32 s6, s6, s54
	s_addc_u32 s7, s7, s55
	global_load_ushort v194, v134, s[6:7]
	global_load_ushort v210, v134, s[6:7] offset:512
	s_add_u32 s6, s6, s54
	s_addc_u32 s7, s7, s55
	global_load_ushort v195, v134, s[6:7]
	global_load_ushort v211, v134, s[6:7] offset:512
	s_add_u32 s6, s6, s54
	s_addc_u32 s7, s7, s55
	v_mul_f32_e32 v18, 0xbfb8aa3b, v70
	v_mul_f32_e32 v19, 0xbfb8aa3b, v71
	v_mul_f32_e32 v20, 0xbfb8aa3b, v72
	v_mul_f32_e32 v21, 0xbfb8aa3b, v73
	v_mul_f32_e32 v22, 0xbfb8aa3b, v74
	v_mul_f32_e32 v23, 0xbfb8aa3b, v75
	v_mul_f32_e32 v24, 0xbfb8aa3b, v76
	v_mul_f32_e32 v25, 0xbfb8aa3b, v77
	v_mul_f32_e32 v26, 0xbfb8aa3b, v78
	v_mul_f32_e32 v27, 0xbfb8aa3b, v79
	v_mul_f32_e32 v28, 0xbfb8aa3b, v80
	v_mul_f32_e32 v29, 0xbfb8aa3b, v81
	v_mul_f32_e32 v30, 0xbfb8aa3b, v82
	v_mul_f32_e32 v31, 0xbfb8aa3b, v83
	v_mul_f32_e32 v32, 0xbfb8aa3b, v84
	v_mul_f32_e32 v33, 0xbfb8aa3b, v85
	v_exp_f32_e64 v236, -v18
	v_exp_f32_e64 v237, -v19
	v_exp_f32_e64 v238, -v20
	v_exp_f32_e64 v239, -v21
	v_exp_f32_e64 v240, -v22
	v_exp_f32_e64 v241, -v23
	v_exp_f32_e64 v242, -v24
	v_exp_f32_e64 v243, -v25
	v_exp_f32_e64 v244, -v26
	v_exp_f32_e64 v245, -v27
	v_exp_f32_e64 v246, -v28
	v_exp_f32_e64 v247, -v29
	v_exp_f32_e64 v248, -v30
	v_exp_f32_e64 v249, -v31
	v_exp_f32_e64 v250, -v32
	v_exp_f32_e64 v251, -v33
	v_exp_f32_e32 v18, v18
	v_exp_f32_e32 v19, v19
	v_exp_f32_e32 v20, v20
	v_exp_f32_e32 v21, v21
	v_exp_f32_e32 v22, v22
	v_exp_f32_e32 v23, v23
	v_exp_f32_e32 v24, v24
	v_exp_f32_e32 v25, v25
	v_exp_f32_e32 v26, v26
	v_exp_f32_e32 v27, v27
	v_exp_f32_e32 v28, v28
	v_exp_f32_e32 v29, v29
	v_exp_f32_e32 v30, v30
	v_exp_f32_e32 v31, v31
	v_exp_f32_e32 v32, v32
	v_exp_f32_e32 v33, v33
	v_lshlrev_b32_e32 v164, 16, v164
	v_lshlrev_b32_e32 v165, 16, v165
	v_lshlrev_b32_e32 v166, 16, v166
	v_lshlrev_b32_e32 v167, 16, v167
	v_lshlrev_b32_e32 v168, 16, v168
	v_lshlrev_b32_e32 v169, 16, v169
	v_lshlrev_b32_e32 v170, 16, v170
	v_lshlrev_b32_e32 v171, 16, v171
	v_lshlrev_b32_e32 v172, 16, v172
	v_lshlrev_b32_e32 v173, 16, v173
	v_lshlrev_b32_e32 v174, 16, v174
	v_lshlrev_b32_e32 v175, 16, v175
	v_lshlrev_b32_e32 v176, 16, v176
	v_lshlrev_b32_e32 v177, 16, v177
	v_lshlrev_b32_e32 v178, 16, v178
	v_lshlrev_b32_e32 v179, 16, v179
	v_lshlrev_b32_e32 v148, 16, v148
	v_lshlrev_b32_e32 v149, 16, v149
	v_lshlrev_b32_e32 v150, 16, v150
	v_lshlrev_b32_e32 v151, 16, v151
	v_lshlrev_b32_e32 v152, 16, v152
	v_lshlrev_b32_e32 v153, 16, v153
	v_lshlrev_b32_e32 v154, 16, v154
	v_lshlrev_b32_e32 v155, 16, v155
	v_lshlrev_b32_e32 v156, 16, v156
	v_lshlrev_b32_e32 v157, 16, v157
	v_lshlrev_b32_e32 v158, 16, v158
	v_lshlrev_b32_e32 v159, 16, v159
	v_lshlrev_b32_e32 v160, 16, v160
	v_lshlrev_b32_e32 v161, 16, v161
	v_lshlrev_b32_e32 v162, 16, v162
	v_lshlrev_b32_e32 v163, 16, v163
	v_mul_f32_e32 v164, v18, v164
	v_mul_f32_e32 v165, v19, v165
	v_mul_f32_e32 v166, v20, v166
	v_mul_f32_e32 v167, v21, v167
	v_mul_f32_e32 v168, v22, v168
	v_mul_f32_e32 v169, v23, v169
	v_mul_f32_e32 v170, v24, v170
	v_mul_f32_e32 v171, v25, v171
	v_mul_f32_e32 v172, v26, v172
	v_mul_f32_e32 v173, v27, v173
	v_mul_f32_e32 v174, v28, v174
	v_mul_f32_e32 v175, v29, v175
	v_mul_f32_e32 v176, v30, v176
	v_mul_f32_e32 v177, v31, v177
	v_mul_f32_e32 v178, v32, v178
	v_mul_f32_e32 v179, v33, v179
	v_mul_f32_e32 v148, 0x3e000000, v148
	v_mul_f32_e32 v149, 0x3e000000, v149
	v_mul_f32_e32 v150, 0x3e000000, v150
	v_mul_f32_e32 v151, 0x3e000000, v151
	v_mul_f32_e32 v152, 0x3e000000, v152
	v_mul_f32_e32 v153, 0x3e000000, v153
	v_mul_f32_e32 v154, 0x3e000000, v154
	v_mul_f32_e32 v155, 0x3e000000, v155
	v_mul_f32_e32 v156, 0x3e000000, v156
	v_mul_f32_e32 v157, 0x3e000000, v157
	v_mul_f32_e32 v158, 0x3e000000, v158
	v_mul_f32_e32 v159, 0x3e000000, v159
	v_mul_f32_e32 v160, 0x3e000000, v160
; __device__ __forceinline__ unsigned f2bf(float f) { unsigned r; asm("v_cvt_pk_bf16_f32 %0, %1, %1" : "=v"(r) : "v"(f)); return r & 0xffffu; }
; __device__ __forceinline__ void gl1_item(PREF p, int l, int item, bool valid, LAS unsigned char* pl, int sw, int lane) {
;     ...
;             for (int ss = 0; ss < 16; ++ss) { const int s = g4 * 16 + ss; const int i = d ? 63 - s : s;
;                 float z = bup;
; #pragma unroll
;                 for (int r2 = 0; r2 < 8; ++r2) { const unsigned w = (unsigned)__builtin_amdgcn_readlane((int)lrp[r2], i);
;                     z = __builtin_amdgcn_fdot2_f32_bf16(__builtin_bit_cast(bf16x2_t, w), __builtin_bit_cast(bf16x2_t, wupp[r2]), z, false); }
;     ...
;                 const float kt = kc[ss] * en, qt = qc[ss] * 0.125f * ep;
;                 const unsigned ktb = f2bf(kt);
;                 sKt[lane * 72 + i] = (bf16_t)ktb;
;                 QK[rowi * 1024 + d * 512 + h * 64 + lane] = (bf16_t)f2bf(qt);
;                 QK[rowi * 1024 + d * 512 + 256 + h * 64 + lane] = (bf16_t)ktb;
;             }
	v_mul_f32_e32 v161, 0x3e000000, v161
	v_mul_f32_e32 v162, 0x3e000000, v162
	v_mul_f32_e32 v163, 0x3e000000, v163
	v_mul_f32_e32 v148, v148, v236
	v_mul_f32_e32 v149, v149, v237
	v_mul_f32_e32 v150, v150, v238
	v_mul_f32_e32 v151, v151, v239
	v_mul_f32_e32 v152, v152, v240
	v_mul_f32_e32 v153, v153, v241
	v_mul_f32_e32 v154, v154, v242
	v_mul_f32_e32 v155, v155, v243
	v_mul_f32_e32 v156, v156, v244
	v_mul_f32_e32 v157, v157, v245
	v_mul_f32_e32 v158, v158, v246
	v_mul_f32_e32 v159, v159, v247
	v_mul_f32_e32 v160, v160, v248
	v_mul_f32_e32 v161, v161, v249
	v_mul_f32_e32 v162, v162, v250
	v_mul_f32_e32 v163, v163, v251
	v_cvt_pk_bf16_f32 v164, v164, v164
	v_cvt_pk_bf16_f32 v165, v165, v165
	v_cvt_pk_bf16_f32 v166, v166, v166
	v_cvt_pk_bf16_f32 v167, v167, v167
	v_cvt_pk_bf16_f32 v168, v168, v168
	v_cvt_pk_bf16_f32 v169, v169, v169
	v_cvt_pk_bf16_f32 v170, v170, v170
	v_cvt_pk_bf16_f32 v171, v171, v171
	v_cvt_pk_bf16_f32 v172, v172, v172
	v_cvt_pk_bf16_f32 v173, v173, v173
	v_cvt_pk_bf16_f32 v174, v174, v174
	v_cvt_pk_bf16_f32 v175, v175, v175
	v_cvt_pk_bf16_f32 v176, v176, v176
	v_cvt_pk_bf16_f32 v177, v177, v177
	v_cvt_pk_bf16_f32 v178, v178, v178
	v_cvt_pk_bf16_f32 v179, v179, v179
	v_cvt_pk_bf16_f32 v148, v148, v148
	v_cvt_pk_bf16_f32 v149, v149, v149
	v_cvt_pk_bf16_f32 v150, v150, v150
	v_cvt_pk_bf16_f32 v151, v151, v151
	v_cvt_pk_bf16_f32 v152, v152, v152
	v_cvt_pk_bf16_f32 v153, v153, v153
	v_cvt_pk_bf16_f32 v154, v154, v154
	v_cvt_pk_bf16_f32 v155, v155, v155
	v_cvt_pk_bf16_f32 v156, v156, v156
	v_cvt_pk_bf16_f32 v157, v157, v157
	v_cvt_pk_bf16_f32 v158, v158, v158
	v_cvt_pk_bf16_f32 v159, v159, v159
	v_cvt_pk_bf16_f32 v160, v160, v160
	v_cvt_pk_bf16_f32 v161, v161, v161
	v_cvt_pk_bf16_f32 v162, v162, v162
	v_cvt_pk_bf16_f32 v163, v163, v163
	ds_write_b16 v60, v164
	v_add_u32_e32 v60, v61, v60
	global_store_short v134, v148, s[4:5]
	global_store_short v134, v164, s[4:5] offset:512
	s_add_u32 s4, s4, s56
	s_addc_u32 s5, s5, s3
	ds_write_b16 v60, v165
	v_add_u32_e32 v60, v61, v60
	global_store_short v134, v149, s[4:5]
	global_store_short v134, v165, s[4:5] offset:512
	s_add_u32 s4, s4, s56
	s_addc_u32 s5, s5, s3
	ds_write_b16 v60, v166
	v_add_u32_e32 v60, v61, v60
	global_store_short v134, v150, s[4:5]
	global_store_short v134, v166, s[4:5] offset:512
	s_add_u32 s4, s4, s56
	s_addc_u32 s5, s5, s3
	ds_write_b16 v60, v167
	v_add_u32_e32 v60, v61, v60
	global_store_short v134, v151, s[4:5]
	global_store_short v134, v167, s[4:5] offset:512
	s_add_u32 s4, s4, s56
	s_addc_u32 s5, s5, s3
	ds_write_b16 v60, v168
	v_add_u32_e32 v60, v61, v60
	global_store_short v134, v152, s[4:5]
	global_store_short v134, v168, s[4:5] offset:512
	s_add_u32 s4, s4, s56
	s_addc_u32 s5, s5, s3
	ds_write_b16 v60, v169
	v_add_u32_e32 v60, v61, v60
	global_store_short v134, v153, s[4:5]
	global_store_short v134, v169, s[4:5] offset:512
	s_add_u32 s4, s4, s56
	s_addc_u32 s5, s5, s3
	ds_write_b16 v60, v170
	v_add_u32_e32 v60, v61, v60
	global_store_short v134, v154, s[4:5]
	global_store_short v134, v170, s[4:5] offset:512
	s_add_u32 s4, s4, s56
	s_addc_u32 s5, s5, s3
	ds_write_b16 v60, v171
	v_add_u32_e32 v60, v61, v60
	global_store_short v134, v155, s[4:5]
	global_store_short v134, v171, s[4:5] offset:512
	s_add_u32 s4, s4, s56
	s_addc_u32 s5, s5, s3
	ds_write_b16 v60, v172
	v_add_u32_e32 v60, v61, v60
	global_store_short v134, v156, s[4:5]
	global_store_short v134, v172, s[4:5] offset:512
	s_add_u32 s4, s4, s56
	s_addc_u32 s5, s5, s3
	ds_write_b16 v60, v173
	v_add_u32_e32 v60, v61, v60
	global_store_short v134, v157, s[4:5]
	global_store_short v134, v173, s[4:5] offset:512
	s_add_u32 s4, s4, s56
	s_addc_u32 s5, s5, s3
	ds_write_b16 v60, v174
	v_add_u32_e32 v60, v61, v60
	global_store_short v134, v158, s[4:5]
	global_store_short v134, v174, s[4:5] offset:512
	s_add_u32 s4, s4, s56
	s_addc_u32 s5, s5, s3
	ds_write_b16 v60, v175
	v_add_u32_e32 v60, v61, v60
	global_store_short v134, v159, s[4:5]
	global_store_short v134, v175, s[4:5] offset:512
	s_add_u32 s4, s4, s56
	s_addc_u32 s5, s5, s3
	ds_write_b16 v60, v176
	v_add_u32_e32 v60, v61, v60
	global_store_short v134, v160, s[4:5]
	global_store_short v134, v176, s[4:5] offset:512
	s_add_u32 s4, s4, s56
	s_addc_u32 s5, s5, s3
	ds_write_b16 v60, v177
	v_add_u32_e32 v60, v61, v60
	global_store_short v134, v161, s[4:5]
	global_store_short v134, v177, s[4:5] offset:512
	s_add_u32 s4, s4, s56
	s_addc_u32 s5, s5, s3
	ds_write_b16 v60, v178
	v_add_u32_e32 v60, v61, v60
	global_store_short v134, v162, s[4:5]
	global_store_short v134, v178, s[4:5] offset:512
	s_add_u32 s4, s4, s56
	s_addc_u32 s5, s5, s3
	ds_write_b16 v60, v179
	v_add_u32_e32 v60, v61, v60
	global_store_short v134, v163, s[4:5]
	global_store_short v134, v179, s[4:5] offset:512
	s_add_u32 s4, s4, s56
	s_addc_u32 s5, s5, s3
	v_mov_b32_e32 v236, v16
	v_dot2c_f32_bf16_dpp v236, v106, v8 row_newbcast:0 row_mask:0xf bank_mask:0xf
	v_dot2c_f32_bf16_dpp v236, v107, v9 row_newbcast:0 row_mask:0xf bank_mask:0xf
	v_dot2c_f32_bf16_dpp v236, v108, v10 row_newbcast:0 row_mask:0xf bank_mask:0xf
	v_dot2c_f32_bf16_dpp v236, v109, v11 row_newbcast:0 row_mask:0xf bank_mask:0xf
	v_dot2c_f32_bf16_dpp v236, v110, v12 row_newbcast:0 row_mask:0xf bank_mask:0xf
	v_dot2c_f32_bf16_dpp v236, v111, v13 row_newbcast:0 row_mask:0xf bank_mask:0xf
	v_dot2c_f32_bf16_dpp v236, v112, v14 row_newbcast:0 row_mask:0xf bank_mask:0xf
	v_dot2c_f32_bf16_dpp v236, v113, v15 row_newbcast:0 row_mask:0xf bank_mask:0xf
	v_mov_b32_e32 v237, v16
	v_dot2c_f32_bf16_dpp v237, v106, v8 row_newbcast:1 row_mask:0xf bank_mask:0xf
	v_dot2c_f32_bf16_dpp v237, v107, v9 row_newbcast:1 row_mask:0xf bank_mask:0xf
; __device__ __forceinline__ void gl1_item(PREF p, int l, int item, bool valid, LAS unsigned char* pl, int sw, int lane) {
;     ...
;             for (int ss = 0; ss < 16; ++ss) { const int s = g4 * 16 + ss; const int i = d ? 63 - s : s;
;                 float z = bup;
; #pragma unroll
;                 for (int r2 = 0; r2 < 8; ++r2) { const unsigned w = (unsigned)__builtin_amdgcn_readlane((int)lrp[r2], i);
;                     z = __builtin_amdgcn_fdot2_f32_bf16(__builtin_bit_cast(bf16x2_t, w), __builtin_bit_cast(bf16x2_t, wupp[r2]), z, false); }
	v_dot2c_f32_bf16_dpp v237, v108, v10 row_newbcast:1 row_mask:0xf bank_mask:0xf
	v_dot2c_f32_bf16_dpp v237, v109, v11 row_newbcast:1 row_mask:0xf bank_mask:0xf
	v_dot2c_f32_bf16_dpp v237, v110, v12 row_newbcast:1 row_mask:0xf bank_mask:0xf
	v_dot2c_f32_bf16_dpp v237, v111, v13 row_newbcast:1 row_mask:0xf bank_mask:0xf
	v_dot2c_f32_bf16_dpp v237, v112, v14 row_newbcast:1 row_mask:0xf bank_mask:0xf
	v_dot2c_f32_bf16_dpp v237, v113, v15 row_newbcast:1 row_mask:0xf bank_mask:0xf
	v_mov_b32_e32 v238, v16
	v_dot2c_f32_bf16_dpp v238, v106, v8 row_newbcast:2 row_mask:0xf bank_mask:0xf
	v_dot2c_f32_bf16_dpp v238, v107, v9 row_newbcast:2 row_mask:0xf bank_mask:0xf
	v_dot2c_f32_bf16_dpp v238, v108, v10 row_newbcast:2 row_mask:0xf bank_mask:0xf
	v_dot2c_f32_bf16_dpp v238, v109, v11 row_newbcast:2 row_mask:0xf bank_mask:0xf
	v_dot2c_f32_bf16_dpp v238, v110, v12 row_newbcast:2 row_mask:0xf bank_mask:0xf
	v_dot2c_f32_bf16_dpp v238, v111, v13 row_newbcast:2 row_mask:0xf bank_mask:0xf
	v_dot2c_f32_bf16_dpp v238, v112, v14 row_newbcast:2 row_mask:0xf bank_mask:0xf
	v_dot2c_f32_bf16_dpp v238, v113, v15 row_newbcast:2 row_mask:0xf bank_mask:0xf
	v_mov_b32_e32 v239, v16
	v_dot2c_f32_bf16_dpp v239, v106, v8 row_newbcast:3 row_mask:0xf bank_mask:0xf
	v_dot2c_f32_bf16_dpp v239, v107, v9 row_newbcast:3 row_mask:0xf bank_mask:0xf
	v_dot2c_f32_bf16_dpp v239, v108, v10 row_newbcast:3 row_mask:0xf bank_mask:0xf
	v_dot2c_f32_bf16_dpp v239, v109, v11 row_newbcast:3 row_mask:0xf bank_mask:0xf
	v_dot2c_f32_bf16_dpp v239, v110, v12 row_newbcast:3 row_mask:0xf bank_mask:0xf
	v_dot2c_f32_bf16_dpp v239, v111, v13 row_newbcast:3 row_mask:0xf bank_mask:0xf
	v_dot2c_f32_bf16_dpp v239, v112, v14 row_newbcast:3 row_mask:0xf bank_mask:0xf
	v_dot2c_f32_bf16_dpp v239, v113, v15 row_newbcast:3 row_mask:0xf bank_mask:0xf
	v_mov_b32_e32 v240, v16
	v_dot2c_f32_bf16_dpp v240, v106, v8 row_newbcast:4 row_mask:0xf bank_mask:0xf
	v_dot2c_f32_bf16_dpp v240, v107, v9 row_newbcast:4 row_mask:0xf bank_mask:0xf
	v_dot2c_f32_bf16_dpp v240, v108, v10 row_newbcast:4 row_mask:0xf bank_mask:0xf
	v_dot2c_f32_bf16_dpp v240, v109, v11 row_newbcast:4 row_mask:0xf bank_mask:0xf
	v_dot2c_f32_bf16_dpp v240, v110, v12 row_newbcast:4 row_mask:0xf bank_mask:0xf
	v_dot2c_f32_bf16_dpp v240, v111, v13 row_newbcast:4 row_mask:0xf bank_mask:0xf
	v_dot2c_f32_bf16_dpp v240, v112, v14 row_newbcast:4 row_mask:0xf bank_mask:0xf
	v_dot2c_f32_bf16_dpp v240, v113, v15 row_newbcast:4 row_mask:0xf bank_mask:0xf
	v_mov_b32_e32 v241, v16
	v_dot2c_f32_bf16_dpp v241, v106, v8 row_newbcast:5 row_mask:0xf bank_mask:0xf
	v_dot2c_f32_bf16_dpp v241, v107, v9 row_newbcast:5 row_mask:0xf bank_mask:0xf
	v_dot2c_f32_bf16_dpp v241, v108, v10 row_newbcast:5 row_mask:0xf bank_mask:0xf
	v_dot2c_f32_bf16_dpp v241, v109, v11 row_newbcast:5 row_mask:0xf bank_mask:0xf
	v_dot2c_f32_bf16_dpp v241, v110, v12 row_newbcast:5 row_mask:0xf bank_mask:0xf
	v_dot2c_f32_bf16_dpp v241, v111, v13 row_newbcast:5 row_mask:0xf bank_mask:0xf
	v_dot2c_f32_bf16_dpp v241, v112, v14 row_newbcast:5 row_mask:0xf bank_mask:0xf
	v_dot2c_f32_bf16_dpp v241, v113, v15 row_newbcast:5 row_mask:0xf bank_mask:0xf
	v_mov_b32_e32 v242, v16
	v_dot2c_f32_bf16_dpp v242, v106, v8 row_newbcast:6 row_mask:0xf bank_mask:0xf
	v_dot2c_f32_bf16_dpp v242, v107, v9 row_newbcast:6 row_mask:0xf bank_mask:0xf
	v_dot2c_f32_bf16_dpp v242, v108, v10 row_newbcast:6 row_mask:0xf bank_mask:0xf
	v_dot2c_f32_bf16_dpp v242, v109, v11 row_newbcast:6 row_mask:0xf bank_mask:0xf
	v_dot2c_f32_bf16_dpp v242, v110, v12 row_newbcast:6 row_mask:0xf bank_mask:0xf
	v_dot2c_f32_bf16_dpp v242, v111, v13 row_newbcast:6 row_mask:0xf bank_mask:0xf
	v_dot2c_f32_bf16_dpp v242, v112, v14 row_newbcast:6 row_mask:0xf bank_mask:0xf
	v_dot2c_f32_bf16_dpp v242, v113, v15 row_newbcast:6 row_mask:0xf bank_mask:0xf
	v_mov_b32_e32 v243, v16
	v_dot2c_f32_bf16_dpp v243, v106, v8 row_newbcast:7 row_mask:0xf bank_mask:0xf
	v_dot2c_f32_bf16_dpp v243, v107, v9 row_newbcast:7 row_mask:0xf bank_mask:0xf
	v_dot2c_f32_bf16_dpp v243, v108, v10 row_newbcast:7 row_mask:0xf bank_mask:0xf
	v_dot2c_f32_bf16_dpp v243, v109, v11 row_newbcast:7 row_mask:0xf bank_mask:0xf
	v_dot2c_f32_bf16_dpp v243, v110, v12 row_newbcast:7 row_mask:0xf bank_mask:0xf
	v_dot2c_f32_bf16_dpp v243, v111, v13 row_newbcast:7 row_mask:0xf bank_mask:0xf
	v_dot2c_f32_bf16_dpp v243, v112, v14 row_newbcast:7 row_mask:0xf bank_mask:0xf
	v_dot2c_f32_bf16_dpp v243, v113, v15 row_newbcast:7 row_mask:0xf bank_mask:0xf
	v_mov_b32_e32 v244, v16
	v_dot2c_f32_bf16_dpp v244, v106, v8 row_newbcast:8 row_mask:0xf bank_mask:0xf
	v_dot2c_f32_bf16_dpp v244, v107, v9 row_newbcast:8 row_mask:0xf bank_mask:0xf
	v_dot2c_f32_bf16_dpp v244, v108, v10 row_newbcast:8 row_mask:0xf bank_mask:0xf
	v_dot2c_f32_bf16_dpp v244, v109, v11 row_newbcast:8 row_mask:0xf bank_mask:0xf
	v_dot2c_f32_bf16_dpp v244, v110, v12 row_newbcast:8 row_mask:0xf bank_mask:0xf
	v_dot2c_f32_bf16_dpp v244, v111, v13 row_newbcast:8 row_mask:0xf bank_mask:0xf
	v_dot2c_f32_bf16_dpp v244, v112, v14 row_newbcast:8 row_mask:0xf bank_mask:0xf
	v_dot2c_f32_bf16_dpp v244, v113, v15 row_newbcast:8 row_mask:0xf bank_mask:0xf
	v_mov_b32_e32 v245, v16
	v_dot2c_f32_bf16_dpp v245, v106, v8 row_newbcast:9 row_mask:0xf bank_mask:0xf
	v_dot2c_f32_bf16_dpp v245, v107, v9 row_newbcast:9 row_mask:0xf bank_mask:0xf
	v_dot2c_f32_bf16_dpp v245, v108, v10 row_newbcast:9 row_mask:0xf bank_mask:0xf
	v_dot2c_f32_bf16_dpp v245, v109, v11 row_newbcast:9 row_mask:0xf bank_mask:0xf
	v_dot2c_f32_bf16_dpp v245, v110, v12 row_newbcast:9 row_mask:0xf bank_mask:0xf
	v_dot2c_f32_bf16_dpp v245, v111, v13 row_newbcast:9 row_mask:0xf bank_mask:0xf
; __device__ __forceinline__ void gl1_item(PREF p, int l, int item, bool valid, LAS unsigned char* pl, int sw, int lane) {
;     ...
;             for (int ss = 0; ss < 16; ++ss) { const int s = g4 * 16 + ss; const int i = d ? 63 - s : s;
;                 float z = bup;
; #pragma unroll
;                 for (int r2 = 0; r2 < 8; ++r2) { const unsigned w = (unsigned)__builtin_amdgcn_readlane((int)lrp[r2], i);
;                     z = __builtin_amdgcn_fdot2_f32_bf16(__builtin_bit_cast(bf16x2_t, w), __builtin_bit_cast(bf16x2_t, wupp[r2]), z, false); }
;                 gv[ss] = -(fmaxf(-z, 0.f) + __logf(1.f + __expf(-fabsf(z)))) * (1.f / 16.f);
	v_dot2c_f32_bf16_dpp v245, v112, v14 row_newbcast:9 row_mask:0xf bank_mask:0xf
	v_dot2c_f32_bf16_dpp v245, v113, v15 row_newbcast:9 row_mask:0xf bank_mask:0xf
	v_mov_b32_e32 v246, v16
	v_dot2c_f32_bf16_dpp v246, v106, v8 row_newbcast:10 row_mask:0xf bank_mask:0xf
	v_dot2c_f32_bf16_dpp v246, v107, v9 row_newbcast:10 row_mask:0xf bank_mask:0xf
	v_dot2c_f32_bf16_dpp v246, v108, v10 row_newbcast:10 row_mask:0xf bank_mask:0xf
	v_dot2c_f32_bf16_dpp v246, v109, v11 row_newbcast:10 row_mask:0xf bank_mask:0xf
	v_dot2c_f32_bf16_dpp v246, v110, v12 row_newbcast:10 row_mask:0xf bank_mask:0xf
	v_dot2c_f32_bf16_dpp v246, v111, v13 row_newbcast:10 row_mask:0xf bank_mask:0xf
	v_dot2c_f32_bf16_dpp v246, v112, v14 row_newbcast:10 row_mask:0xf bank_mask:0xf
	v_dot2c_f32_bf16_dpp v246, v113, v15 row_newbcast:10 row_mask:0xf bank_mask:0xf
	v_mov_b32_e32 v247, v16
	v_dot2c_f32_bf16_dpp v247, v106, v8 row_newbcast:11 row_mask:0xf bank_mask:0xf
	v_dot2c_f32_bf16_dpp v247, v107, v9 row_newbcast:11 row_mask:0xf bank_mask:0xf
	v_dot2c_f32_bf16_dpp v247, v108, v10 row_newbcast:11 row_mask:0xf bank_mask:0xf
	v_dot2c_f32_bf16_dpp v247, v109, v11 row_newbcast:11 row_mask:0xf bank_mask:0xf
	v_dot2c_f32_bf16_dpp v247, v110, v12 row_newbcast:11 row_mask:0xf bank_mask:0xf
	v_dot2c_f32_bf16_dpp v247, v111, v13 row_newbcast:11 row_mask:0xf bank_mask:0xf
	v_dot2c_f32_bf16_dpp v247, v112, v14 row_newbcast:11 row_mask:0xf bank_mask:0xf
	v_dot2c_f32_bf16_dpp v247, v113, v15 row_newbcast:11 row_mask:0xf bank_mask:0xf
	v_mov_b32_e32 v248, v16
	v_dot2c_f32_bf16_dpp v248, v106, v8 row_newbcast:12 row_mask:0xf bank_mask:0xf
	v_dot2c_f32_bf16_dpp v248, v107, v9 row_newbcast:12 row_mask:0xf bank_mask:0xf
	v_dot2c_f32_bf16_dpp v248, v108, v10 row_newbcast:12 row_mask:0xf bank_mask:0xf
	v_dot2c_f32_bf16_dpp v248, v109, v11 row_newbcast:12 row_mask:0xf bank_mask:0xf
	v_dot2c_f32_bf16_dpp v248, v110, v12 row_newbcast:12 row_mask:0xf bank_mask:0xf
	v_dot2c_f32_bf16_dpp v248, v111, v13 row_newbcast:12 row_mask:0xf bank_mask:0xf
	v_dot2c_f32_bf16_dpp v248, v112, v14 row_newbcast:12 row_mask:0xf bank_mask:0xf
	v_dot2c_f32_bf16_dpp v248, v113, v15 row_newbcast:12 row_mask:0xf bank_mask:0xf
	v_mov_b32_e32 v249, v16
	v_dot2c_f32_bf16_dpp v249, v106, v8 row_newbcast:13 row_mask:0xf bank_mask:0xf
	v_dot2c_f32_bf16_dpp v249, v107, v9 row_newbcast:13 row_mask:0xf bank_mask:0xf
	v_dot2c_f32_bf16_dpp v249, v108, v10 row_newbcast:13 row_mask:0xf bank_mask:0xf
	v_dot2c_f32_bf16_dpp v249, v109, v11 row_newbcast:13 row_mask:0xf bank_mask:0xf
	v_dot2c_f32_bf16_dpp v249, v110, v12 row_newbcast:13 row_mask:0xf bank_mask:0xf
	v_dot2c_f32_bf16_dpp v249, v111, v13 row_newbcast:13 row_mask:0xf bank_mask:0xf
	v_dot2c_f32_bf16_dpp v249, v112, v14 row_newbcast:13 row_mask:0xf bank_mask:0xf
	v_dot2c_f32_bf16_dpp v249, v113, v15 row_newbcast:13 row_mask:0xf bank_mask:0xf
	v_mov_b32_e32 v250, v16
	v_dot2c_f32_bf16_dpp v250, v106, v8 row_newbcast:14 row_mask:0xf bank_mask:0xf
	v_dot2c_f32_bf16_dpp v250, v107, v9 row_newbcast:14 row_mask:0xf bank_mask:0xf
	v_dot2c_f32_bf16_dpp v250, v108, v10 row_newbcast:14 row_mask:0xf bank_mask:0xf
	v_dot2c_f32_bf16_dpp v250, v109, v11 row_newbcast:14 row_mask:0xf bank_mask:0xf
	v_dot2c_f32_bf16_dpp v250, v110, v12 row_newbcast:14 row_mask:0xf bank_mask:0xf
	v_dot2c_f32_bf16_dpp v250, v111, v13 row_newbcast:14 row_mask:0xf bank_mask:0xf
	v_dot2c_f32_bf16_dpp v250, v112, v14 row_newbcast:14 row_mask:0xf bank_mask:0xf
	v_dot2c_f32_bf16_dpp v250, v113, v15 row_newbcast:14 row_mask:0xf bank_mask:0xf
	v_mov_b32_e32 v251, v16
	v_dot2c_f32_bf16_dpp v251, v106, v8 row_newbcast:15 row_mask:0xf bank_mask:0xf
	v_dot2c_f32_bf16_dpp v251, v107, v9 row_newbcast:15 row_mask:0xf bank_mask:0xf
	v_dot2c_f32_bf16_dpp v251, v108, v10 row_newbcast:15 row_mask:0xf bank_mask:0xf
	v_dot2c_f32_bf16_dpp v251, v109, v11 row_newbcast:15 row_mask:0xf bank_mask:0xf
	v_dot2c_f32_bf16_dpp v251, v110, v12 row_newbcast:15 row_mask:0xf bank_mask:0xf
	v_dot2c_f32_bf16_dpp v251, v111, v13 row_newbcast:15 row_mask:0xf bank_mask:0xf
	v_dot2c_f32_bf16_dpp v251, v112, v14 row_newbcast:15 row_mask:0xf bank_mask:0xf
	v_dot2c_f32_bf16_dpp v251, v113, v15 row_newbcast:15 row_mask:0xf bank_mask:0xf
	s_nop 2
	v_mul_f32_e64 v18, |v236|, s1
	v_mul_f32_e64 v19, |v237|, s1
	v_mul_f32_e64 v20, |v238|, s1
	v_mul_f32_e64 v21, |v239|, s1
	v_mul_f32_e64 v22, |v240|, s1
	v_mul_f32_e64 v23, |v241|, s1
	v_mul_f32_e64 v24, |v242|, s1
	v_mul_f32_e64 v25, |v243|, s1
	v_mul_f32_e64 v26, |v244|, s1
	v_mul_f32_e64 v27, |v245|, s1
	v_mul_f32_e64 v28, |v246|, s1
	v_mul_f32_e64 v29, |v247|, s1
	v_mul_f32_e64 v30, |v248|, s1
	v_mul_f32_e64 v31, |v249|, s1
	v_mul_f32_e64 v32, |v250|, s1
	v_mul_f32_e64 v33, |v251|, s1
	v_exp_f32_e32 v18, v18
	v_exp_f32_e32 v19, v19
	v_exp_f32_e32 v20, v20
	v_exp_f32_e32 v21, v21
	v_exp_f32_e32 v22, v22
	v_exp_f32_e32 v23, v23
	v_exp_f32_e32 v24, v24
	v_exp_f32_e32 v25, v25
	v_exp_f32_e32 v26, v26
	v_exp_f32_e32 v27, v27
	v_exp_f32_e32 v28, v28
	v_exp_f32_e32 v29, v29
	v_exp_f32_e32 v30, v30
	v_exp_f32_e32 v31, v31
	v_exp_f32_e32 v32, v32
	v_exp_f32_e32 v33, v33
	v_max_f32_e64 v236, -v236, 0
	v_max_f32_e64 v237, -v237, 0
	v_max_f32_e64 v238, -v238, 0
	v_max_f32_e64 v239, -v239, 0
	v_max_f32_e64 v240, -v240, 0
	v_max_f32_e64 v241, -v241, 0
	v_max_f32_e64 v242, -v242, 0
	v_max_f32_e64 v243, -v243, 0
	v_max_f32_e64 v244, -v244, 0
	v_max_f32_e64 v245, -v245, 0
	v_max_f32_e64 v246, -v246, 0
	v_max_f32_e64 v247, -v247, 0
	v_max_f32_e64 v248, -v248, 0
	v_max_f32_e64 v249, -v249, 0
	v_max_f32_e64 v250, -v250, 0
	v_max_f32_e64 v251, -v251, 0
	v_add_f32_e32 v18, 1.0, v18
	v_add_f32_e32 v19, 1.0, v19
	v_add_f32_e32 v20, 1.0, v20
; __device__ __forceinline__ void gl1_item(PREF p, int l, int item, bool valid, LAS unsigned char* pl, int sw, int lane) {
;     ...
;             if (g4 < 3) {
; #pragma unroll
;                 for (int ss = 0; ss < 16; ++ss) { const int s = (g4 + 1) * 16 + ss; const int i = d ? 63 - s : s; const bf16_t* pr = P + (size_t)(row0 + i * rstride) * PW + h * 64 + lane;
;                     qn[ss] = __builtin_bit_cast(float, (unsigned)pr[1024]); kn[ss] = __builtin_bit_cast(float, (unsigned)pr[1280]); }
;                 __builtin_amdgcn_sched_barrier(0);
;             }
;             float gv[16];
; #pragma unroll
;             for (int ss = 0; ss < 16; ++ss) { const int s = g4 * 16 + ss; const int i = d ? 63 - s : s;
;                 float z = bup;
; #pragma unroll
;                 for (int r2 = 0; r2 < 8; ++r2) { const unsigned w = (unsigned)__builtin_amdgcn_readlane((int)lrp[r2], i);
;                     z = __builtin_amdgcn_fdot2_f32_bf16(__builtin_bit_cast(bf16x2_t, w), __builtin_bit_cast(bf16x2_t, wupp[r2]), z, false); }
;                 gv[ss] = -(fmaxf(-z, 0.f) + __logf(1.f + __expf(-fabsf(z)))) * (1.f / 16.f);
;                 __builtin_amdgcn_sched_barrier(0);
;             }
; #pragma unroll
;             for (int ss = 0; ss < 16; ++ss) { const int s = g4 * 16 + ss; const int i = d ? 63 - s : s; const size_t rowi = (size_t)(row0 + i * rstride);
;                 bc += gv[ss];
;                 const float en = __expf(-bc), ep = __expf(bc);
;                 const float kt = kc[ss] * en, qt = qc[ss] * 0.125f * ep;
	v_add_f32_e32 v21, 1.0, v21
	v_add_f32_e32 v22, 1.0, v22
	v_add_f32_e32 v23, 1.0, v23
	v_add_f32_e32 v24, 1.0, v24
	v_add_f32_e32 v25, 1.0, v25
	v_add_f32_e32 v26, 1.0, v26
	v_add_f32_e32 v27, 1.0, v27
	v_add_f32_e32 v28, 1.0, v28
	v_add_f32_e32 v29, 1.0, v29
	v_add_f32_e32 v30, 1.0, v30
	v_add_f32_e32 v31, 1.0, v31
	v_add_f32_e32 v32, 1.0, v32
	v_add_f32_e32 v33, 1.0, v33
	v_log_f32_e32 v18, v18
	v_log_f32_e32 v19, v19
	v_log_f32_e32 v20, v20
	v_log_f32_e32 v21, v21
	v_log_f32_e32 v22, v22
	v_log_f32_e32 v23, v23
	v_log_f32_e32 v24, v24
	v_log_f32_e32 v25, v25
	v_log_f32_e32 v26, v26
	v_log_f32_e32 v27, v27
	v_log_f32_e32 v28, v28
	v_log_f32_e32 v29, v29
	v_log_f32_e32 v30, v30
	v_log_f32_e32 v31, v31
	v_log_f32_e32 v32, v32
	v_log_f32_e32 v33, v33
	s_mov_b32 s45, 0x3f317217
	v_mul_f32_e32 v70, 0x3f317217, v18
	v_mul_f32_e32 v71, 0x3f317217, v19
	v_mul_f32_e32 v72, 0x3f317217, v20
	v_mul_f32_e32 v73, 0x3f317217, v21
	v_mul_f32_e32 v74, 0x3f317217, v22
	v_mul_f32_e32 v75, 0x3f317217, v23
	v_mul_f32_e32 v76, 0x3f317217, v24
	v_mul_f32_e32 v77, 0x3f317217, v25
	v_mul_f32_e32 v78, 0x3f317217, v26
	v_mul_f32_e32 v79, 0x3f317217, v27
	v_mul_f32_e32 v80, 0x3f317217, v28
	v_mul_f32_e32 v81, 0x3f317217, v29
	v_mul_f32_e32 v82, 0x3f317217, v30
	v_mul_f32_e32 v83, 0x3f317217, v31
	v_mul_f32_e32 v84, 0x3f317217, v32
	v_mul_f32_e32 v85, 0x3f317217, v33
	v_fma_f32 v70, v18, s45, -v70
	v_fma_f32 v71, v19, s45, -v71
	v_fma_f32 v72, v20, s45, -v72
	v_fma_f32 v73, v21, s45, -v73
	v_fma_f32 v74, v22, s45, -v74
	v_fma_f32 v75, v23, s45, -v75
	v_fma_f32 v76, v24, s45, -v76
	v_fma_f32 v77, v25, s45, -v77
	v_fma_f32 v78, v26, s45, -v78
	v_fma_f32 v79, v27, s45, -v79
	v_fma_f32 v80, v28, s45, -v80
	v_fma_f32 v81, v29, s45, -v81
	v_fma_f32 v82, v30, s45, -v82
	v_fma_f32 v83, v31, s45, -v83
	v_fma_f32 v84, v32, s45, -v84
	v_fma_f32 v85, v33, s45, -v85
	v_fmac_f32_e32 v70, 0x3377d1cf, v18
	v_fmac_f32_e32 v71, 0x3377d1cf, v19
	v_fmac_f32_e32 v72, 0x3377d1cf, v20
	v_fmac_f32_e32 v73, 0x3377d1cf, v21
	v_fmac_f32_e32 v74, 0x3377d1cf, v22
	v_fmac_f32_e32 v75, 0x3377d1cf, v23
	v_fmac_f32_e32 v76, 0x3377d1cf, v24
	v_fmac_f32_e32 v77, 0x3377d1cf, v25
	v_fmac_f32_e32 v78, 0x3377d1cf, v26
	v_fmac_f32_e32 v79, 0x3377d1cf, v27
	v_fmac_f32_e32 v80, 0x3377d1cf, v28
	v_fmac_f32_e32 v81, 0x3377d1cf, v29
	v_fmac_f32_e32 v82, 0x3377d1cf, v30
	v_fmac_f32_e32 v83, 0x3377d1cf, v31
	v_fmac_f32_e32 v84, 0x3377d1cf, v32
	v_fmac_f32_e32 v85, 0x3377d1cf, v33
	v_fmac_f32_e32 v70, 0x3f317217, v18
	v_fmac_f32_e32 v71, 0x3f317217, v19
	v_fmac_f32_e32 v72, 0x3f317217, v20
	v_fmac_f32_e32 v73, 0x3f317217, v21
	v_fmac_f32_e32 v74, 0x3f317217, v22
	v_fmac_f32_e32 v75, 0x3f317217, v23
	v_fmac_f32_e32 v76, 0x3f317217, v24
	v_fmac_f32_e32 v77, 0x3f317217, v25
	v_fmac_f32_e32 v78, 0x3f317217, v26
	v_fmac_f32_e32 v79, 0x3f317217, v27
	v_fmac_f32_e32 v80, 0x3f317217, v28
	v_fmac_f32_e32 v81, 0x3f317217, v29
	v_fmac_f32_e32 v82, 0x3f317217, v30
	v_fmac_f32_e32 v83, 0x3f317217, v31
	v_fmac_f32_e32 v84, 0x3f317217, v32
	v_fmac_f32_e32 v85, 0x3f317217, v33
	v_add_f32_e32 v236, v236, v70
	v_add_f32_e32 v237, v237, v71
	v_add_f32_e32 v238, v238, v72
	v_add_f32_e32 v239, v239, v73
	v_add_f32_e32 v240, v240, v74
	v_add_f32_e32 v241, v241, v75
	v_add_f32_e32 v242, v242, v76
	v_add_f32_e32 v243, v243, v77
	v_add_f32_e32 v244, v244, v78
	v_add_f32_e32 v245, v245, v79
	v_add_f32_e32 v246, v246, v80
	v_add_f32_e32 v247, v247, v81
	v_add_f32_e32 v248, v248, v82
	v_add_f32_e32 v249, v249, v83
	v_add_f32_e32 v250, v250, v84
	v_add_f32_e32 v251, v251, v85
	v_fma_f32 v70, v236, s49, v17
	v_fma_f32 v71, v237, s49, v70
	v_fma_f32 v72, v238, s49, v71
	v_fma_f32 v73, v239, s49, v72
	v_fma_f32 v74, v240, s49, v73
	v_fma_f32 v75, v241, s49, v74
	v_fma_f32 v76, v242, s49, v75
	v_fma_f32 v77, v243, s49, v76
	v_fma_f32 v78, v244, s49, v77
	v_fma_f32 v79, v245, s49, v78
	v_fma_f32 v80, v246, s49, v79
	v_fma_f32 v81, v247, s49, v80
	v_fma_f32 v82, v248, s49, v81
	v_fma_f32 v83, v249, s49, v82
	v_fma_f32 v84, v250, s49, v83
	v_fma_f32 v85, v251, s49, v84
	v_mov_b32_e32 v17, v85
	s_waitcnt vmcnt(32)
	global_load_ushort v148, v134, s[6:7]
	global_load_ushort v164, v134, s[6:7] offset:512
	s_add_u32 s6, s6, s54
	s_addc_u32 s7, s7, s55
	global_load_ushort v149, v134, s[6:7]
	global_load_ushort v165, v134, s[6:7] offset:512
	s_add_u32 s6, s6, s54
	s_addc_u32 s7, s7, s55
	global_load_ushort v150, v134, s[6:7]
	global_load_ushort v166, v134, s[6:7] offset:512
	s_add_u32 s6, s6, s54
	s_addc_u32 s7, s7, s55
	global_load_ushort v151, v134, s[6:7]
	global_load_ushort v167, v134, s[6:7] offset:512
	s_add_u32 s6, s6, s54
	s_addc_u32 s7, s7, s55
	global_load_ushort v152, v134, s[6:7]
	global_load_ushort v168, v134, s[6:7] offset:512
	s_add_u32 s6, s6, s54
	s_addc_u32 s7, s7, s55
	global_load_ushort v153, v134, s[6:7]
	global_load_ushort v169, v134, s[6:7] offset:512
	s_add_u32 s6, s6, s54
	s_addc_u32 s7, s7, s55
	global_load_ushort v154, v134, s[6:7]
	global_load_ushort v170, v134, s[6:7] offset:512
	s_add_u32 s6, s6, s54
	s_addc_u32 s7, s7, s55
	global_load_ushort v155, v134, s[6:7]
	global_load_ushort v171, v134, s[6:7] offset:512
	s_add_u32 s6, s6, s54
	s_addc_u32 s7, s7, s55
	global_load_ushort v156, v134, s[6:7]
	global_load_ushort v172, v134, s[6:7] offset:512
	s_add_u32 s6, s6, s54
	s_addc_u32 s7, s7, s55
	global_load_ushort v157, v134, s[6:7]
	global_load_ushort v173, v134, s[6:7] offset:512
	s_add_u32 s6, s6, s54
	s_addc_u32 s7, s7, s55
	global_load_ushort v158, v134, s[6:7]
	global_load_ushort v174, v134, s[6:7] offset:512
	s_add_u32 s6, s6, s54
	s_addc_u32 s7, s7, s55
	global_load_ushort v159, v134, s[6:7]
; __device__ __forceinline__ unsigned f2bf(float f) { unsigned r; asm("v_cvt_pk_bf16_f32 %0, %1, %1" : "=v"(r) : "v"(f)); return r & 0xffffu; }
; __device__ __forceinline__ void gl1_item(PREF p, int l, int item, bool valid, LAS unsigned char* pl, int sw, int lane) {
;     ...
;             for (int ss = 0; ss < 16; ++ss) { const int s = g4 * 16 + ss; const int i = d ? 63 - s : s; const size_t rowi = (size_t)(row0 + i * rstride);
;                 bc += gv[ss];
;                 const float en = __expf(-bc), ep = __expf(bc);
;                 const float kt = kc[ss] * en, qt = qc[ss] * 0.125f * ep;
;                 const unsigned ktb = f2bf(kt);
;                 sKt[lane * 72 + i] = (bf16_t)ktb;
;                 QK[rowi * 1024 + d * 512 + h * 64 + lane] = (bf16_t)f2bf(qt);
;                 QK[rowi * 1024 + d * 512 + 256 + h * 64 + lane] = (bf16_t)ktb;
	global_load_ushort v175, v134, s[6:7] offset:512
	s_add_u32 s6, s6, s54
	s_addc_u32 s7, s7, s55
	global_load_ushort v160, v134, s[6:7]
	global_load_ushort v176, v134, s[6:7] offset:512
	s_add_u32 s6, s6, s54
	s_addc_u32 s7, s7, s55
	global_load_ushort v161, v134, s[6:7]
	global_load_ushort v177, v134, s[6:7] offset:512
	s_add_u32 s6, s6, s54
	s_addc_u32 s7, s7, s55
	global_load_ushort v162, v134, s[6:7]
	global_load_ushort v178, v134, s[6:7] offset:512
	s_add_u32 s6, s6, s54
	s_addc_u32 s7, s7, s55
	global_load_ushort v163, v134, s[6:7]
	global_load_ushort v179, v134, s[6:7] offset:512
	s_add_u32 s6, s6, s54
	s_addc_u32 s7, s7, s55
	v_mul_f32_e32 v18, 0xbfb8aa3b, v70
	v_mul_f32_e32 v19, 0xbfb8aa3b, v71
	v_mul_f32_e32 v20, 0xbfb8aa3b, v72
	v_mul_f32_e32 v21, 0xbfb8aa3b, v73
	v_mul_f32_e32 v22, 0xbfb8aa3b, v74
	v_mul_f32_e32 v23, 0xbfb8aa3b, v75
	v_mul_f32_e32 v24, 0xbfb8aa3b, v76
	v_mul_f32_e32 v25, 0xbfb8aa3b, v77
	v_mul_f32_e32 v26, 0xbfb8aa3b, v78
	v_mul_f32_e32 v27, 0xbfb8aa3b, v79
	v_mul_f32_e32 v28, 0xbfb8aa3b, v80
	v_mul_f32_e32 v29, 0xbfb8aa3b, v81
	v_mul_f32_e32 v30, 0xbfb8aa3b, v82
	v_mul_f32_e32 v31, 0xbfb8aa3b, v83
	v_mul_f32_e32 v32, 0xbfb8aa3b, v84
	v_mul_f32_e32 v33, 0xbfb8aa3b, v85
	v_exp_f32_e64 v236, -v18
	v_exp_f32_e64 v237, -v19
	v_exp_f32_e64 v238, -v20
	v_exp_f32_e64 v239, -v21
	v_exp_f32_e64 v240, -v22
	v_exp_f32_e64 v241, -v23
	v_exp_f32_e64 v242, -v24
	v_exp_f32_e64 v243, -v25
	v_exp_f32_e64 v244, -v26
	v_exp_f32_e64 v245, -v27
	v_exp_f32_e64 v246, -v28
	v_exp_f32_e64 v247, -v29
	v_exp_f32_e64 v248, -v30
	v_exp_f32_e64 v249, -v31
	v_exp_f32_e64 v250, -v32
	v_exp_f32_e64 v251, -v33
	v_exp_f32_e32 v18, v18
	v_exp_f32_e32 v19, v19
	v_exp_f32_e32 v20, v20
	v_exp_f32_e32 v21, v21
	v_exp_f32_e32 v22, v22
	v_exp_f32_e32 v23, v23
	v_exp_f32_e32 v24, v24
	v_exp_f32_e32 v25, v25
	v_exp_f32_e32 v26, v26
	v_exp_f32_e32 v27, v27
	v_exp_f32_e32 v28, v28
	v_exp_f32_e32 v29, v29
	v_exp_f32_e32 v30, v30
	v_exp_f32_e32 v31, v31
	v_exp_f32_e32 v32, v32
	v_exp_f32_e32 v33, v33
	v_lshlrev_b32_e32 v196, 16, v196
	v_lshlrev_b32_e32 v197, 16, v197
	v_lshlrev_b32_e32 v198, 16, v198
	v_lshlrev_b32_e32 v199, 16, v199
	v_lshlrev_b32_e32 v200, 16, v200
	v_lshlrev_b32_e32 v201, 16, v201
	v_lshlrev_b32_e32 v202, 16, v202
	v_lshlrev_b32_e32 v203, 16, v203
	v_lshlrev_b32_e32 v204, 16, v204
	v_lshlrev_b32_e32 v205, 16, v205
	v_lshlrev_b32_e32 v206, 16, v206
	v_lshlrev_b32_e32 v207, 16, v207
	v_lshlrev_b32_e32 v208, 16, v208
	v_lshlrev_b32_e32 v209, 16, v209
	v_lshlrev_b32_e32 v210, 16, v210
	v_lshlrev_b32_e32 v211, 16, v211
	v_lshlrev_b32_e32 v180, 16, v180
	v_lshlrev_b32_e32 v181, 16, v181
	v_lshlrev_b32_e32 v182, 16, v182
	v_lshlrev_b32_e32 v183, 16, v183
	v_lshlrev_b32_e32 v184, 16, v184
	v_lshlrev_b32_e32 v185, 16, v185
	v_lshlrev_b32_e32 v186, 16, v186
	v_lshlrev_b32_e32 v187, 16, v187
	v_lshlrev_b32_e32 v188, 16, v188
	v_lshlrev_b32_e32 v189, 16, v189
	v_lshlrev_b32_e32 v190, 16, v190
	v_lshlrev_b32_e32 v191, 16, v191
	v_lshlrev_b32_e32 v192, 16, v192
	v_lshlrev_b32_e32 v193, 16, v193
	v_lshlrev_b32_e32 v194, 16, v194
	v_lshlrev_b32_e32 v195, 16, v195
	v_mul_f32_e32 v196, v18, v196
	v_mul_f32_e32 v197, v19, v197
	v_mul_f32_e32 v198, v20, v198
	v_mul_f32_e32 v199, v21, v199
	v_mul_f32_e32 v200, v22, v200
	v_mul_f32_e32 v201, v23, v201
	v_mul_f32_e32 v202, v24, v202
	v_mul_f32_e32 v203, v25, v203
	v_mul_f32_e32 v204, v26, v204
	v_mul_f32_e32 v205, v27, v205
	v_mul_f32_e32 v206, v28, v206
	v_mul_f32_e32 v207, v29, v207
	v_mul_f32_e32 v208, v30, v208
	v_mul_f32_e32 v209, v31, v209
	v_mul_f32_e32 v210, v32, v210
	v_mul_f32_e32 v211, v33, v211
	v_mul_f32_e32 v180, 0x3e000000, v180
	v_mul_f32_e32 v181, 0x3e000000, v181
	v_mul_f32_e32 v182, 0x3e000000, v182
	v_mul_f32_e32 v183, 0x3e000000, v183
	v_mul_f32_e32 v184, 0x3e000000, v184
	v_mul_f32_e32 v185, 0x3e000000, v185
	v_mul_f32_e32 v186, 0x3e000000, v186
	v_mul_f32_e32 v187, 0x3e000000, v187
	v_mul_f32_e32 v188, 0x3e000000, v188
	v_mul_f32_e32 v189, 0x3e000000, v189
	v_mul_f32_e32 v190, 0x3e000000, v190
	v_mul_f32_e32 v191, 0x3e000000, v191
	v_mul_f32_e32 v192, 0x3e000000, v192
	v_mul_f32_e32 v193, 0x3e000000, v193
	v_mul_f32_e32 v194, 0x3e000000, v194
	v_mul_f32_e32 v195, 0x3e000000, v195
	v_mul_f32_e32 v180, v180, v236
	v_mul_f32_e32 v181, v181, v237
	v_mul_f32_e32 v182, v182, v238
	v_mul_f32_e32 v183, v183, v239
	v_mul_f32_e32 v184, v184, v240
	v_mul_f32_e32 v185, v185, v241
	v_mul_f32_e32 v186, v186, v242
	v_mul_f32_e32 v187, v187, v243
	v_mul_f32_e32 v188, v188, v244
	v_mul_f32_e32 v189, v189, v245
	v_mul_f32_e32 v190, v190, v246
	v_mul_f32_e32 v191, v191, v247
	v_mul_f32_e32 v192, v192, v248
	v_mul_f32_e32 v193, v193, v249
	v_mul_f32_e32 v194, v194, v250
	v_mul_f32_e32 v195, v195, v251
	v_cvt_pk_bf16_f32 v196, v196, v196
	v_cvt_pk_bf16_f32 v197, v197, v197
	v_cvt_pk_bf16_f32 v198, v198, v198
	v_cvt_pk_bf16_f32 v199, v199, v199
	v_cvt_pk_bf16_f32 v200, v200, v200
	v_cvt_pk_bf16_f32 v201, v201, v201
	v_cvt_pk_bf16_f32 v202, v202, v202
	v_cvt_pk_bf16_f32 v203, v203, v203
	v_cvt_pk_bf16_f32 v204, v204, v204
	v_cvt_pk_bf16_f32 v205, v205, v205
	v_cvt_pk_bf16_f32 v206, v206, v206
	v_cvt_pk_bf16_f32 v207, v207, v207
	v_cvt_pk_bf16_f32 v208, v208, v208
	v_cvt_pk_bf16_f32 v209, v209, v209
	v_cvt_pk_bf16_f32 v210, v210, v210
	v_cvt_pk_bf16_f32 v211, v211, v211
	v_cvt_pk_bf16_f32 v180, v180, v180
	v_cvt_pk_bf16_f32 v181, v181, v181
	v_cvt_pk_bf16_f32 v182, v182, v182
	v_cvt_pk_bf16_f32 v183, v183, v183
	v_cvt_pk_bf16_f32 v184, v184, v184
	v_cvt_pk_bf16_f32 v185, v185, v185
	v_cvt_pk_bf16_f32 v186, v186, v186
	v_cvt_pk_bf16_f32 v187, v187, v187
	v_cvt_pk_bf16_f32 v188, v188, v188
	v_cvt_pk_bf16_f32 v189, v189, v189
; __device__ __forceinline__ unsigned f2bf(float f) { unsigned r; asm("v_cvt_pk_bf16_f32 %0, %1, %1" : "=v"(r) : "v"(f)); return r & 0xffffu; }
; __device__ __forceinline__ void gl1_item(PREF p, int l, int item, bool valid, LAS unsigned char* pl, int sw, int lane) {
;     ...
;             for (int ss = 0; ss < 16; ++ss) { const int s = g4 * 16 + ss; const int i = d ? 63 - s : s;
;                 float z = bup;
; #pragma unroll
;                 for (int r2 = 0; r2 < 8; ++r2) { const unsigned w = (unsigned)__builtin_amdgcn_readlane((int)lrp[r2], i);
;                     z = __builtin_amdgcn_fdot2_f32_bf16(__builtin_bit_cast(bf16x2_t, w), __builtin_bit_cast(bf16x2_t, wupp[r2]), z, false); }
;     ...
;             for (int ss = 0; ss < 16; ++ss) { const int s = g4 * 16 + ss; const int i = d ? 63 - s : s; const size_t rowi = (size_t)(row0 + i * rstride);
;                 bc += gv[ss];
;                 const float en = __expf(-bc), ep = __expf(bc);
;                 const float kt = kc[ss] * en, qt = qc[ss] * 0.125f * ep;
;                 const unsigned ktb = f2bf(kt);
;                 sKt[lane * 72 + i] = (bf16_t)ktb;
;                 QK[rowi * 1024 + d * 512 + h * 64 + lane] = (bf16_t)f2bf(qt);
;                 QK[rowi * 1024 + d * 512 + 256 + h * 64 + lane] = (bf16_t)ktb;
;             }
	v_cvt_pk_bf16_f32 v190, v190, v190
	v_cvt_pk_bf16_f32 v191, v191, v191
	v_cvt_pk_bf16_f32 v192, v192, v192
	v_cvt_pk_bf16_f32 v193, v193, v193
	v_cvt_pk_bf16_f32 v194, v194, v194
	v_cvt_pk_bf16_f32 v195, v195, v195
	ds_write_b16 v60, v196
	v_add_u32_e32 v60, v61, v60
	global_store_short v134, v180, s[4:5]
	global_store_short v134, v196, s[4:5] offset:512
	s_add_u32 s4, s4, s56
	s_addc_u32 s5, s5, s3
	ds_write_b16 v60, v197
	v_add_u32_e32 v60, v61, v60
	global_store_short v134, v181, s[4:5]
	global_store_short v134, v197, s[4:5] offset:512
	s_add_u32 s4, s4, s56
	s_addc_u32 s5, s5, s3
	ds_write_b16 v60, v198
	v_add_u32_e32 v60, v61, v60
	global_store_short v134, v182, s[4:5]
	global_store_short v134, v198, s[4:5] offset:512
	s_add_u32 s4, s4, s56
	s_addc_u32 s5, s5, s3
	ds_write_b16 v60, v199
	v_add_u32_e32 v60, v61, v60
	global_store_short v134, v183, s[4:5]
	global_store_short v134, v199, s[4:5] offset:512
	s_add_u32 s4, s4, s56
	s_addc_u32 s5, s5, s3
	ds_write_b16 v60, v200
	v_add_u32_e32 v60, v61, v60
	global_store_short v134, v184, s[4:5]
	global_store_short v134, v200, s[4:5] offset:512
	s_add_u32 s4, s4, s56
	s_addc_u32 s5, s5, s3
	ds_write_b16 v60, v201
	v_add_u32_e32 v60, v61, v60
	global_store_short v134, v185, s[4:5]
	global_store_short v134, v201, s[4:5] offset:512
	s_add_u32 s4, s4, s56
	s_addc_u32 s5, s5, s3
	ds_write_b16 v60, v202
	v_add_u32_e32 v60, v61, v60
	global_store_short v134, v186, s[4:5]
	global_store_short v134, v202, s[4:5] offset:512
	s_add_u32 s4, s4, s56
	s_addc_u32 s5, s5, s3
	ds_write_b16 v60, v203
	v_add_u32_e32 v60, v61, v60
	global_store_short v134, v187, s[4:5]
	global_store_short v134, v203, s[4:5] offset:512
	s_add_u32 s4, s4, s56
	s_addc_u32 s5, s5, s3
	ds_write_b16 v60, v204
	v_add_u32_e32 v60, v61, v60
	global_store_short v134, v188, s[4:5]
	global_store_short v134, v204, s[4:5] offset:512
	s_add_u32 s4, s4, s56
	s_addc_u32 s5, s5, s3
	ds_write_b16 v60, v205
	v_add_u32_e32 v60, v61, v60
	global_store_short v134, v189, s[4:5]
	global_store_short v134, v205, s[4:5] offset:512
	s_add_u32 s4, s4, s56
	s_addc_u32 s5, s5, s3
	ds_write_b16 v60, v206
	v_add_u32_e32 v60, v61, v60
	global_store_short v134, v190, s[4:5]
	global_store_short v134, v206, s[4:5] offset:512
	s_add_u32 s4, s4, s56
	s_addc_u32 s5, s5, s3
	ds_write_b16 v60, v207
	v_add_u32_e32 v60, v61, v60
	global_store_short v134, v191, s[4:5]
	global_store_short v134, v207, s[4:5] offset:512
	s_add_u32 s4, s4, s56
	s_addc_u32 s5, s5, s3
	ds_write_b16 v60, v208
	v_add_u32_e32 v60, v61, v60
	global_store_short v134, v192, s[4:5]
	global_store_short v134, v208, s[4:5] offset:512
	s_add_u32 s4, s4, s56
	s_addc_u32 s5, s5, s3
	ds_write_b16 v60, v209
	v_add_u32_e32 v60, v61, v60
	global_store_short v134, v193, s[4:5]
	global_store_short v134, v209, s[4:5] offset:512
	s_add_u32 s4, s4, s56
	s_addc_u32 s5, s5, s3
	ds_write_b16 v60, v210
	v_add_u32_e32 v60, v61, v60
	global_store_short v134, v194, s[4:5]
	global_store_short v134, v210, s[4:5] offset:512
	s_add_u32 s4, s4, s56
	s_addc_u32 s5, s5, s3
	ds_write_b16 v60, v211
	v_add_u32_e32 v60, v61, v60
	global_store_short v134, v195, s[4:5]
	global_store_short v134, v211, s[4:5] offset:512
	s_add_u32 s4, s4, s56
	s_addc_u32 s5, s5, s3
	v_mov_b32_e32 v236, v16
	v_dot2c_f32_bf16_dpp v236, v114, v8 row_newbcast:0 row_mask:0xf bank_mask:0xf
	v_dot2c_f32_bf16_dpp v236, v115, v9 row_newbcast:0 row_mask:0xf bank_mask:0xf
	v_dot2c_f32_bf16_dpp v236, v116, v10 row_newbcast:0 row_mask:0xf bank_mask:0xf
	v_dot2c_f32_bf16_dpp v236, v117, v11 row_newbcast:0 row_mask:0xf bank_mask:0xf
	v_dot2c_f32_bf16_dpp v236, v118, v12 row_newbcast:0 row_mask:0xf bank_mask:0xf
	v_dot2c_f32_bf16_dpp v236, v119, v13 row_newbcast:0 row_mask:0xf bank_mask:0xf
	v_dot2c_f32_bf16_dpp v236, v120, v14 row_newbcast:0 row_mask:0xf bank_mask:0xf
	v_dot2c_f32_bf16_dpp v236, v121, v15 row_newbcast:0 row_mask:0xf bank_mask:0xf
	v_mov_b32_e32 v237, v16
	v_dot2c_f32_bf16_dpp v237, v114, v8 row_newbcast:1 row_mask:0xf bank_mask:0xf
	v_dot2c_f32_bf16_dpp v237, v115, v9 row_newbcast:1 row_mask:0xf bank_mask:0xf
	v_dot2c_f32_bf16_dpp v237, v116, v10 row_newbcast:1 row_mask:0xf bank_mask:0xf
	v_dot2c_f32_bf16_dpp v237, v117, v11 row_newbcast:1 row_mask:0xf bank_mask:0xf
	v_dot2c_f32_bf16_dpp v237, v118, v12 row_newbcast:1 row_mask:0xf bank_mask:0xf
	v_dot2c_f32_bf16_dpp v237, v119, v13 row_newbcast:1 row_mask:0xf bank_mask:0xf
	v_dot2c_f32_bf16_dpp v237, v120, v14 row_newbcast:1 row_mask:0xf bank_mask:0xf
	v_dot2c_f32_bf16_dpp v237, v121, v15 row_newbcast:1 row_mask:0xf bank_mask:0xf
	v_mov_b32_e32 v238, v16
	v_dot2c_f32_bf16_dpp v238, v114, v8 row_newbcast:2 row_mask:0xf bank_mask:0xf
	v_dot2c_f32_bf16_dpp v238, v115, v9 row_newbcast:2 row_mask:0xf bank_mask:0xf
	v_dot2c_f32_bf16_dpp v238, v116, v10 row_newbcast:2 row_mask:0xf bank_mask:0xf
	v_dot2c_f32_bf16_dpp v238, v117, v11 row_newbcast:2 row_mask:0xf bank_mask:0xf
	v_dot2c_f32_bf16_dpp v238, v118, v12 row_newbcast:2 row_mask:0xf bank_mask:0xf
	v_dot2c_f32_bf16_dpp v238, v119, v13 row_newbcast:2 row_mask:0xf bank_mask:0xf
	v_dot2c_f32_bf16_dpp v238, v120, v14 row_newbcast:2 row_mask:0xf bank_mask:0xf
	v_dot2c_f32_bf16_dpp v238, v121, v15 row_newbcast:2 row_mask:0xf bank_mask:0xf
	v_mov_b32_e32 v239, v16
	v_dot2c_f32_bf16_dpp v239, v114, v8 row_newbcast:3 row_mask:0xf bank_mask:0xf
	v_dot2c_f32_bf16_dpp v239, v115, v9 row_newbcast:3 row_mask:0xf bank_mask:0xf
	v_dot2c_f32_bf16_dpp v239, v116, v10 row_newbcast:3 row_mask:0xf bank_mask:0xf
	v_dot2c_f32_bf16_dpp v239, v117, v11 row_newbcast:3 row_mask:0xf bank_mask:0xf
	v_dot2c_f32_bf16_dpp v239, v118, v12 row_newbcast:3 row_mask:0xf bank_mask:0xf
; __device__ __forceinline__ void gl1_item(PREF p, int l, int item, bool valid, LAS unsigned char* pl, int sw, int lane) {
;     ...
;             for (int ss = 0; ss < 16; ++ss) { const int s = g4 * 16 + ss; const int i = d ? 63 - s : s;
;                 float z = bup;
; #pragma unroll
;                 for (int r2 = 0; r2 < 8; ++r2) { const unsigned w = (unsigned)__builtin_amdgcn_readlane((int)lrp[r2], i);
;                     z = __builtin_amdgcn_fdot2_f32_bf16(__builtin_bit_cast(bf16x2_t, w), __builtin_bit_cast(bf16x2_t, wupp[r2]), z, false); }
;                 gv[ss] = -(fmaxf(-z, 0.f) + __logf(1.f + __expf(-fabsf(z)))) * (1.f / 16.f);
	v_dot2c_f32_bf16_dpp v239, v119, v13 row_newbcast:3 row_mask:0xf bank_mask:0xf
	v_dot2c_f32_bf16_dpp v239, v120, v14 row_newbcast:3 row_mask:0xf bank_mask:0xf
	v_dot2c_f32_bf16_dpp v239, v121, v15 row_newbcast:3 row_mask:0xf bank_mask:0xf
	v_mov_b32_e32 v240, v16
	v_dot2c_f32_bf16_dpp v240, v114, v8 row_newbcast:4 row_mask:0xf bank_mask:0xf
	v_dot2c_f32_bf16_dpp v240, v115, v9 row_newbcast:4 row_mask:0xf bank_mask:0xf
	v_dot2c_f32_bf16_dpp v240, v116, v10 row_newbcast:4 row_mask:0xf bank_mask:0xf
	v_dot2c_f32_bf16_dpp v240, v117, v11 row_newbcast:4 row_mask:0xf bank_mask:0xf
	v_dot2c_f32_bf16_dpp v240, v118, v12 row_newbcast:4 row_mask:0xf bank_mask:0xf
	v_dot2c_f32_bf16_dpp v240, v119, v13 row_newbcast:4 row_mask:0xf bank_mask:0xf
	v_dot2c_f32_bf16_dpp v240, v120, v14 row_newbcast:4 row_mask:0xf bank_mask:0xf
	v_dot2c_f32_bf16_dpp v240, v121, v15 row_newbcast:4 row_mask:0xf bank_mask:0xf
	v_mov_b32_e32 v241, v16
	v_dot2c_f32_bf16_dpp v241, v114, v8 row_newbcast:5 row_mask:0xf bank_mask:0xf
	v_dot2c_f32_bf16_dpp v241, v115, v9 row_newbcast:5 row_mask:0xf bank_mask:0xf
	v_dot2c_f32_bf16_dpp v241, v116, v10 row_newbcast:5 row_mask:0xf bank_mask:0xf
	v_dot2c_f32_bf16_dpp v241, v117, v11 row_newbcast:5 row_mask:0xf bank_mask:0xf
	v_dot2c_f32_bf16_dpp v241, v118, v12 row_newbcast:5 row_mask:0xf bank_mask:0xf
	v_dot2c_f32_bf16_dpp v241, v119, v13 row_newbcast:5 row_mask:0xf bank_mask:0xf
	v_dot2c_f32_bf16_dpp v241, v120, v14 row_newbcast:5 row_mask:0xf bank_mask:0xf
	v_dot2c_f32_bf16_dpp v241, v121, v15 row_newbcast:5 row_mask:0xf bank_mask:0xf
	v_mov_b32_e32 v242, v16
	v_dot2c_f32_bf16_dpp v242, v114, v8 row_newbcast:6 row_mask:0xf bank_mask:0xf
	v_dot2c_f32_bf16_dpp v242, v115, v9 row_newbcast:6 row_mask:0xf bank_mask:0xf
	v_dot2c_f32_bf16_dpp v242, v116, v10 row_newbcast:6 row_mask:0xf bank_mask:0xf
	v_dot2c_f32_bf16_dpp v242, v117, v11 row_newbcast:6 row_mask:0xf bank_mask:0xf
	v_dot2c_f32_bf16_dpp v242, v118, v12 row_newbcast:6 row_mask:0xf bank_mask:0xf
	v_dot2c_f32_bf16_dpp v242, v119, v13 row_newbcast:6 row_mask:0xf bank_mask:0xf
	v_dot2c_f32_bf16_dpp v242, v120, v14 row_newbcast:6 row_mask:0xf bank_mask:0xf
	v_dot2c_f32_bf16_dpp v242, v121, v15 row_newbcast:6 row_mask:0xf bank_mask:0xf
	v_mov_b32_e32 v243, v16
	v_dot2c_f32_bf16_dpp v243, v114, v8 row_newbcast:7 row_mask:0xf bank_mask:0xf
	v_dot2c_f32_bf16_dpp v243, v115, v9 row_newbcast:7 row_mask:0xf bank_mask:0xf
	v_dot2c_f32_bf16_dpp v243, v116, v10 row_newbcast:7 row_mask:0xf bank_mask:0xf
	v_dot2c_f32_bf16_dpp v243, v117, v11 row_newbcast:7 row_mask:0xf bank_mask:0xf
	v_dot2c_f32_bf16_dpp v243, v118, v12 row_newbcast:7 row_mask:0xf bank_mask:0xf
	v_dot2c_f32_bf16_dpp v243, v119, v13 row_newbcast:7 row_mask:0xf bank_mask:0xf
	v_dot2c_f32_bf16_dpp v243, v120, v14 row_newbcast:7 row_mask:0xf bank_mask:0xf
	v_dot2c_f32_bf16_dpp v243, v121, v15 row_newbcast:7 row_mask:0xf bank_mask:0xf
	v_mov_b32_e32 v244, v16
	v_dot2c_f32_bf16_dpp v244, v114, v8 row_newbcast:8 row_mask:0xf bank_mask:0xf
	v_dot2c_f32_bf16_dpp v244, v115, v9 row_newbcast:8 row_mask:0xf bank_mask:0xf
	v_dot2c_f32_bf16_dpp v244, v116, v10 row_newbcast:8 row_mask:0xf bank_mask:0xf
	v_dot2c_f32_bf16_dpp v244, v117, v11 row_newbcast:8 row_mask:0xf bank_mask:0xf
	v_dot2c_f32_bf16_dpp v244, v118, v12 row_newbcast:8 row_mask:0xf bank_mask:0xf
	v_dot2c_f32_bf16_dpp v244, v119, v13 row_newbcast:8 row_mask:0xf bank_mask:0xf
	v_dot2c_f32_bf16_dpp v244, v120, v14 row_newbcast:8 row_mask:0xf bank_mask:0xf
	v_dot2c_f32_bf16_dpp v244, v121, v15 row_newbcast:8 row_mask:0xf bank_mask:0xf
	v_mov_b32_e32 v245, v16
	v_dot2c_f32_bf16_dpp v245, v114, v8 row_newbcast:9 row_mask:0xf bank_mask:0xf
	v_dot2c_f32_bf16_dpp v245, v115, v9 row_newbcast:9 row_mask:0xf bank_mask:0xf
	v_dot2c_f32_bf16_dpp v245, v116, v10 row_newbcast:9 row_mask:0xf bank_mask:0xf
	v_dot2c_f32_bf16_dpp v245, v117, v11 row_newbcast:9 row_mask:0xf bank_mask:0xf
	v_dot2c_f32_bf16_dpp v245, v118, v12 row_newbcast:9 row_mask:0xf bank_mask:0xf
	v_dot2c_f32_bf16_dpp v245, v119, v13 row_newbcast:9 row_mask:0xf bank_mask:0xf
	v_dot2c_f32_bf16_dpp v245, v120, v14 row_newbcast:9 row_mask:0xf bank_mask:0xf
	v_dot2c_f32_bf16_dpp v245, v121, v15 row_newbcast:9 row_mask:0xf bank_mask:0xf
	v_mov_b32_e32 v246, v16
	v_dot2c_f32_bf16_dpp v246, v114, v8 row_newbcast:10 row_mask:0xf bank_mask:0xf
	v_dot2c_f32_bf16_dpp v246, v115, v9 row_newbcast:10 row_mask:0xf bank_mask:0xf
	v_dot2c_f32_bf16_dpp v246, v116, v10 row_newbcast:10 row_mask:0xf bank_mask:0xf
	v_dot2c_f32_bf16_dpp v246, v117, v11 row_newbcast:10 row_mask:0xf bank_mask:0xf
	v_dot2c_f32_bf16_dpp v246, v118, v12 row_newbcast:10 row_mask:0xf bank_mask:0xf
	v_dot2c_f32_bf16_dpp v246, v119, v13 row_newbcast:10 row_mask:0xf bank_mask:0xf
	v_dot2c_f32_bf16_dpp v246, v120, v14 row_newbcast:10 row_mask:0xf bank_mask:0xf
	v_dot2c_f32_bf16_dpp v246, v121, v15 row_newbcast:10 row_mask:0xf bank_mask:0xf
	v_mov_b32_e32 v247, v16
	v_dot2c_f32_bf16_dpp v247, v114, v8 row_newbcast:11 row_mask:0xf bank_mask:0xf
	v_dot2c_f32_bf16_dpp v247, v115, v9 row_newbcast:11 row_mask:0xf bank_mask:0xf
	v_dot2c_f32_bf16_dpp v247, v116, v10 row_newbcast:11 row_mask:0xf bank_mask:0xf
	v_dot2c_f32_bf16_dpp v247, v117, v11 row_newbcast:11 row_mask:0xf bank_mask:0xf
	v_dot2c_f32_bf16_dpp v247, v118, v12 row_newbcast:11 row_mask:0xf bank_mask:0xf
	v_dot2c_f32_bf16_dpp v247, v119, v13 row_newbcast:11 row_mask:0xf bank_mask:0xf
	v_dot2c_f32_bf16_dpp v247, v120, v14 row_newbcast:11 row_mask:0xf bank_mask:0xf
	v_dot2c_f32_bf16_dpp v247, v121, v15 row_newbcast:11 row_mask:0xf bank_mask:0xf
	v_mov_b32_e32 v248, v16
	v_dot2c_f32_bf16_dpp v248, v114, v8 row_newbcast:12 row_mask:0xf bank_mask:0xf
; __device__ __forceinline__ void gl1_item(PREF p, int l, int item, bool valid, LAS unsigned char* pl, int sw, int lane) {
;     ...
;             for (int ss = 0; ss < 16; ++ss) { const int s = g4 * 16 + ss; const int i = d ? 63 - s : s;
;                 float z = bup;
; #pragma unroll
;                 for (int r2 = 0; r2 < 8; ++r2) { const unsigned w = (unsigned)__builtin_amdgcn_readlane((int)lrp[r2], i);
;                     z = __builtin_amdgcn_fdot2_f32_bf16(__builtin_bit_cast(bf16x2_t, w), __builtin_bit_cast(bf16x2_t, wupp[r2]), z, false); }
;                 gv[ss] = -(fmaxf(-z, 0.f) + __logf(1.f + __expf(-fabsf(z)))) * (1.f / 16.f);
	v_dot2c_f32_bf16_dpp v248, v115, v9 row_newbcast:12 row_mask:0xf bank_mask:0xf
	v_dot2c_f32_bf16_dpp v248, v116, v10 row_newbcast:12 row_mask:0xf bank_mask:0xf
	v_dot2c_f32_bf16_dpp v248, v117, v11 row_newbcast:12 row_mask:0xf bank_mask:0xf
	v_dot2c_f32_bf16_dpp v248, v118, v12 row_newbcast:12 row_mask:0xf bank_mask:0xf
	v_dot2c_f32_bf16_dpp v248, v119, v13 row_newbcast:12 row_mask:0xf bank_mask:0xf
	v_dot2c_f32_bf16_dpp v248, v120, v14 row_newbcast:12 row_mask:0xf bank_mask:0xf
	v_dot2c_f32_bf16_dpp v248, v121, v15 row_newbcast:12 row_mask:0xf bank_mask:0xf
	v_mov_b32_e32 v249, v16
	v_dot2c_f32_bf16_dpp v249, v114, v8 row_newbcast:13 row_mask:0xf bank_mask:0xf
	v_dot2c_f32_bf16_dpp v249, v115, v9 row_newbcast:13 row_mask:0xf bank_mask:0xf
	v_dot2c_f32_bf16_dpp v249, v116, v10 row_newbcast:13 row_mask:0xf bank_mask:0xf
	v_dot2c_f32_bf16_dpp v249, v117, v11 row_newbcast:13 row_mask:0xf bank_mask:0xf
	v_dot2c_f32_bf16_dpp v249, v118, v12 row_newbcast:13 row_mask:0xf bank_mask:0xf
	v_dot2c_f32_bf16_dpp v249, v119, v13 row_newbcast:13 row_mask:0xf bank_mask:0xf
	v_dot2c_f32_bf16_dpp v249, v120, v14 row_newbcast:13 row_mask:0xf bank_mask:0xf
	v_dot2c_f32_bf16_dpp v249, v121, v15 row_newbcast:13 row_mask:0xf bank_mask:0xf
	v_mov_b32_e32 v250, v16
	v_dot2c_f32_bf16_dpp v250, v114, v8 row_newbcast:14 row_mask:0xf bank_mask:0xf
	v_dot2c_f32_bf16_dpp v250, v115, v9 row_newbcast:14 row_mask:0xf bank_mask:0xf
	v_dot2c_f32_bf16_dpp v250, v116, v10 row_newbcast:14 row_mask:0xf bank_mask:0xf
	v_dot2c_f32_bf16_dpp v250, v117, v11 row_newbcast:14 row_mask:0xf bank_mask:0xf
	v_dot2c_f32_bf16_dpp v250, v118, v12 row_newbcast:14 row_mask:0xf bank_mask:0xf
	v_dot2c_f32_bf16_dpp v250, v119, v13 row_newbcast:14 row_mask:0xf bank_mask:0xf
	v_dot2c_f32_bf16_dpp v250, v120, v14 row_newbcast:14 row_mask:0xf bank_mask:0xf
	v_dot2c_f32_bf16_dpp v250, v121, v15 row_newbcast:14 row_mask:0xf bank_mask:0xf
	v_mov_b32_e32 v251, v16
	v_dot2c_f32_bf16_dpp v251, v114, v8 row_newbcast:15 row_mask:0xf bank_mask:0xf
	v_dot2c_f32_bf16_dpp v251, v115, v9 row_newbcast:15 row_mask:0xf bank_mask:0xf
	v_dot2c_f32_bf16_dpp v251, v116, v10 row_newbcast:15 row_mask:0xf bank_mask:0xf
	v_dot2c_f32_bf16_dpp v251, v117, v11 row_newbcast:15 row_mask:0xf bank_mask:0xf
	v_dot2c_f32_bf16_dpp v251, v118, v12 row_newbcast:15 row_mask:0xf bank_mask:0xf
	v_dot2c_f32_bf16_dpp v251, v119, v13 row_newbcast:15 row_mask:0xf bank_mask:0xf
	v_dot2c_f32_bf16_dpp v251, v120, v14 row_newbcast:15 row_mask:0xf bank_mask:0xf
	v_dot2c_f32_bf16_dpp v251, v121, v15 row_newbcast:15 row_mask:0xf bank_mask:0xf
	s_nop 2
	v_mul_f32_e64 v18, |v236|, s1
	v_mul_f32_e64 v19, |v237|, s1
	v_mul_f32_e64 v20, |v238|, s1
	v_mul_f32_e64 v21, |v239|, s1
	v_mul_f32_e64 v22, |v240|, s1
	v_mul_f32_e64 v23, |v241|, s1
	v_mul_f32_e64 v24, |v242|, s1
	v_mul_f32_e64 v25, |v243|, s1
	v_mul_f32_e64 v26, |v244|, s1
	v_mul_f32_e64 v27, |v245|, s1
	v_mul_f32_e64 v28, |v246|, s1
	v_mul_f32_e64 v29, |v247|, s1
	v_mul_f32_e64 v30, |v248|, s1
	v_mul_f32_e64 v31, |v249|, s1
	v_mul_f32_e64 v32, |v250|, s1
	v_mul_f32_e64 v33, |v251|, s1
	v_exp_f32_e32 v18, v18
	v_exp_f32_e32 v19, v19
	v_exp_f32_e32 v20, v20
	v_exp_f32_e32 v21, v21
	v_exp_f32_e32 v22, v22
	v_exp_f32_e32 v23, v23
	v_exp_f32_e32 v24, v24
	v_exp_f32_e32 v25, v25
	v_exp_f32_e32 v26, v26
	v_exp_f32_e32 v27, v27
	v_exp_f32_e32 v28, v28
	v_exp_f32_e32 v29, v29
	v_exp_f32_e32 v30, v30
	v_exp_f32_e32 v31, v31
	v_exp_f32_e32 v32, v32
	v_exp_f32_e32 v33, v33
	v_max_f32_e64 v236, -v236, 0
	v_max_f32_e64 v237, -v237, 0
	v_max_f32_e64 v238, -v238, 0
	v_max_f32_e64 v239, -v239, 0
	v_max_f32_e64 v240, -v240, 0
	v_max_f32_e64 v241, -v241, 0
	v_max_f32_e64 v242, -v242, 0
	v_max_f32_e64 v243, -v243, 0
	v_max_f32_e64 v244, -v244, 0
	v_max_f32_e64 v245, -v245, 0
	v_max_f32_e64 v246, -v246, 0
	v_max_f32_e64 v247, -v247, 0
	v_max_f32_e64 v248, -v248, 0
	v_max_f32_e64 v249, -v249, 0
	v_max_f32_e64 v250, -v250, 0
	v_max_f32_e64 v251, -v251, 0
	v_add_f32_e32 v18, 1.0, v18
	v_add_f32_e32 v19, 1.0, v19
	v_add_f32_e32 v20, 1.0, v20
	v_add_f32_e32 v21, 1.0, v21
	v_add_f32_e32 v22, 1.0, v22
	v_add_f32_e32 v23, 1.0, v23
	v_add_f32_e32 v24, 1.0, v24
	v_add_f32_e32 v25, 1.0, v25
	v_add_f32_e32 v26, 1.0, v26
	v_add_f32_e32 v27, 1.0, v27
	v_add_f32_e32 v28, 1.0, v28
	v_add_f32_e32 v29, 1.0, v29
	v_add_f32_e32 v30, 1.0, v30
	v_add_f32_e32 v31, 1.0, v31
	v_add_f32_e32 v32, 1.0, v32
	v_add_f32_e32 v33, 1.0, v33
	v_log_f32_e32 v18, v18
	v_log_f32_e32 v19, v19
	v_log_f32_e32 v20, v20
	v_log_f32_e32 v21, v21
	v_log_f32_e32 v22, v22
	v_log_f32_e32 v23, v23
	v_log_f32_e32 v24, v24
	v_log_f32_e32 v25, v25
	v_log_f32_e32 v26, v26
	v_log_f32_e32 v27, v27
	v_log_f32_e32 v28, v28
	v_log_f32_e32 v29, v29
	v_log_f32_e32 v30, v30
	v_log_f32_e32 v31, v31
	v_log_f32_e32 v32, v32
	v_log_f32_e32 v33, v33
	s_mov_b32 s45, 0x3f317217
	v_mul_f32_e32 v70, 0x3f317217, v18
	v_mul_f32_e32 v71, 0x3f317217, v19
	v_mul_f32_e32 v72, 0x3f317217, v20
	v_mul_f32_e32 v73, 0x3f317217, v21
	v_mul_f32_e32 v74, 0x3f317217, v22
	v_mul_f32_e32 v75, 0x3f317217, v23
	v_mul_f32_e32 v76, 0x3f317217, v24
	v_mul_f32_e32 v77, 0x3f317217, v25
	v_mul_f32_e32 v78, 0x3f317217, v26
	v_mul_f32_e32 v79, 0x3f317217, v27
	v_mul_f32_e32 v80, 0x3f317217, v28
	v_mul_f32_e32 v81, 0x3f317217, v29
	v_mul_f32_e32 v82, 0x3f317217, v30
	v_mul_f32_e32 v83, 0x3f317217, v31
	v_mul_f32_e32 v84, 0x3f317217, v32
	v_mul_f32_e32 v85, 0x3f317217, v33
	v_fma_f32 v70, v18, s45, -v70
	v_fma_f32 v71, v19, s45, -v71
	v_fma_f32 v72, v20, s45, -v72
	v_fma_f32 v73, v21, s45, -v73
	v_fma_f32 v74, v22, s45, -v74
	v_fma_f32 v75, v23, s45, -v75
	v_fma_f32 v76, v24, s45, -v76
	v_fma_f32 v77, v25, s45, -v77
; __device__ __forceinline__ void gl1_item(PREF p, int l, int item, bool valid, LAS unsigned char* pl, int sw, int lane) {
;     ...
;             if (g4 < 3) {
; #pragma unroll
;                 for (int ss = 0; ss < 16; ++ss) { const int s = (g4 + 1) * 16 + ss; const int i = d ? 63 - s : s; const bf16_t* pr = P + (size_t)(row0 + i * rstride) * PW + h * 64 + lane;
;                     qn[ss] = __builtin_bit_cast(float, (unsigned)pr[1024]); kn[ss] = __builtin_bit_cast(float, (unsigned)pr[1280]); }
;                 __builtin_amdgcn_sched_barrier(0);
;             }
;             float gv[16];
; #pragma unroll
;             for (int ss = 0; ss < 16; ++ss) { const int s = g4 * 16 + ss; const int i = d ? 63 - s : s;
;                 float z = bup;
; #pragma unroll
;                 for (int r2 = 0; r2 < 8; ++r2) { const unsigned w = (unsigned)__builtin_amdgcn_readlane((int)lrp[r2], i);
;                     z = __builtin_amdgcn_fdot2_f32_bf16(__builtin_bit_cast(bf16x2_t, w), __builtin_bit_cast(bf16x2_t, wupp[r2]), z, false); }
;                 gv[ss] = -(fmaxf(-z, 0.f) + __logf(1.f + __expf(-fabsf(z)))) * (1.f / 16.f);
;                 __builtin_amdgcn_sched_barrier(0);
;             }
; #pragma unroll
;             for (int ss = 0; ss < 16; ++ss) { const int s = g4 * 16 + ss; const int i = d ? 63 - s : s; const size_t rowi = (size_t)(row0 + i * rstride);
;                 bc += gv[ss];
;                 const float en = __expf(-bc), ep = __expf(bc);
;                 const float kt = kc[ss] * en, qt = qc[ss] * 0.125f * ep;
	v_fma_f32 v78, v26, s45, -v78
	v_fma_f32 v79, v27, s45, -v79
	v_fma_f32 v80, v28, s45, -v80
	v_fma_f32 v81, v29, s45, -v81
	v_fma_f32 v82, v30, s45, -v82
	v_fma_f32 v83, v31, s45, -v83
	v_fma_f32 v84, v32, s45, -v84
	v_fma_f32 v85, v33, s45, -v85
	v_fmac_f32_e32 v70, 0x3377d1cf, v18
	v_fmac_f32_e32 v71, 0x3377d1cf, v19
	v_fmac_f32_e32 v72, 0x3377d1cf, v20
	v_fmac_f32_e32 v73, 0x3377d1cf, v21
	v_fmac_f32_e32 v74, 0x3377d1cf, v22
	v_fmac_f32_e32 v75, 0x3377d1cf, v23
	v_fmac_f32_e32 v76, 0x3377d1cf, v24
	v_fmac_f32_e32 v77, 0x3377d1cf, v25
	v_fmac_f32_e32 v78, 0x3377d1cf, v26
	v_fmac_f32_e32 v79, 0x3377d1cf, v27
	v_fmac_f32_e32 v80, 0x3377d1cf, v28
	v_fmac_f32_e32 v81, 0x3377d1cf, v29
	v_fmac_f32_e32 v82, 0x3377d1cf, v30
	v_fmac_f32_e32 v83, 0x3377d1cf, v31
	v_fmac_f32_e32 v84, 0x3377d1cf, v32
	v_fmac_f32_e32 v85, 0x3377d1cf, v33
	v_fmac_f32_e32 v70, 0x3f317217, v18
	v_fmac_f32_e32 v71, 0x3f317217, v19
	v_fmac_f32_e32 v72, 0x3f317217, v20
	v_fmac_f32_e32 v73, 0x3f317217, v21
	v_fmac_f32_e32 v74, 0x3f317217, v22
	v_fmac_f32_e32 v75, 0x3f317217, v23
	v_fmac_f32_e32 v76, 0x3f317217, v24
	v_fmac_f32_e32 v77, 0x3f317217, v25
	v_fmac_f32_e32 v78, 0x3f317217, v26
	v_fmac_f32_e32 v79, 0x3f317217, v27
	v_fmac_f32_e32 v80, 0x3f317217, v28
	v_fmac_f32_e32 v81, 0x3f317217, v29
	v_fmac_f32_e32 v82, 0x3f317217, v30
	v_fmac_f32_e32 v83, 0x3f317217, v31
	v_fmac_f32_e32 v84, 0x3f317217, v32
	v_fmac_f32_e32 v85, 0x3f317217, v33
	v_add_f32_e32 v236, v236, v70
	v_add_f32_e32 v237, v237, v71
	v_add_f32_e32 v238, v238, v72
	v_add_f32_e32 v239, v239, v73
	v_add_f32_e32 v240, v240, v74
	v_add_f32_e32 v241, v241, v75
	v_add_f32_e32 v242, v242, v76
	v_add_f32_e32 v243, v243, v77
	v_add_f32_e32 v244, v244, v78
	v_add_f32_e32 v245, v245, v79
	v_add_f32_e32 v246, v246, v80
	v_add_f32_e32 v247, v247, v81
	v_add_f32_e32 v248, v248, v82
	v_add_f32_e32 v249, v249, v83
	v_add_f32_e32 v250, v250, v84
	v_add_f32_e32 v251, v251, v85
	v_fma_f32 v70, v236, s49, v17
	v_fma_f32 v71, v237, s49, v70
	v_fma_f32 v72, v238, s49, v71
	v_fma_f32 v73, v239, s49, v72
	v_fma_f32 v74, v240, s49, v73
	v_fma_f32 v75, v241, s49, v74
	v_fma_f32 v76, v242, s49, v75
	v_fma_f32 v77, v243, s49, v76
	v_fma_f32 v78, v244, s49, v77
	v_fma_f32 v79, v245, s49, v78
	v_fma_f32 v80, v246, s49, v79
	v_fma_f32 v81, v247, s49, v80
	v_fma_f32 v82, v248, s49, v81
	v_fma_f32 v83, v249, s49, v82
	v_fma_f32 v84, v250, s49, v83
	v_fma_f32 v85, v251, s49, v84
	v_mov_b32_e32 v17, v85
	s_waitcnt vmcnt(32)
	global_load_ushort v180, v134, s[6:7]
	global_load_ushort v196, v134, s[6:7] offset:512
	s_add_u32 s6, s6, s54
	s_addc_u32 s7, s7, s55
	global_load_ushort v181, v134, s[6:7]
	global_load_ushort v197, v134, s[6:7] offset:512
	s_add_u32 s6, s6, s54
	s_addc_u32 s7, s7, s55
	global_load_ushort v182, v134, s[6:7]
	global_load_ushort v198, v134, s[6:7] offset:512
	s_add_u32 s6, s6, s54
	s_addc_u32 s7, s7, s55
	global_load_ushort v183, v134, s[6:7]
	global_load_ushort v199, v134, s[6:7] offset:512
	s_add_u32 s6, s6, s54
	s_addc_u32 s7, s7, s55
	global_load_ushort v184, v134, s[6:7]
	global_load_ushort v200, v134, s[6:7] offset:512
	s_add_u32 s6, s6, s54
	s_addc_u32 s7, s7, s55
	global_load_ushort v185, v134, s[6:7]
	global_load_ushort v201, v134, s[6:7] offset:512
	s_add_u32 s6, s6, s54
	s_addc_u32 s7, s7, s55
	global_load_ushort v186, v134, s[6:7]
	global_load_ushort v202, v134, s[6:7] offset:512
	s_add_u32 s6, s6, s54
	s_addc_u32 s7, s7, s55
	global_load_ushort v187, v134, s[6:7]
	global_load_ushort v203, v134, s[6:7] offset:512
	s_add_u32 s6, s6, s54
	s_addc_u32 s7, s7, s55
	global_load_ushort v188, v134, s[6:7]
	global_load_ushort v204, v134, s[6:7] offset:512
	s_add_u32 s6, s6, s54
	s_addc_u32 s7, s7, s55
	global_load_ushort v189, v134, s[6:7]
	global_load_ushort v205, v134, s[6:7] offset:512
	s_add_u32 s6, s6, s54
	s_addc_u32 s7, s7, s55
	global_load_ushort v190, v134, s[6:7]
	global_load_ushort v206, v134, s[6:7] offset:512
	s_add_u32 s6, s6, s54
	s_addc_u32 s7, s7, s55
	global_load_ushort v191, v134, s[6:7]
	global_load_ushort v207, v134, s[6:7] offset:512
	s_add_u32 s6, s6, s54
	s_addc_u32 s7, s7, s55
	global_load_ushort v192, v134, s[6:7]
	global_load_ushort v208, v134, s[6:7] offset:512
	s_add_u32 s6, s6, s54
	s_addc_u32 s7, s7, s55
	global_load_ushort v193, v134, s[6:7]
	global_load_ushort v209, v134, s[6:7] offset:512
	s_add_u32 s6, s6, s54
	s_addc_u32 s7, s7, s55
	global_load_ushort v194, v134, s[6:7]
	global_load_ushort v210, v134, s[6:7] offset:512
	s_add_u32 s6, s6, s54
	s_addc_u32 s7, s7, s55
	global_load_ushort v195, v134, s[6:7]
	global_load_ushort v211, v134, s[6:7] offset:512
	s_add_u32 s6, s6, s54
	s_addc_u32 s7, s7, s55
	v_mul_f32_e32 v18, 0xbfb8aa3b, v70
	v_mul_f32_e32 v19, 0xbfb8aa3b, v71
	v_mul_f32_e32 v20, 0xbfb8aa3b, v72
	v_mul_f32_e32 v21, 0xbfb8aa3b, v73
	v_mul_f32_e32 v22, 0xbfb8aa3b, v74
	v_mul_f32_e32 v23, 0xbfb8aa3b, v75
	v_mul_f32_e32 v24, 0xbfb8aa3b, v76
	v_mul_f32_e32 v25, 0xbfb8aa3b, v77
	v_mul_f32_e32 v26, 0xbfb8aa3b, v78
	v_mul_f32_e32 v27, 0xbfb8aa3b, v79
	v_mul_f32_e32 v28, 0xbfb8aa3b, v80
	v_mul_f32_e32 v29, 0xbfb8aa3b, v81
	v_mul_f32_e32 v30, 0xbfb8aa3b, v82
	v_mul_f32_e32 v31, 0xbfb8aa3b, v83
	v_mul_f32_e32 v32, 0xbfb8aa3b, v84
	v_mul_f32_e32 v33, 0xbfb8aa3b, v85
	v_exp_f32_e64 v236, -v18
	v_exp_f32_e64 v237, -v19
	v_exp_f32_e64 v238, -v20
	v_exp_f32_e64 v239, -v21
	v_exp_f32_e64 v240, -v22
	v_exp_f32_e64 v241, -v23
	v_exp_f32_e64 v242, -v24
	v_exp_f32_e64 v243, -v25
	v_exp_f32_e64 v244, -v26
	v_exp_f32_e64 v245, -v27
	v_exp_f32_e64 v246, -v28
	v_exp_f32_e64 v247, -v29
	v_exp_f32_e64 v248, -v30
	v_exp_f32_e64 v249, -v31
	v_exp_f32_e64 v250, -v32
	v_exp_f32_e64 v251, -v33
; __device__ __forceinline__ unsigned f2bf(float f) { unsigned r; asm("v_cvt_pk_bf16_f32 %0, %1, %1" : "=v"(r) : "v"(f)); return r & 0xffffu; }
; __device__ __forceinline__ void gl1_item(PREF p, int l, int item, bool valid, LAS unsigned char* pl, int sw, int lane) {
;     ...
;             for (int ss = 0; ss < 16; ++ss) { const int s = g4 * 16 + ss; const int i = d ? 63 - s : s; const size_t rowi = (size_t)(row0 + i * rstride);
;                 bc += gv[ss];
;                 const float en = __expf(-bc), ep = __expf(bc);
;                 const float kt = kc[ss] * en, qt = qc[ss] * 0.125f * ep;
;                 const unsigned ktb = f2bf(kt);
;                 sKt[lane * 72 + i] = (bf16_t)ktb;
;                 QK[rowi * 1024 + d * 512 + h * 64 + lane] = (bf16_t)f2bf(qt);
;                 QK[rowi * 1024 + d * 512 + 256 + h * 64 + lane] = (bf16_t)ktb;
;             }
	v_exp_f32_e32 v18, v18
	v_exp_f32_e32 v19, v19
	v_exp_f32_e32 v20, v20
	v_exp_f32_e32 v21, v21
	v_exp_f32_e32 v22, v22
	v_exp_f32_e32 v23, v23
	v_exp_f32_e32 v24, v24
	v_exp_f32_e32 v25, v25
	v_exp_f32_e32 v26, v26
	v_exp_f32_e32 v27, v27
	v_exp_f32_e32 v28, v28
	v_exp_f32_e32 v29, v29
	v_exp_f32_e32 v30, v30
	v_exp_f32_e32 v31, v31
	v_exp_f32_e32 v32, v32
	v_exp_f32_e32 v33, v33
	v_lshlrev_b32_e32 v164, 16, v164
	v_lshlrev_b32_e32 v165, 16, v165
	v_lshlrev_b32_e32 v166, 16, v166
	v_lshlrev_b32_e32 v167, 16, v167
	v_lshlrev_b32_e32 v168, 16, v168
	v_lshlrev_b32_e32 v169, 16, v169
	v_lshlrev_b32_e32 v170, 16, v170
	v_lshlrev_b32_e32 v171, 16, v171
	v_lshlrev_b32_e32 v172, 16, v172
	v_lshlrev_b32_e32 v173, 16, v173
	v_lshlrev_b32_e32 v174, 16, v174
	v_lshlrev_b32_e32 v175, 16, v175
	v_lshlrev_b32_e32 v176, 16, v176
	v_lshlrev_b32_e32 v177, 16, v177
	v_lshlrev_b32_e32 v178, 16, v178
	v_lshlrev_b32_e32 v179, 16, v179
	v_lshlrev_b32_e32 v148, 16, v148
	v_lshlrev_b32_e32 v149, 16, v149
	v_lshlrev_b32_e32 v150, 16, v150
	v_lshlrev_b32_e32 v151, 16, v151
	v_lshlrev_b32_e32 v152, 16, v152
	v_lshlrev_b32_e32 v153, 16, v153
	v_lshlrev_b32_e32 v154, 16, v154
	v_lshlrev_b32_e32 v155, 16, v155
	v_lshlrev_b32_e32 v156, 16, v156
	v_lshlrev_b32_e32 v157, 16, v157
	v_lshlrev_b32_e32 v158, 16, v158
	v_lshlrev_b32_e32 v159, 16, v159
	v_lshlrev_b32_e32 v160, 16, v160
	v_lshlrev_b32_e32 v161, 16, v161
	v_lshlrev_b32_e32 v162, 16, v162
	v_lshlrev_b32_e32 v163, 16, v163
	v_mul_f32_e32 v164, v18, v164
	v_mul_f32_e32 v165, v19, v165
	v_mul_f32_e32 v166, v20, v166
	v_mul_f32_e32 v167, v21, v167
	v_mul_f32_e32 v168, v22, v168
	v_mul_f32_e32 v169, v23, v169
	v_mul_f32_e32 v170, v24, v170
	v_mul_f32_e32 v171, v25, v171
	v_mul_f32_e32 v172, v26, v172
	v_mul_f32_e32 v173, v27, v173
	v_mul_f32_e32 v174, v28, v174
	v_mul_f32_e32 v175, v29, v175
	v_mul_f32_e32 v176, v30, v176
	v_mul_f32_e32 v177, v31, v177
	v_mul_f32_e32 v178, v32, v178
	v_mul_f32_e32 v179, v33, v179
	v_mul_f32_e32 v148, 0x3e000000, v148
	v_mul_f32_e32 v149, 0x3e000000, v149
	v_mul_f32_e32 v150, 0x3e000000, v150
	v_mul_f32_e32 v151, 0x3e000000, v151
	v_mul_f32_e32 v152, 0x3e000000, v152
	v_mul_f32_e32 v153, 0x3e000000, v153
	v_mul_f32_e32 v154, 0x3e000000, v154
	v_mul_f32_e32 v155, 0x3e000000, v155
	v_mul_f32_e32 v156, 0x3e000000, v156
	v_mul_f32_e32 v157, 0x3e000000, v157
	v_mul_f32_e32 v158, 0x3e000000, v158
	v_mul_f32_e32 v159, 0x3e000000, v159
	v_mul_f32_e32 v160, 0x3e000000, v160
	v_mul_f32_e32 v161, 0x3e000000, v161
	v_mul_f32_e32 v162, 0x3e000000, v162
	v_mul_f32_e32 v163, 0x3e000000, v163
	v_mul_f32_e32 v148, v148, v236
	v_mul_f32_e32 v149, v149, v237
	v_mul_f32_e32 v150, v150, v238
	v_mul_f32_e32 v151, v151, v239
	v_mul_f32_e32 v152, v152, v240
	v_mul_f32_e32 v153, v153, v241
	v_mul_f32_e32 v154, v154, v242
	v_mul_f32_e32 v155, v155, v243
	v_mul_f32_e32 v156, v156, v244
	v_mul_f32_e32 v157, v157, v245
	v_mul_f32_e32 v158, v158, v246
	v_mul_f32_e32 v159, v159, v247
	v_mul_f32_e32 v160, v160, v248
	v_mul_f32_e32 v161, v161, v249
	v_mul_f32_e32 v162, v162, v250
	v_mul_f32_e32 v163, v163, v251
	v_cvt_pk_bf16_f32 v164, v164, v164
	v_cvt_pk_bf16_f32 v165, v165, v165
	v_cvt_pk_bf16_f32 v166, v166, v166
	v_cvt_pk_bf16_f32 v167, v167, v167
	v_cvt_pk_bf16_f32 v168, v168, v168
	v_cvt_pk_bf16_f32 v169, v169, v169
	v_cvt_pk_bf16_f32 v170, v170, v170
	v_cvt_pk_bf16_f32 v171, v171, v171
	v_cvt_pk_bf16_f32 v172, v172, v172
	v_cvt_pk_bf16_f32 v173, v173, v173
	v_cvt_pk_bf16_f32 v174, v174, v174
	v_cvt_pk_bf16_f32 v175, v175, v175
	v_cvt_pk_bf16_f32 v176, v176, v176
	v_cvt_pk_bf16_f32 v177, v177, v177
	v_cvt_pk_bf16_f32 v178, v178, v178
	v_cvt_pk_bf16_f32 v179, v179, v179
	v_cvt_pk_bf16_f32 v148, v148, v148
	v_cvt_pk_bf16_f32 v149, v149, v149
	v_cvt_pk_bf16_f32 v150, v150, v150
	v_cvt_pk_bf16_f32 v151, v151, v151
	v_cvt_pk_bf16_f32 v152, v152, v152
	v_cvt_pk_bf16_f32 v153, v153, v153
	v_cvt_pk_bf16_f32 v154, v154, v154
	v_cvt_pk_bf16_f32 v155, v155, v155
	v_cvt_pk_bf16_f32 v156, v156, v156
	v_cvt_pk_bf16_f32 v157, v157, v157
	v_cvt_pk_bf16_f32 v158, v158, v158
	v_cvt_pk_bf16_f32 v159, v159, v159
	v_cvt_pk_bf16_f32 v160, v160, v160
	v_cvt_pk_bf16_f32 v161, v161, v161
	v_cvt_pk_bf16_f32 v162, v162, v162
	v_cvt_pk_bf16_f32 v163, v163, v163
	ds_write_b16 v60, v164
	v_add_u32_e32 v60, v61, v60
	global_store_short v134, v148, s[4:5]
	global_store_short v134, v164, s[4:5] offset:512
	s_add_u32 s4, s4, s56
	s_addc_u32 s5, s5, s3
	ds_write_b16 v60, v165
	v_add_u32_e32 v60, v61, v60
	global_store_short v134, v149, s[4:5]
	global_store_short v134, v165, s[4:5] offset:512
	s_add_u32 s4, s4, s56
	s_addc_u32 s5, s5, s3
	ds_write_b16 v60, v166
	v_add_u32_e32 v60, v61, v60
	global_store_short v134, v150, s[4:5]
	global_store_short v134, v166, s[4:5] offset:512
	s_add_u32 s4, s4, s56
	s_addc_u32 s5, s5, s3
	ds_write_b16 v60, v167
	v_add_u32_e32 v60, v61, v60
	global_store_short v134, v151, s[4:5]
	global_store_short v134, v167, s[4:5] offset:512
	s_add_u32 s4, s4, s56
	s_addc_u32 s5, s5, s3
	ds_write_b16 v60, v168
	v_add_u32_e32 v60, v61, v60
	global_store_short v134, v152, s[4:5]
	global_store_short v134, v168, s[4:5] offset:512
	s_add_u32 s4, s4, s56
	s_addc_u32 s5, s5, s3
	ds_write_b16 v60, v169
	v_add_u32_e32 v60, v61, v60
	global_store_short v134, v153, s[4:5]
	global_store_short v134, v169, s[4:5] offset:512
	s_add_u32 s4, s4, s56
	s_addc_u32 s5, s5, s3
	ds_write_b16 v60, v170
	v_add_u32_e32 v60, v61, v60
	global_store_short v134, v154, s[4:5]
	global_store_short v134, v170, s[4:5] offset:512
	s_add_u32 s4, s4, s56
	s_addc_u32 s5, s5, s3
	ds_write_b16 v60, v171
	v_add_u32_e32 v60, v61, v60
	global_store_short v134, v155, s[4:5]
; __device__ __forceinline__ unsigned f2bf(float f) { unsigned r; asm("v_cvt_pk_bf16_f32 %0, %1, %1" : "=v"(r) : "v"(f)); return r & 0xffffu; }
; __device__ __forceinline__ void gl1_item(PREF p, int l, int item, bool valid, LAS unsigned char* pl, int sw, int lane) {
;     ...
;             for (int ss = 0; ss < 16; ++ss) { const int s = g4 * 16 + ss; const int i = d ? 63 - s : s;
;                 float z = bup;
; #pragma unroll
;                 for (int r2 = 0; r2 < 8; ++r2) { const unsigned w = (unsigned)__builtin_amdgcn_readlane((int)lrp[r2], i);
;                     z = __builtin_amdgcn_fdot2_f32_bf16(__builtin_bit_cast(bf16x2_t, w), __builtin_bit_cast(bf16x2_t, wupp[r2]), z, false); }
;     ...
;             for (int ss = 0; ss < 16; ++ss) { const int s = g4 * 16 + ss; const int i = d ? 63 - s : s; const size_t rowi = (size_t)(row0 + i * rstride);
;                 bc += gv[ss];
;                 const float en = __expf(-bc), ep = __expf(bc);
;                 const float kt = kc[ss] * en, qt = qc[ss] * 0.125f * ep;
;                 const unsigned ktb = f2bf(kt);
;                 sKt[lane * 72 + i] = (bf16_t)ktb;
;                 QK[rowi * 1024 + d * 512 + h * 64 + lane] = (bf16_t)f2bf(qt);
;                 QK[rowi * 1024 + d * 512 + 256 + h * 64 + lane] = (bf16_t)ktb;
;             }
	global_store_short v134, v171, s[4:5] offset:512
	s_add_u32 s4, s4, s56
	s_addc_u32 s5, s5, s3
	ds_write_b16 v60, v172
	v_add_u32_e32 v60, v61, v60
	global_store_short v134, v156, s[4:5]
	global_store_short v134, v172, s[4:5] offset:512
	s_add_u32 s4, s4, s56
	s_addc_u32 s5, s5, s3
	ds_write_b16 v60, v173
	v_add_u32_e32 v60, v61, v60
	global_store_short v134, v157, s[4:5]
	global_store_short v134, v173, s[4:5] offset:512
	s_add_u32 s4, s4, s56
	s_addc_u32 s5, s5, s3
	ds_write_b16 v60, v174
	v_add_u32_e32 v60, v61, v60
	global_store_short v134, v158, s[4:5]
	global_store_short v134, v174, s[4:5] offset:512
	s_add_u32 s4, s4, s56
	s_addc_u32 s5, s5, s3
	ds_write_b16 v60, v175
	v_add_u32_e32 v60, v61, v60
	global_store_short v134, v159, s[4:5]
	global_store_short v134, v175, s[4:5] offset:512
	s_add_u32 s4, s4, s56
	s_addc_u32 s5, s5, s3
	ds_write_b16 v60, v176
	v_add_u32_e32 v60, v61, v60
	global_store_short v134, v160, s[4:5]
	global_store_short v134, v176, s[4:5] offset:512
	s_add_u32 s4, s4, s56
	s_addc_u32 s5, s5, s3
	ds_write_b16 v60, v177
	v_add_u32_e32 v60, v61, v60
	global_store_short v134, v161, s[4:5]
	global_store_short v134, v177, s[4:5] offset:512
	s_add_u32 s4, s4, s56
	s_addc_u32 s5, s5, s3
	ds_write_b16 v60, v178
	v_add_u32_e32 v60, v61, v60
	global_store_short v134, v162, s[4:5]
	global_store_short v134, v178, s[4:5] offset:512
	s_add_u32 s4, s4, s56
	s_addc_u32 s5, s5, s3
	ds_write_b16 v60, v179
	v_add_u32_e32 v60, v61, v60
	global_store_short v134, v163, s[4:5]
	global_store_short v134, v179, s[4:5] offset:512
	s_add_u32 s4, s4, s56
	s_addc_u32 s5, s5, s3
	v_mov_b32_e32 v236, v16
	v_dot2c_f32_bf16_dpp v236, v122, v8 row_newbcast:0 row_mask:0xf bank_mask:0xf
	v_dot2c_f32_bf16_dpp v236, v123, v9 row_newbcast:0 row_mask:0xf bank_mask:0xf
	v_dot2c_f32_bf16_dpp v236, v124, v10 row_newbcast:0 row_mask:0xf bank_mask:0xf
	v_dot2c_f32_bf16_dpp v236, v125, v11 row_newbcast:0 row_mask:0xf bank_mask:0xf
	v_dot2c_f32_bf16_dpp v236, v126, v12 row_newbcast:0 row_mask:0xf bank_mask:0xf
	v_dot2c_f32_bf16_dpp v236, v127, v13 row_newbcast:0 row_mask:0xf bank_mask:0xf
	v_dot2c_f32_bf16_dpp v236, v128, v14 row_newbcast:0 row_mask:0xf bank_mask:0xf
	v_dot2c_f32_bf16_dpp v236, v129, v15 row_newbcast:0 row_mask:0xf bank_mask:0xf
	v_mov_b32_e32 v237, v16
	v_dot2c_f32_bf16_dpp v237, v122, v8 row_newbcast:1 row_mask:0xf bank_mask:0xf
	v_dot2c_f32_bf16_dpp v237, v123, v9 row_newbcast:1 row_mask:0xf bank_mask:0xf
	v_dot2c_f32_bf16_dpp v237, v124, v10 row_newbcast:1 row_mask:0xf bank_mask:0xf
	v_dot2c_f32_bf16_dpp v237, v125, v11 row_newbcast:1 row_mask:0xf bank_mask:0xf
	v_dot2c_f32_bf16_dpp v237, v126, v12 row_newbcast:1 row_mask:0xf bank_mask:0xf
	v_dot2c_f32_bf16_dpp v237, v127, v13 row_newbcast:1 row_mask:0xf bank_mask:0xf
	v_dot2c_f32_bf16_dpp v237, v128, v14 row_newbcast:1 row_mask:0xf bank_mask:0xf
	v_dot2c_f32_bf16_dpp v237, v129, v15 row_newbcast:1 row_mask:0xf bank_mask:0xf
	v_mov_b32_e32 v238, v16
	v_dot2c_f32_bf16_dpp v238, v122, v8 row_newbcast:2 row_mask:0xf bank_mask:0xf
	v_dot2c_f32_bf16_dpp v238, v123, v9 row_newbcast:2 row_mask:0xf bank_mask:0xf
	v_dot2c_f32_bf16_dpp v238, v124, v10 row_newbcast:2 row_mask:0xf bank_mask:0xf
	v_dot2c_f32_bf16_dpp v238, v125, v11 row_newbcast:2 row_mask:0xf bank_mask:0xf
	v_dot2c_f32_bf16_dpp v238, v126, v12 row_newbcast:2 row_mask:0xf bank_mask:0xf
	v_dot2c_f32_bf16_dpp v238, v127, v13 row_newbcast:2 row_mask:0xf bank_mask:0xf
	v_dot2c_f32_bf16_dpp v238, v128, v14 row_newbcast:2 row_mask:0xf bank_mask:0xf
	v_dot2c_f32_bf16_dpp v238, v129, v15 row_newbcast:2 row_mask:0xf bank_mask:0xf
	v_mov_b32_e32 v239, v16
	v_dot2c_f32_bf16_dpp v239, v122, v8 row_newbcast:3 row_mask:0xf bank_mask:0xf
	v_dot2c_f32_bf16_dpp v239, v123, v9 row_newbcast:3 row_mask:0xf bank_mask:0xf
	v_dot2c_f32_bf16_dpp v239, v124, v10 row_newbcast:3 row_mask:0xf bank_mask:0xf
	v_dot2c_f32_bf16_dpp v239, v125, v11 row_newbcast:3 row_mask:0xf bank_mask:0xf
	v_dot2c_f32_bf16_dpp v239, v126, v12 row_newbcast:3 row_mask:0xf bank_mask:0xf
	v_dot2c_f32_bf16_dpp v239, v127, v13 row_newbcast:3 row_mask:0xf bank_mask:0xf
	v_dot2c_f32_bf16_dpp v239, v128, v14 row_newbcast:3 row_mask:0xf bank_mask:0xf
	v_dot2c_f32_bf16_dpp v239, v129, v15 row_newbcast:3 row_mask:0xf bank_mask:0xf
	v_mov_b32_e32 v240, v16
	v_dot2c_f32_bf16_dpp v240, v122, v8 row_newbcast:4 row_mask:0xf bank_mask:0xf
	v_dot2c_f32_bf16_dpp v240, v123, v9 row_newbcast:4 row_mask:0xf bank_mask:0xf
	v_dot2c_f32_bf16_dpp v240, v124, v10 row_newbcast:4 row_mask:0xf bank_mask:0xf
	v_dot2c_f32_bf16_dpp v240, v125, v11 row_newbcast:4 row_mask:0xf bank_mask:0xf
	v_dot2c_f32_bf16_dpp v240, v126, v12 row_newbcast:4 row_mask:0xf bank_mask:0xf
	v_dot2c_f32_bf16_dpp v240, v127, v13 row_newbcast:4 row_mask:0xf bank_mask:0xf
	v_dot2c_f32_bf16_dpp v240, v128, v14 row_newbcast:4 row_mask:0xf bank_mask:0xf
	v_dot2c_f32_bf16_dpp v240, v129, v15 row_newbcast:4 row_mask:0xf bank_mask:0xf
	v_mov_b32_e32 v241, v16
	v_dot2c_f32_bf16_dpp v241, v122, v8 row_newbcast:5 row_mask:0xf bank_mask:0xf
	v_dot2c_f32_bf16_dpp v241, v123, v9 row_newbcast:5 row_mask:0xf bank_mask:0xf
	v_dot2c_f32_bf16_dpp v241, v124, v10 row_newbcast:5 row_mask:0xf bank_mask:0xf
	v_dot2c_f32_bf16_dpp v241, v125, v11 row_newbcast:5 row_mask:0xf bank_mask:0xf
	v_dot2c_f32_bf16_dpp v241, v126, v12 row_newbcast:5 row_mask:0xf bank_mask:0xf
	v_dot2c_f32_bf16_dpp v241, v127, v13 row_newbcast:5 row_mask:0xf bank_mask:0xf
	v_dot2c_f32_bf16_dpp v241, v128, v14 row_newbcast:5 row_mask:0xf bank_mask:0xf
	v_dot2c_f32_bf16_dpp v241, v129, v15 row_newbcast:5 row_mask:0xf bank_mask:0xf
	v_mov_b32_e32 v242, v16
; __device__ __forceinline__ void gl1_item(PREF p, int l, int item, bool valid, LAS unsigned char* pl, int sw, int lane) {
;     ...
;             for (int ss = 0; ss < 16; ++ss) { const int s = g4 * 16 + ss; const int i = d ? 63 - s : s;
;                 float z = bup;
; #pragma unroll
;                 for (int r2 = 0; r2 < 8; ++r2) { const unsigned w = (unsigned)__builtin_amdgcn_readlane((int)lrp[r2], i);
;                     z = __builtin_amdgcn_fdot2_f32_bf16(__builtin_bit_cast(bf16x2_t, w), __builtin_bit_cast(bf16x2_t, wupp[r2]), z, false); }
;                 gv[ss] = -(fmaxf(-z, 0.f) + __logf(1.f + __expf(-fabsf(z)))) * (1.f / 16.f);
	v_dot2c_f32_bf16_dpp v242, v122, v8 row_newbcast:6 row_mask:0xf bank_mask:0xf
	v_dot2c_f32_bf16_dpp v242, v123, v9 row_newbcast:6 row_mask:0xf bank_mask:0xf
	v_dot2c_f32_bf16_dpp v242, v124, v10 row_newbcast:6 row_mask:0xf bank_mask:0xf
	v_dot2c_f32_bf16_dpp v242, v125, v11 row_newbcast:6 row_mask:0xf bank_mask:0xf
	v_dot2c_f32_bf16_dpp v242, v126, v12 row_newbcast:6 row_mask:0xf bank_mask:0xf
	v_dot2c_f32_bf16_dpp v242, v127, v13 row_newbcast:6 row_mask:0xf bank_mask:0xf
	v_dot2c_f32_bf16_dpp v242, v128, v14 row_newbcast:6 row_mask:0xf bank_mask:0xf
	v_dot2c_f32_bf16_dpp v242, v129, v15 row_newbcast:6 row_mask:0xf bank_mask:0xf
	v_mov_b32_e32 v243, v16
	v_dot2c_f32_bf16_dpp v243, v122, v8 row_newbcast:7 row_mask:0xf bank_mask:0xf
	v_dot2c_f32_bf16_dpp v243, v123, v9 row_newbcast:7 row_mask:0xf bank_mask:0xf
	v_dot2c_f32_bf16_dpp v243, v124, v10 row_newbcast:7 row_mask:0xf bank_mask:0xf
	v_dot2c_f32_bf16_dpp v243, v125, v11 row_newbcast:7 row_mask:0xf bank_mask:0xf
	v_dot2c_f32_bf16_dpp v243, v126, v12 row_newbcast:7 row_mask:0xf bank_mask:0xf
	v_dot2c_f32_bf16_dpp v243, v127, v13 row_newbcast:7 row_mask:0xf bank_mask:0xf
	v_dot2c_f32_bf16_dpp v243, v128, v14 row_newbcast:7 row_mask:0xf bank_mask:0xf
	v_dot2c_f32_bf16_dpp v243, v129, v15 row_newbcast:7 row_mask:0xf bank_mask:0xf
	v_mov_b32_e32 v244, v16
	v_dot2c_f32_bf16_dpp v244, v122, v8 row_newbcast:8 row_mask:0xf bank_mask:0xf
	v_dot2c_f32_bf16_dpp v244, v123, v9 row_newbcast:8 row_mask:0xf bank_mask:0xf
	v_dot2c_f32_bf16_dpp v244, v124, v10 row_newbcast:8 row_mask:0xf bank_mask:0xf
	v_dot2c_f32_bf16_dpp v244, v125, v11 row_newbcast:8 row_mask:0xf bank_mask:0xf
	v_dot2c_f32_bf16_dpp v244, v126, v12 row_newbcast:8 row_mask:0xf bank_mask:0xf
	v_dot2c_f32_bf16_dpp v244, v127, v13 row_newbcast:8 row_mask:0xf bank_mask:0xf
	v_dot2c_f32_bf16_dpp v244, v128, v14 row_newbcast:8 row_mask:0xf bank_mask:0xf
	v_dot2c_f32_bf16_dpp v244, v129, v15 row_newbcast:8 row_mask:0xf bank_mask:0xf
	v_mov_b32_e32 v245, v16
	v_dot2c_f32_bf16_dpp v245, v122, v8 row_newbcast:9 row_mask:0xf bank_mask:0xf
	v_dot2c_f32_bf16_dpp v245, v123, v9 row_newbcast:9 row_mask:0xf bank_mask:0xf
	v_dot2c_f32_bf16_dpp v245, v124, v10 row_newbcast:9 row_mask:0xf bank_mask:0xf
	v_dot2c_f32_bf16_dpp v245, v125, v11 row_newbcast:9 row_mask:0xf bank_mask:0xf
	v_dot2c_f32_bf16_dpp v245, v126, v12 row_newbcast:9 row_mask:0xf bank_mask:0xf
	v_dot2c_f32_bf16_dpp v245, v127, v13 row_newbcast:9 row_mask:0xf bank_mask:0xf
	v_dot2c_f32_bf16_dpp v245, v128, v14 row_newbcast:9 row_mask:0xf bank_mask:0xf
	v_dot2c_f32_bf16_dpp v245, v129, v15 row_newbcast:9 row_mask:0xf bank_mask:0xf
	v_mov_b32_e32 v246, v16
	v_dot2c_f32_bf16_dpp v246, v122, v8 row_newbcast:10 row_mask:0xf bank_mask:0xf
	v_dot2c_f32_bf16_dpp v246, v123, v9 row_newbcast:10 row_mask:0xf bank_mask:0xf
	v_dot2c_f32_bf16_dpp v246, v124, v10 row_newbcast:10 row_mask:0xf bank_mask:0xf
	v_dot2c_f32_bf16_dpp v246, v125, v11 row_newbcast:10 row_mask:0xf bank_mask:0xf
	v_dot2c_f32_bf16_dpp v246, v126, v12 row_newbcast:10 row_mask:0xf bank_mask:0xf
	v_dot2c_f32_bf16_dpp v246, v127, v13 row_newbcast:10 row_mask:0xf bank_mask:0xf
	v_dot2c_f32_bf16_dpp v246, v128, v14 row_newbcast:10 row_mask:0xf bank_mask:0xf
	v_dot2c_f32_bf16_dpp v246, v129, v15 row_newbcast:10 row_mask:0xf bank_mask:0xf
	v_mov_b32_e32 v247, v16
	v_dot2c_f32_bf16_dpp v247, v122, v8 row_newbcast:11 row_mask:0xf bank_mask:0xf
	v_dot2c_f32_bf16_dpp v247, v123, v9 row_newbcast:11 row_mask:0xf bank_mask:0xf
	v_dot2c_f32_bf16_dpp v247, v124, v10 row_newbcast:11 row_mask:0xf bank_mask:0xf
	v_dot2c_f32_bf16_dpp v247, v125, v11 row_newbcast:11 row_mask:0xf bank_mask:0xf
	v_dot2c_f32_bf16_dpp v247, v126, v12 row_newbcast:11 row_mask:0xf bank_mask:0xf
	v_dot2c_f32_bf16_dpp v247, v127, v13 row_newbcast:11 row_mask:0xf bank_mask:0xf
	v_dot2c_f32_bf16_dpp v247, v128, v14 row_newbcast:11 row_mask:0xf bank_mask:0xf
	v_dot2c_f32_bf16_dpp v247, v129, v15 row_newbcast:11 row_mask:0xf bank_mask:0xf
	v_mov_b32_e32 v248, v16
	v_dot2c_f32_bf16_dpp v248, v122, v8 row_newbcast:12 row_mask:0xf bank_mask:0xf
	v_dot2c_f32_bf16_dpp v248, v123, v9 row_newbcast:12 row_mask:0xf bank_mask:0xf
	v_dot2c_f32_bf16_dpp v248, v124, v10 row_newbcast:12 row_mask:0xf bank_mask:0xf
	v_dot2c_f32_bf16_dpp v248, v125, v11 row_newbcast:12 row_mask:0xf bank_mask:0xf
	v_dot2c_f32_bf16_dpp v248, v126, v12 row_newbcast:12 row_mask:0xf bank_mask:0xf
	v_dot2c_f32_bf16_dpp v248, v127, v13 row_newbcast:12 row_mask:0xf bank_mask:0xf
	v_dot2c_f32_bf16_dpp v248, v128, v14 row_newbcast:12 row_mask:0xf bank_mask:0xf
	v_dot2c_f32_bf16_dpp v248, v129, v15 row_newbcast:12 row_mask:0xf bank_mask:0xf
	v_mov_b32_e32 v249, v16
	v_dot2c_f32_bf16_dpp v249, v122, v8 row_newbcast:13 row_mask:0xf bank_mask:0xf
	v_dot2c_f32_bf16_dpp v249, v123, v9 row_newbcast:13 row_mask:0xf bank_mask:0xf
	v_dot2c_f32_bf16_dpp v249, v124, v10 row_newbcast:13 row_mask:0xf bank_mask:0xf
	v_dot2c_f32_bf16_dpp v249, v125, v11 row_newbcast:13 row_mask:0xf bank_mask:0xf
	v_dot2c_f32_bf16_dpp v249, v126, v12 row_newbcast:13 row_mask:0xf bank_mask:0xf
	v_dot2c_f32_bf16_dpp v249, v127, v13 row_newbcast:13 row_mask:0xf bank_mask:0xf
	v_dot2c_f32_bf16_dpp v249, v128, v14 row_newbcast:13 row_mask:0xf bank_mask:0xf
	v_dot2c_f32_bf16_dpp v249, v129, v15 row_newbcast:13 row_mask:0xf bank_mask:0xf
	v_mov_b32_e32 v250, v16
	v_dot2c_f32_bf16_dpp v250, v122, v8 row_newbcast:14 row_mask:0xf bank_mask:0xf
	v_dot2c_f32_bf16_dpp v250, v123, v9 row_newbcast:14 row_mask:0xf bank_mask:0xf
	v_dot2c_f32_bf16_dpp v250, v124, v10 row_newbcast:14 row_mask:0xf bank_mask:0xf
	v_dot2c_f32_bf16_dpp v250, v125, v11 row_newbcast:14 row_mask:0xf bank_mask:0xf
; __device__ __forceinline__ void gl1_item(PREF p, int l, int item, bool valid, LAS unsigned char* pl, int sw, int lane) {
;     ...
;             for (int ss = 0; ss < 16; ++ss) { const int s = g4 * 16 + ss; const int i = d ? 63 - s : s;
;                 float z = bup;
; #pragma unroll
;                 for (int r2 = 0; r2 < 8; ++r2) { const unsigned w = (unsigned)__builtin_amdgcn_readlane((int)lrp[r2], i);
;                     z = __builtin_amdgcn_fdot2_f32_bf16(__builtin_bit_cast(bf16x2_t, w), __builtin_bit_cast(bf16x2_t, wupp[r2]), z, false); }
;                 gv[ss] = -(fmaxf(-z, 0.f) + __logf(1.f + __expf(-fabsf(z)))) * (1.f / 16.f);
;                 __builtin_amdgcn_sched_barrier(0);
;             }
; #pragma unroll
;             for (int ss = 0; ss < 16; ++ss) { const int s = g4 * 16 + ss; const int i = d ? 63 - s : s; const size_t rowi = (size_t)(row0 + i * rstride);
;                 bc += gv[ss];
;                 const float en = __expf(-bc), ep = __expf(bc);
;                 const float kt = kc[ss] * en, qt = qc[ss] * 0.125f * ep;
	v_dot2c_f32_bf16_dpp v250, v126, v12 row_newbcast:14 row_mask:0xf bank_mask:0xf
	v_dot2c_f32_bf16_dpp v250, v127, v13 row_newbcast:14 row_mask:0xf bank_mask:0xf
	v_dot2c_f32_bf16_dpp v250, v128, v14 row_newbcast:14 row_mask:0xf bank_mask:0xf
	v_dot2c_f32_bf16_dpp v250, v129, v15 row_newbcast:14 row_mask:0xf bank_mask:0xf
	v_mov_b32_e32 v251, v16
	v_dot2c_f32_bf16_dpp v251, v122, v8 row_newbcast:15 row_mask:0xf bank_mask:0xf
	v_dot2c_f32_bf16_dpp v251, v123, v9 row_newbcast:15 row_mask:0xf bank_mask:0xf
	v_dot2c_f32_bf16_dpp v251, v124, v10 row_newbcast:15 row_mask:0xf bank_mask:0xf
	v_dot2c_f32_bf16_dpp v251, v125, v11 row_newbcast:15 row_mask:0xf bank_mask:0xf
	v_dot2c_f32_bf16_dpp v251, v126, v12 row_newbcast:15 row_mask:0xf bank_mask:0xf
	v_dot2c_f32_bf16_dpp v251, v127, v13 row_newbcast:15 row_mask:0xf bank_mask:0xf
	v_dot2c_f32_bf16_dpp v251, v128, v14 row_newbcast:15 row_mask:0xf bank_mask:0xf
	v_dot2c_f32_bf16_dpp v251, v129, v15 row_newbcast:15 row_mask:0xf bank_mask:0xf
	s_nop 2
	v_mul_f32_e64 v18, |v236|, s1
	v_mul_f32_e64 v19, |v237|, s1
	v_mul_f32_e64 v20, |v238|, s1
	v_mul_f32_e64 v21, |v239|, s1
	v_mul_f32_e64 v22, |v240|, s1
	v_mul_f32_e64 v23, |v241|, s1
	v_mul_f32_e64 v24, |v242|, s1
	v_mul_f32_e64 v25, |v243|, s1
	v_mul_f32_e64 v26, |v244|, s1
	v_mul_f32_e64 v27, |v245|, s1
	v_mul_f32_e64 v28, |v246|, s1
	v_mul_f32_e64 v29, |v247|, s1
	v_mul_f32_e64 v30, |v248|, s1
	v_mul_f32_e64 v31, |v249|, s1
	v_mul_f32_e64 v32, |v250|, s1
	v_mul_f32_e64 v33, |v251|, s1
	v_exp_f32_e32 v18, v18
	v_exp_f32_e32 v19, v19
	v_exp_f32_e32 v20, v20
	v_exp_f32_e32 v21, v21
	v_exp_f32_e32 v22, v22
	v_exp_f32_e32 v23, v23
	v_exp_f32_e32 v24, v24
	v_exp_f32_e32 v25, v25
	v_exp_f32_e32 v26, v26
	v_exp_f32_e32 v27, v27
	v_exp_f32_e32 v28, v28
	v_exp_f32_e32 v29, v29
	v_exp_f32_e32 v30, v30
	v_exp_f32_e32 v31, v31
	v_exp_f32_e32 v32, v32
	v_exp_f32_e32 v33, v33
	v_max_f32_e64 v236, -v236, 0
	v_max_f32_e64 v237, -v237, 0
	v_max_f32_e64 v238, -v238, 0
	v_max_f32_e64 v239, -v239, 0
	v_max_f32_e64 v240, -v240, 0
	v_max_f32_e64 v241, -v241, 0
	v_max_f32_e64 v242, -v242, 0
	v_max_f32_e64 v243, -v243, 0
	v_max_f32_e64 v244, -v244, 0
	v_max_f32_e64 v245, -v245, 0
	v_max_f32_e64 v246, -v246, 0
	v_max_f32_e64 v247, -v247, 0
	v_max_f32_e64 v248, -v248, 0
	v_max_f32_e64 v249, -v249, 0
	v_max_f32_e64 v250, -v250, 0
	v_max_f32_e64 v251, -v251, 0
	v_add_f32_e32 v18, 1.0, v18
	v_add_f32_e32 v19, 1.0, v19
	v_add_f32_e32 v20, 1.0, v20
	v_add_f32_e32 v21, 1.0, v21
	v_add_f32_e32 v22, 1.0, v22
	v_add_f32_e32 v23, 1.0, v23
	v_add_f32_e32 v24, 1.0, v24
	v_add_f32_e32 v25, 1.0, v25
	v_add_f32_e32 v26, 1.0, v26
	v_add_f32_e32 v27, 1.0, v27
	v_add_f32_e32 v28, 1.0, v28
	v_add_f32_e32 v29, 1.0, v29
	v_add_f32_e32 v30, 1.0, v30
	v_add_f32_e32 v31, 1.0, v31
	v_add_f32_e32 v32, 1.0, v32
	v_add_f32_e32 v33, 1.0, v33
	v_log_f32_e32 v18, v18
	v_log_f32_e32 v19, v19
	v_log_f32_e32 v20, v20
	v_log_f32_e32 v21, v21
	v_log_f32_e32 v22, v22
	v_log_f32_e32 v23, v23
	v_log_f32_e32 v24, v24
	v_log_f32_e32 v25, v25
	v_log_f32_e32 v26, v26
	v_log_f32_e32 v27, v27
	v_log_f32_e32 v28, v28
	v_log_f32_e32 v29, v29
	v_log_f32_e32 v30, v30
	v_log_f32_e32 v31, v31
	v_log_f32_e32 v32, v32
	v_log_f32_e32 v33, v33
	s_mov_b32 s45, 0x3f317217
	v_mul_f32_e32 v70, 0x3f317217, v18
	v_mul_f32_e32 v71, 0x3f317217, v19
	v_mul_f32_e32 v72, 0x3f317217, v20
	v_mul_f32_e32 v73, 0x3f317217, v21
	v_mul_f32_e32 v74, 0x3f317217, v22
	v_mul_f32_e32 v75, 0x3f317217, v23
	v_mul_f32_e32 v76, 0x3f317217, v24
	v_mul_f32_e32 v77, 0x3f317217, v25
	v_mul_f32_e32 v78, 0x3f317217, v26
	v_mul_f32_e32 v79, 0x3f317217, v27
	v_mul_f32_e32 v80, 0x3f317217, v28
	v_mul_f32_e32 v81, 0x3f317217, v29
	v_mul_f32_e32 v82, 0x3f317217, v30
	v_mul_f32_e32 v83, 0x3f317217, v31
	v_mul_f32_e32 v84, 0x3f317217, v32
	v_mul_f32_e32 v85, 0x3f317217, v33
	v_fma_f32 v70, v18, s45, -v70
	v_fma_f32 v71, v19, s45, -v71
	v_fma_f32 v72, v20, s45, -v72
	v_fma_f32 v73, v21, s45, -v73
	v_fma_f32 v74, v22, s45, -v74
	v_fma_f32 v75, v23, s45, -v75
	v_fma_f32 v76, v24, s45, -v76
	v_fma_f32 v77, v25, s45, -v77
	v_fma_f32 v78, v26, s45, -v78
	v_fma_f32 v79, v27, s45, -v79
	v_fma_f32 v80, v28, s45, -v80
	v_fma_f32 v81, v29, s45, -v81
	v_fma_f32 v82, v30, s45, -v82
	v_fma_f32 v83, v31, s45, -v83
	v_fma_f32 v84, v32, s45, -v84
	v_fma_f32 v85, v33, s45, -v85
	v_fmac_f32_e32 v70, 0x3377d1cf, v18
	v_fmac_f32_e32 v71, 0x3377d1cf, v19
	v_fmac_f32_e32 v72, 0x3377d1cf, v20
	v_fmac_f32_e32 v73, 0x3377d1cf, v21
	v_fmac_f32_e32 v74, 0x3377d1cf, v22
	v_fmac_f32_e32 v75, 0x3377d1cf, v23
	v_fmac_f32_e32 v76, 0x3377d1cf, v24
	v_fmac_f32_e32 v77, 0x3377d1cf, v25
	v_fmac_f32_e32 v78, 0x3377d1cf, v26
	v_fmac_f32_e32 v79, 0x3377d1cf, v27
	v_fmac_f32_e32 v80, 0x3377d1cf, v28
	v_fmac_f32_e32 v81, 0x3377d1cf, v29
	v_fmac_f32_e32 v82, 0x3377d1cf, v30
	v_fmac_f32_e32 v83, 0x3377d1cf, v31
	v_fmac_f32_e32 v84, 0x3377d1cf, v32
	v_fmac_f32_e32 v85, 0x3377d1cf, v33
	v_fmac_f32_e32 v70, 0x3f317217, v18
	v_fmac_f32_e32 v71, 0x3f317217, v19
	v_fmac_f32_e32 v72, 0x3f317217, v20
	v_fmac_f32_e32 v73, 0x3f317217, v21
	v_fmac_f32_e32 v74, 0x3f317217, v22
	v_fmac_f32_e32 v75, 0x3f317217, v23
	v_fmac_f32_e32 v76, 0x3f317217, v24
	v_fmac_f32_e32 v77, 0x3f317217, v25
	v_fmac_f32_e32 v78, 0x3f317217, v26
	v_fmac_f32_e32 v79, 0x3f317217, v27
	v_fmac_f32_e32 v80, 0x3f317217, v28
	v_fmac_f32_e32 v81, 0x3f317217, v29
	v_fmac_f32_e32 v82, 0x3f317217, v30
	v_fmac_f32_e32 v83, 0x3f317217, v31
	v_fmac_f32_e32 v84, 0x3f317217, v32
	v_fmac_f32_e32 v85, 0x3f317217, v33
	v_add_f32_e32 v236, v236, v70
	v_add_f32_e32 v237, v237, v71
	v_add_f32_e32 v238, v238, v72
	v_add_f32_e32 v239, v239, v73
	v_add_f32_e32 v240, v240, v74
	v_add_f32_e32 v241, v241, v75
	v_add_f32_e32 v242, v242, v76
	v_add_f32_e32 v243, v243, v77
	v_add_f32_e32 v244, v244, v78
	v_add_f32_e32 v245, v245, v79
	v_add_f32_e32 v246, v246, v80
	v_add_f32_e32 v247, v247, v81
	v_add_f32_e32 v248, v248, v82
	v_add_f32_e32 v249, v249, v83
	v_add_f32_e32 v250, v250, v84
	v_add_f32_e32 v251, v251, v85
	v_fma_f32 v70, v236, s49, v17
	v_fma_f32 v71, v237, s49, v70
	v_fma_f32 v72, v238, s49, v71
	v_fma_f32 v73, v239, s49, v72
	v_fma_f32 v74, v240, s49, v73
	v_fma_f32 v75, v241, s49, v74
	v_fma_f32 v76, v242, s49, v75
	v_fma_f32 v77, v243, s49, v76
	v_fma_f32 v78, v244, s49, v77
	v_fma_f32 v79, v245, s49, v78
	v_fma_f32 v80, v246, s49, v79
	v_fma_f32 v81, v247, s49, v80
	v_fma_f32 v82, v248, s49, v81
	v_fma_f32 v83, v249, s49, v82
	v_fma_f32 v84, v250, s49, v83
	v_fma_f32 v85, v251, s49, v84
	v_mov_b32_e32 v17, v85
	s_waitcnt vmcnt(32)
; __device__ __forceinline__ unsigned f2bf(float f) { unsigned r; asm("v_cvt_pk_bf16_f32 %0, %1, %1" : "=v"(r) : "v"(f)); return r & 0xffffu; }
; __device__ __forceinline__ void gl1_item(PREF p, int l, int item, bool valid, LAS unsigned char* pl, int sw, int lane) {
;     ...
;             for (int ss = 0; ss < 16; ++ss) { const int s = g4 * 16 + ss; const int i = d ? 63 - s : s; const size_t rowi = (size_t)(row0 + i * rstride);
;                 bc += gv[ss];
;                 const float en = __expf(-bc), ep = __expf(bc);
;                 const float kt = kc[ss] * en, qt = qc[ss] * 0.125f * ep;
;                 const unsigned ktb = f2bf(kt);
;                 sKt[lane * 72 + i] = (bf16_t)ktb;
;                 QK[rowi * 1024 + d * 512 + h * 64 + lane] = (bf16_t)f2bf(qt);
;                 QK[rowi * 1024 + d * 512 + 256 + h * 64 + lane] = (bf16_t)ktb;
	v_mul_f32_e32 v18, 0xbfb8aa3b, v70
	v_mul_f32_e32 v19, 0xbfb8aa3b, v71
	v_mul_f32_e32 v20, 0xbfb8aa3b, v72
	v_mul_f32_e32 v21, 0xbfb8aa3b, v73
	v_mul_f32_e32 v22, 0xbfb8aa3b, v74
	v_mul_f32_e32 v23, 0xbfb8aa3b, v75
	v_mul_f32_e32 v24, 0xbfb8aa3b, v76
	v_mul_f32_e32 v25, 0xbfb8aa3b, v77
	v_mul_f32_e32 v26, 0xbfb8aa3b, v78
	v_mul_f32_e32 v27, 0xbfb8aa3b, v79
	v_mul_f32_e32 v28, 0xbfb8aa3b, v80
	v_mul_f32_e32 v29, 0xbfb8aa3b, v81
	v_mul_f32_e32 v30, 0xbfb8aa3b, v82
	v_mul_f32_e32 v31, 0xbfb8aa3b, v83
	v_mul_f32_e32 v32, 0xbfb8aa3b, v84
	v_mul_f32_e32 v33, 0xbfb8aa3b, v85
	v_exp_f32_e64 v236, -v18
	v_exp_f32_e64 v237, -v19
	v_exp_f32_e64 v238, -v20
	v_exp_f32_e64 v239, -v21
	v_exp_f32_e64 v240, -v22
	v_exp_f32_e64 v241, -v23
	v_exp_f32_e64 v242, -v24
	v_exp_f32_e64 v243, -v25
	v_exp_f32_e64 v244, -v26
	v_exp_f32_e64 v245, -v27
	v_exp_f32_e64 v246, -v28
	v_exp_f32_e64 v247, -v29
	v_exp_f32_e64 v248, -v30
	v_exp_f32_e64 v249, -v31
	v_exp_f32_e64 v250, -v32
	v_exp_f32_e64 v251, -v33
	v_exp_f32_e32 v18, v18
	v_exp_f32_e32 v19, v19
	v_exp_f32_e32 v20, v20
	v_exp_f32_e32 v21, v21
	v_exp_f32_e32 v22, v22
	v_exp_f32_e32 v23, v23
	v_exp_f32_e32 v24, v24
	v_exp_f32_e32 v25, v25
	v_exp_f32_e32 v26, v26
	v_exp_f32_e32 v27, v27
	v_exp_f32_e32 v28, v28
	v_exp_f32_e32 v29, v29
	v_exp_f32_e32 v30, v30
	v_exp_f32_e32 v31, v31
	v_exp_f32_e32 v32, v32
	v_exp_f32_e32 v33, v33
	v_lshlrev_b32_e32 v196, 16, v196
	v_lshlrev_b32_e32 v197, 16, v197
	v_lshlrev_b32_e32 v198, 16, v198
	v_lshlrev_b32_e32 v199, 16, v199
	v_lshlrev_b32_e32 v200, 16, v200
	v_lshlrev_b32_e32 v201, 16, v201
	v_lshlrev_b32_e32 v202, 16, v202
	v_lshlrev_b32_e32 v203, 16, v203
	v_lshlrev_b32_e32 v204, 16, v204
	v_lshlrev_b32_e32 v205, 16, v205
	v_lshlrev_b32_e32 v206, 16, v206
	v_lshlrev_b32_e32 v207, 16, v207
	v_lshlrev_b32_e32 v208, 16, v208
	v_lshlrev_b32_e32 v209, 16, v209
	v_lshlrev_b32_e32 v210, 16, v210
	v_lshlrev_b32_e32 v211, 16, v211
	v_lshlrev_b32_e32 v180, 16, v180
	v_lshlrev_b32_e32 v181, 16, v181
	v_lshlrev_b32_e32 v182, 16, v182
	v_lshlrev_b32_e32 v183, 16, v183
	v_lshlrev_b32_e32 v184, 16, v184
	v_lshlrev_b32_e32 v185, 16, v185
	v_lshlrev_b32_e32 v186, 16, v186
	v_lshlrev_b32_e32 v187, 16, v187
	v_lshlrev_b32_e32 v188, 16, v188
	v_lshlrev_b32_e32 v189, 16, v189
	v_lshlrev_b32_e32 v190, 16, v190
	v_lshlrev_b32_e32 v191, 16, v191
	v_lshlrev_b32_e32 v192, 16, v192
	v_lshlrev_b32_e32 v193, 16, v193
	v_lshlrev_b32_e32 v194, 16, v194
	v_lshlrev_b32_e32 v195, 16, v195
	v_mul_f32_e32 v196, v18, v196
	v_mul_f32_e32 v197, v19, v197
	v_mul_f32_e32 v198, v20, v198
	v_mul_f32_e32 v199, v21, v199
	v_mul_f32_e32 v200, v22, v200
	v_mul_f32_e32 v201, v23, v201
	v_mul_f32_e32 v202, v24, v202
	v_mul_f32_e32 v203, v25, v203
	v_mul_f32_e32 v204, v26, v204
	v_mul_f32_e32 v205, v27, v205
	v_mul_f32_e32 v206, v28, v206
	v_mul_f32_e32 v207, v29, v207
	v_mul_f32_e32 v208, v30, v208
	v_mul_f32_e32 v209, v31, v209
	v_mul_f32_e32 v210, v32, v210
	v_mul_f32_e32 v211, v33, v211
	v_mul_f32_e32 v180, 0x3e000000, v180
	v_mul_f32_e32 v181, 0x3e000000, v181
	v_mul_f32_e32 v182, 0x3e000000, v182
	v_mul_f32_e32 v183, 0x3e000000, v183
	v_mul_f32_e32 v184, 0x3e000000, v184
	v_mul_f32_e32 v185, 0x3e000000, v185
	v_mul_f32_e32 v186, 0x3e000000, v186
	v_mul_f32_e32 v187, 0x3e000000, v187
	v_mul_f32_e32 v188, 0x3e000000, v188
	v_mul_f32_e32 v189, 0x3e000000, v189
	v_mul_f32_e32 v190, 0x3e000000, v190
	v_mul_f32_e32 v191, 0x3e000000, v191
	v_mul_f32_e32 v192, 0x3e000000, v192
	v_mul_f32_e32 v193, 0x3e000000, v193
	v_mul_f32_e32 v194, 0x3e000000, v194
	v_mul_f32_e32 v195, 0x3e000000, v195
	v_mul_f32_e32 v180, v180, v236
	v_mul_f32_e32 v181, v181, v237
	v_mul_f32_e32 v182, v182, v238
	v_mul_f32_e32 v183, v183, v239
	v_mul_f32_e32 v184, v184, v240
	v_mul_f32_e32 v185, v185, v241
	v_mul_f32_e32 v186, v186, v242
	v_mul_f32_e32 v187, v187, v243
	v_mul_f32_e32 v188, v188, v244
	v_mul_f32_e32 v189, v189, v245
	v_mul_f32_e32 v190, v190, v246
	v_mul_f32_e32 v191, v191, v247
	v_mul_f32_e32 v192, v192, v248
	v_mul_f32_e32 v193, v193, v249
	v_mul_f32_e32 v194, v194, v250
	v_mul_f32_e32 v195, v195, v251
	v_cvt_pk_bf16_f32 v196, v196, v196
	v_cvt_pk_bf16_f32 v197, v197, v197
	v_cvt_pk_bf16_f32 v198, v198, v198
	v_cvt_pk_bf16_f32 v199, v199, v199
	v_cvt_pk_bf16_f32 v200, v200, v200
	v_cvt_pk_bf16_f32 v201, v201, v201
	v_cvt_pk_bf16_f32 v202, v202, v202
	v_cvt_pk_bf16_f32 v203, v203, v203
	v_cvt_pk_bf16_f32 v204, v204, v204
	v_cvt_pk_bf16_f32 v205, v205, v205
; __device__ __forceinline__ unsigned f2bf(float f) { unsigned r; asm("v_cvt_pk_bf16_f32 %0, %1, %1" : "=v"(r) : "v"(f)); return r & 0xffffu; }
; __device__ __forceinline__ void gl1_item(PREF p, int l, int item, bool valid, LAS unsigned char* pl, int sw, int lane) {
;     ...
;             for (int ss = 0; ss < 16; ++ss) { const int s = g4 * 16 + ss; const int i = d ? 63 - s : s; const size_t rowi = (size_t)(row0 + i * rstride);
;                 bc += gv[ss];
;                 const float en = __expf(-bc), ep = __expf(bc);
;                 const float kt = kc[ss] * en, qt = qc[ss] * 0.125f * ep;
;                 const unsigned ktb = f2bf(kt);
;                 sKt[lane * 72 + i] = (bf16_t)ktb;
;                 QK[rowi * 1024 + d * 512 + h * 64 + lane] = (bf16_t)f2bf(qt);
;                 QK[rowi * 1024 + d * 512 + 256 + h * 64 + lane] = (bf16_t)ktb;
;             }
; #pragma unroll
;             for (int ss = 0; ss < 16; ++ss) { qc[ss] = bf2f(__builtin_bit_cast(unsigned, qn[ss])); kc[ss] = bf2f(__builtin_bit_cast(unsigned, kn[ss])); }
;         }
;         const float Dv = __expf(bc);
;         sD[lane] = Dv; GLD[(size_t)(seq * NCH + cj) * 64 + lane] = Dv;
	v_cvt_pk_bf16_f32 v206, v206, v206
	v_cvt_pk_bf16_f32 v207, v207, v207
	v_cvt_pk_bf16_f32 v208, v208, v208
	v_cvt_pk_bf16_f32 v209, v209, v209
	v_cvt_pk_bf16_f32 v210, v210, v210
	v_cvt_pk_bf16_f32 v211, v211, v211
	v_cvt_pk_bf16_f32 v180, v180, v180
	v_cvt_pk_bf16_f32 v181, v181, v181
	v_cvt_pk_bf16_f32 v182, v182, v182
	v_cvt_pk_bf16_f32 v183, v183, v183
	v_cvt_pk_bf16_f32 v184, v184, v184
	v_cvt_pk_bf16_f32 v185, v185, v185
	v_cvt_pk_bf16_f32 v186, v186, v186
	v_cvt_pk_bf16_f32 v187, v187, v187
	v_cvt_pk_bf16_f32 v188, v188, v188
	v_cvt_pk_bf16_f32 v189, v189, v189
	v_cvt_pk_bf16_f32 v190, v190, v190
	v_cvt_pk_bf16_f32 v191, v191, v191
	v_cvt_pk_bf16_f32 v192, v192, v192
	v_cvt_pk_bf16_f32 v193, v193, v193
	v_cvt_pk_bf16_f32 v194, v194, v194
	v_cvt_pk_bf16_f32 v195, v195, v195
	ds_write_b16 v60, v196
	v_add_u32_e32 v60, v61, v60
	global_store_short v134, v180, s[4:5]
	global_store_short v134, v196, s[4:5] offset:512
	s_add_u32 s4, s4, s56
	s_addc_u32 s5, s5, s3
	ds_write_b16 v60, v197
	v_add_u32_e32 v60, v61, v60
	global_store_short v134, v181, s[4:5]
	global_store_short v134, v197, s[4:5] offset:512
	s_add_u32 s4, s4, s56
	s_addc_u32 s5, s5, s3
	ds_write_b16 v60, v198
	v_add_u32_e32 v60, v61, v60
	global_store_short v134, v182, s[4:5]
	global_store_short v134, v198, s[4:5] offset:512
	s_add_u32 s4, s4, s56
	s_addc_u32 s5, s5, s3
	ds_write_b16 v60, v199
	v_add_u32_e32 v60, v61, v60
	global_store_short v134, v183, s[4:5]
	global_store_short v134, v199, s[4:5] offset:512
	s_add_u32 s4, s4, s56
	s_addc_u32 s5, s5, s3
	ds_write_b16 v60, v200
	v_add_u32_e32 v60, v61, v60
	global_store_short v134, v184, s[4:5]
	global_store_short v134, v200, s[4:5] offset:512
	s_add_u32 s4, s4, s56
	s_addc_u32 s5, s5, s3
	ds_write_b16 v60, v201
	v_add_u32_e32 v60, v61, v60
	global_store_short v134, v185, s[4:5]
	global_store_short v134, v201, s[4:5] offset:512
	s_add_u32 s4, s4, s56
	s_addc_u32 s5, s5, s3
	ds_write_b16 v60, v202
	v_add_u32_e32 v60, v61, v60
	global_store_short v134, v186, s[4:5]
	global_store_short v134, v202, s[4:5] offset:512
	s_add_u32 s4, s4, s56
	s_addc_u32 s5, s5, s3
	ds_write_b16 v60, v203
	v_add_u32_e32 v60, v61, v60
	global_store_short v134, v187, s[4:5]
	global_store_short v134, v203, s[4:5] offset:512
	s_add_u32 s4, s4, s56
	s_addc_u32 s5, s5, s3
	ds_write_b16 v60, v204
	v_add_u32_e32 v60, v61, v60
	global_store_short v134, v188, s[4:5]
	global_store_short v134, v204, s[4:5] offset:512
	s_add_u32 s4, s4, s56
	s_addc_u32 s5, s5, s3
	ds_write_b16 v60, v205
	v_add_u32_e32 v60, v61, v60
	global_store_short v134, v189, s[4:5]
	global_store_short v134, v205, s[4:5] offset:512
	s_add_u32 s4, s4, s56
	s_addc_u32 s5, s5, s3
	ds_write_b16 v60, v206
	v_add_u32_e32 v60, v61, v60
	global_store_short v134, v190, s[4:5]
	global_store_short v134, v206, s[4:5] offset:512
	s_add_u32 s4, s4, s56
	s_addc_u32 s5, s5, s3
	ds_write_b16 v60, v207
	v_add_u32_e32 v60, v61, v60
	global_store_short v134, v191, s[4:5]
	global_store_short v134, v207, s[4:5] offset:512
	s_add_u32 s4, s4, s56
	s_addc_u32 s5, s5, s3
	ds_write_b16 v60, v208
	v_add_u32_e32 v60, v61, v60
	global_store_short v134, v192, s[4:5]
	global_store_short v134, v208, s[4:5] offset:512
	s_add_u32 s4, s4, s56
	s_addc_u32 s5, s5, s3
	ds_write_b16 v60, v209
	v_add_u32_e32 v60, v61, v60
	global_store_short v134, v193, s[4:5]
	global_store_short v134, v209, s[4:5] offset:512
	s_add_u32 s4, s4, s56
	s_addc_u32 s5, s5, s3
	ds_write_b16 v60, v210
	v_add_u32_e32 v60, v61, v60
	global_store_short v134, v194, s[4:5]
	global_store_short v134, v210, s[4:5] offset:512
	s_add_u32 s4, s4, s56
	s_addc_u32 s5, s5, s3
	ds_write_b16 v60, v211
	v_add_u32_e32 v60, v61, v60
	global_store_short v134, v195, s[4:5]
	global_store_short v134, v211, s[4:5] offset:512
	s_add_u32 s4, s4, s56
	s_addc_u32 s5, s5, s3
	v_mul_f32_e32 v18, 0x3fb8aa3b, v17
	v_exp_f32_e32 v18, v18
	v_readlane_b32 s50, v253, 55
	v_readlane_b32 s51, v253, 56
	v_readlane_b32 s45, v254, 11
	s_nop 3
	s_load_dwordx2 s[46:47], s[50:51], 0xc0
	s_and_b32 s48, s38, 1
	s_lshr_b32 s45, s45, 7
	s_mul_i32 s45, s45, 0x9200
	s_lshl_b32 s48, s48, 8
	s_add_i32 s45, s45, s48
	v_lshl_add_u32 v86, v64, 2, s45
	ds_write_b32 v86, v18 offset:36864
	s_or_b32 s45, s42, s38
	s_mulk_i32 s45, 0x104
	s_add_i32 s45, s45, s41
	s_lshl_b32 s45, s45, 8
	s_waitcnt lgkmcnt(0)
	s_add_u32 s46, s46, 0xd00000
	s_addc_u32 s47, s47, 0
	s_add_u32 s46, s46, s45
	s_addc_u32 s47, s47, 0
	global_store_dword v135, v18, s[46:47]
